# one static s_setprio 1 for waves 4-7 at kernel entry, per-segment priority toggles in GEMM loops removed
# baseline (speedup 1.0000x reference)
; #define LAS __attribute__((address_space(3)))
; __global__ void __launch_bounds__(NTHR, 2) hybrid_fwd(Args args) {
;     extern __shared__ __attribute__((aligned(16))) unsigned char lds_raw[];
;     cg::grid_group grid = cg::this_grid();
;     LAS unsigned char* const lds0 = (LAS unsigned char*)lds_raw;
;     volatile LAS unsigned* xst = (volatile LAS unsigned*)(lds0 + LDS_BYTES - 16);
;     if (threadIdx.x == 0) { xst[0] = 0u; xst[1] = 0u; }
;     unsigned* barw = (unsigned*)args.ws;
;     if (blockIdx.x == 0) for (int i = threadIdx.x; i < XCD_BAR_WORDS; i += NTHR) barw[i] = 0u;
;     __syncthreads();
;     XcdBarrier xbar; xbar.bar = barw; xbar.x = 0u; xbar.st = xst;
;     const int lo = args.ph_lo, hi = args.ph_hi; int ph = 0;
.LBB0_2:
	s_or_b64 exec, exec, s[6:7]
	v_readfirstlane_b32 s4, v150
	s_cmpk_lt_u32 s4, 0x100
	s_cbranch_scc1 .Lprio_lead_half
	s_setprio 1
.Lprio_lead_half:
	s_load_dwordx16 s[40:55], s[0:1], 0x0
	s_load_dwordx16 s[68:83], s[0:1], 0x40
	s_load_dwordx16 s[12:27], s[0:1], 0x80
	s_mov_b32 s30, s2
	s_cmp_lg_u32 s2, 0
	s_waitcnt lgkmcnt(0)
	v_writelane_b32 v252, s12, 4
	s_nop 1
	v_writelane_b32 v252, s13, 5
	v_writelane_b32 v252, s14, 6
	v_writelane_b32 v252, s15, 7
	v_writelane_b32 v252, s16, 8
	v_writelane_b32 v252, s17, 9
	v_writelane_b32 v252, s18, 10
	v_writelane_b32 v252, s19, 11
	v_writelane_b32 v252, s20, 12
	v_writelane_b32 v252, s21, 13
	v_writelane_b32 v252, s22, 14
	v_writelane_b32 v252, s23, 15
	v_writelane_b32 v252, s24, 16
	v_writelane_b32 v252, s25, 17
	v_writelane_b32 v252, s26, 18
	v_writelane_b32 v252, s27, 19
	s_load_dwordx16 s[12:27], s[0:1], 0xc0
	s_cbranch_scc1 .LBB0_10
	v_sub_u32_e32 v1, 0xd7f, v150
	v_lshrrev_b32_e32 v2, 9, v1
	v_add_u32_e32 v1, 2, v2
	v_add_u32_e32 v151, 0x200, v150
	s_mov_b32 s28, 0
	v_and_b32_e32 v3, 14, v1
	v_mov_b32_e32 v1, v2
	s_mov_b32 s29, 1
	s_mov_b64 s[4:5], 0
	v_mov_b32_e32 v5, 0
	s_mov_b32 s6, s28
	v_mov_b64_e32 v[6:7], v[150:151]
	s_branch .LBB0_5

; #define PG8_STAGE(bufoff, gbase, voff) do { _Pragma("unroll") for (int _i = 0; _i < 2; ++_i) \
;         __builtin_amdgcn_global_load_lds((const unsigned*)((const char*)(gbase) + (voff)[_i]), (PG8_LAS unsigned*)(lds + (bufoff) + ldsw + _i * 8192), 16, 0, 0); } while (0)
; #define PG8_LDA(dst, b, h) do { _Pragma("unroll") for (int m = 0; m < 4; ++m) _Pragma("unroll") for (int k = 0; k < 2; ++k) dst[m][k] = *(const PG8_LAS bf16x8*)(lds + PG8_SA(b, h) + aoff + m * 2048 + k * 1024); } while (0)
; #define PG8_LDB(dst, b, h) do { _Pragma("unroll") for (int n = 0; n < 2; ++n) _Pragma("unroll") for (int k = 0; k < 2; ++k) dst[n][k] = *(const PG8_LAS bf16x8*)(lds + PG8_SB(b, h) + boff + n * 2048 + k * 1024); } while (0)
; template <class Epi, class Sched, bool ALIGN_EPI = false, bool SP2 = false>
; __device__ __forceinline__ void gemm_phase(PG8_LAS unsigned char* lds, const Gemm g, const Sched& S, const Epi& E) {
;     ...
;         for (int t = 0; t < nt; t += 2) {
;             const bool last = (t == nt - 2);
;             const char* a1 = cA + (size_t)(t + 1) * kstep;
;             const char* a2 = last ? nA : cA + (size_t)(t + 2) * kstep; const char* b2 = last ? nB : cB + (size_t)(t + 2) * kstep;
;             const char* a3 = a2 + kstep; const char* b3 = b2 + kstep;
;             if (last && has_next) S.a_ready(nxt);
;             if constexpr (SP2) {
;             PG8_LDB(B0, 0, 0); PG8_LDB(B1, 0, 1); PG8_SCHED; PG8_LDA(At, 0, 0); PG8_STAGE(PG8_SA(1, 1), a1 + hstep, voffA);
;             PG8_WAIT_V(8); PG8_WAIT_L(0); PG8_BAR; PG8_MMA(0, 0, At, B0); PG8_MMA(0, 1, At, B1); PG8_BAR; PG8_SCHED;
;             PG8_LDA(At, 0, 1); PG8_STAGE(PG8_SB(0, 0), b2, voffB); PG8_STAGE(PG8_SB(0, 1), b2 + hstep, voffB); PG8_STAGE(PG8_SA(0, 0), a2, voffA);
;             PG8_WAIT_V(8); PG8_WAIT_L(0); PG8_BAR; PG8_MMA(1, 0, At, B0); PG8_MMA(1, 1, At, B1); PG8_BAR; PG8_SCHED;
;             PG8_LDB(B0, 1, 0); PG8_LDB(B1, 1, 1); PG8_SCHED; PG8_LDA(At, 1, 0); PG8_STAGE(PG8_SA(0, 1), a2 + hstep, voffA);
;             PG8_WAIT_V(8); PG8_WAIT_L(0); PG8_BAR; PG8_MMA(0, 0, At, B0); PG8_MMA(0, 1, At, B1); PG8_BAR; PG8_SCHED;
;             PG8_LDA(At, 1, 1); PG8_STAGE(PG8_SB(1, 0), b3, voffB); PG8_STAGE(PG8_SB(1, 1), b3 + hstep, voffB); PG8_STAGE(PG8_SA(1, 0), a3, voffA);
;             PG8_WAIT_V(8); PG8_WAIT_L(0); PG8_BAR; PG8_MMA(1, 0, At, B0); PG8_MMA(1, 1, At, B1); PG8_BAR; PG8_SCHED;
.LBB0_128:
	s_add_u32 s34, s8, 0xfff80080
	s_addc_u32 s35, s9, -1
	s_add_i32 s83, 0, 0x10000
	s_cmp_eq_u32 s82, 28
	s_cselect_b32 s41, s27, s35
	s_cselect_b32 s40, s78, s34
	v_add_u32_e32 v146, s83, v147
	s_cselect_b32 s35, s25, s81
	s_cselect_b32 s34, s79, s80
	s_add_i32 s84, 0, 0x14000
	ds_read_b128 v[142:145], v146
	ds_read_b128 v[162:165], v146 offset:1024
	ds_read_b128 v[166:169], v146 offset:2048
	ds_read_b128 v[170:173], v146 offset:3072
	v_add_u32_e32 v146, s84, v147
	ds_read_b128 v[174:177], v146
	ds_read_b128 v[178:181], v146 offset:1024
	ds_read_b128 v[182:185], v146 offset:2048
	ds_read_b128 v[186:189], v146 offset:3072
	s_add_i32 m0, s49, 0xc000
	ds_read_b128 v[190:193], v152
	ds_read_b128 v[194:197], v152 offset:1024
	ds_read_b128 v[198:201], v152 offset:2048
	ds_read_b128 v[202:205], v152 offset:3072
	ds_read_b128 v[230:233], v152 offset:4096
	ds_read_b128 v[234:237], v152 offset:5120
	ds_read_b128 v[238:241], v152 offset:6144
	ds_read_b128 v[242:245], v152 offset:7168
	global_load_lds_dwordx4 v140, s[8:9]
	s_add_i32 m0, s49, 0xe000
	s_nop 0
	global_load_lds_dwordx4 v138, s[8:9]
	s_waitcnt vmcnt(8)
	s_waitcnt lgkmcnt(0)
	s_barrier
	s_waitcnt lgkmcnt(0)
	v_mfma_f32_16x16x32_bf16 v[130:133], v[142:145], v[190:193], v[130:133]
	v_mfma_f32_16x16x32_bf16 v[122:125], v[166:169], v[190:193], v[122:125]
	v_mfma_f32_16x16x32_bf16 v[114:117], v[142:145], v[198:201], v[114:117]
	v_mfma_f32_16x16x32_bf16 v[106:109], v[166:169], v[198:201], v[106:109]
	v_mfma_f32_16x16x32_bf16 v[98:101], v[142:145], v[230:233], v[98:101]
	v_mfma_f32_16x16x32_bf16 v[90:93], v[166:169], v[230:233], v[90:93]
	v_mfma_f32_16x16x32_bf16 v[82:85], v[142:145], v[238:241], v[82:85]
	v_mfma_f32_16x16x32_bf16 v[74:77], v[166:169], v[238:241], v[74:77]
	v_mfma_f32_16x16x32_bf16 v[130:133], v[162:165], v[194:197], v[130:133]
	v_mfma_f32_16x16x32_bf16 v[122:125], v[170:173], v[194:197], v[122:125]
	v_mfma_f32_16x16x32_bf16 v[114:117], v[162:165], v[202:205], v[114:117]
	v_mfma_f32_16x16x32_bf16 v[106:109], v[170:173], v[202:205], v[106:109]
	v_mfma_f32_16x16x32_bf16 v[98:101], v[162:165], v[234:237], v[98:101]
	v_mfma_f32_16x16x32_bf16 v[90:93], v[170:173], v[234:237], v[90:93]
	v_mfma_f32_16x16x32_bf16 v[82:85], v[162:165], v[242:245], v[82:85]
	v_mfma_f32_16x16x32_bf16 v[74:77], v[170:173], v[242:245], v[74:77]
	v_mfma_f32_16x16x32_bf16 v[126:129], v[174:177], v[190:193], v[126:129]
	v_mfma_f32_16x16x32_bf16 v[118:121], v[182:185], v[190:193], v[118:121]
	v_mfma_f32_16x16x32_bf16 v[110:113], v[174:177], v[198:201], v[110:113]
	v_mfma_f32_16x16x32_bf16 v[102:105], v[182:185], v[198:201], v[102:105]
	v_mfma_f32_16x16x32_bf16 v[94:97], v[174:177], v[230:233], v[94:97]
	v_mfma_f32_16x16x32_bf16 v[86:89], v[182:185], v[230:233], v[86:89]
	v_mfma_f32_16x16x32_bf16 v[78:81], v[174:177], v[238:241], v[78:81]
	v_mfma_f32_16x16x32_bf16 v[70:73], v[182:185], v[238:241], v[70:73]
	v_mfma_f32_16x16x32_bf16 v[126:129], v[178:181], v[194:197], v[126:129]
	v_mfma_f32_16x16x32_bf16 v[118:121], v[186:189], v[194:197], v[118:121]
	v_mfma_f32_16x16x32_bf16 v[110:113], v[178:181], v[202:205], v[110:113]
	v_mfma_f32_16x16x32_bf16 v[102:105], v[186:189], v[202:205], v[102:105]
	v_mfma_f32_16x16x32_bf16 v[94:97], v[178:181], v[234:237], v[94:97]
	v_mfma_f32_16x16x32_bf16 v[86:89], v[186:189], v[234:237], v[86:89]
	v_mfma_f32_16x16x32_bf16 v[78:81], v[178:181], v[242:245], v[78:81]
	v_mfma_f32_16x16x32_bf16 v[70:73], v[186:189], v[242:245], v[70:73]
	s_barrier
	s_add_i32 s83, s83, s48
	s_mov_b32 m0, s83
	ds_read_b128 v[190:193], v152 offset:16384
	ds_read_b128 v[194:197], v152 offset:17408
	ds_read_b128 v[198:201], v152 offset:18432
	ds_read_b128 v[202:205], v152 offset:19456
	ds_read_b128 v[230:233], v152 offset:20480
	ds_read_b128 v[234:237], v152 offset:21504
	ds_read_b128 v[238:241], v152 offset:22528
	ds_read_b128 v[242:245], v152 offset:23552
	global_load_lds_dwordx4 v2, s[34:35]
	s_add_i32 m0, s83, 0x2000
	s_add_u32 s86, s34, 0x80000
	s_addc_u32 s87, s35, 0
	s_add_i32 s83, s84, s48
	global_load_lds_dwordx4 v0, s[34:35]
	s_mov_b32 m0, s83
	v_lshl_add_u64 v[250:251], s[40:41], 0, v[134:135]
	global_load_lds_dwordx4 v2, s[86:87]
	s_add_i32 m0, s83, 0x2000
	s_nop 0
	global_load_lds_dwordx4 v0, s[86:87]
	v_lshl_add_u64 v[248:249], s[40:41], 0, v[136:137]
	s_mov_b32 m0, s49
	s_nop 0
	global_load_lds_dwordx4 v136, s[40:41]
	s_mov_b32 m0, s51
	s_nop 0
	global_load_lds_dwordx4 v134, s[40:41]
	s_waitcnt vmcnt(8)
	s_waitcnt lgkmcnt(0)
	s_barrier
	s_waitcnt lgkmcnt(0)
	v_mfma_f32_16x16x32_bf16 v[66:69], v[142:145], v[190:193], v[66:69]
	v_mfma_f32_16x16x32_bf16 v[58:61], v[166:169], v[190:193], v[58:61]
	v_mfma_f32_16x16x32_bf16 v[50:53], v[142:145], v[198:201], v[50:53]
	v_mfma_f32_16x16x32_bf16 v[42:45], v[166:169], v[198:201], v[42:45]
	v_mfma_f32_16x16x32_bf16 v[34:37], v[142:145], v[230:233], v[34:37]
	v_mfma_f32_16x16x32_bf16 v[26:29], v[166:169], v[230:233], v[26:29]
	v_mfma_f32_16x16x32_bf16 v[18:21], v[142:145], v[238:241], v[18:21]
	v_mfma_f32_16x16x32_bf16 v[10:13], v[166:169], v[238:241], v[10:13]
	v_mfma_f32_16x16x32_bf16 v[66:69], v[162:165], v[194:197], v[66:69]
	v_mfma_f32_16x16x32_bf16 v[58:61], v[170:173], v[194:197], v[58:61]
	v_mfma_f32_16x16x32_bf16 v[50:53], v[162:165], v[202:205], v[50:53]
	v_mfma_f32_16x16x32_bf16 v[42:45], v[170:173], v[202:205], v[42:45]
	v_mfma_f32_16x16x32_bf16 v[34:37], v[162:165], v[234:237], v[34:37]
	v_mfma_f32_16x16x32_bf16 v[26:29], v[170:173], v[234:237], v[26:29]
	v_mfma_f32_16x16x32_bf16 v[18:21], v[162:165], v[242:245], v[18:21]
	v_mfma_f32_16x16x32_bf16 v[10:13], v[170:173], v[242:245], v[10:13]
	v_mfma_f32_16x16x32_bf16 v[62:65], v[174:177], v[190:193], v[62:65]
	v_mfma_f32_16x16x32_bf16 v[54:57], v[182:185], v[190:193], v[54:57]
	v_mfma_f32_16x16x32_bf16 v[46:49], v[174:177], v[198:201], v[46:49]
	v_mfma_f32_16x16x32_bf16 v[38:41], v[182:185], v[198:201], v[38:41]
	v_mfma_f32_16x16x32_bf16 v[30:33], v[174:177], v[230:233], v[30:33]
	v_mfma_f32_16x16x32_bf16 v[22:25], v[182:185], v[230:233], v[22:25]
	v_mfma_f32_16x16x32_bf16 v[14:17], v[174:177], v[238:241], v[14:17]
	v_mfma_f32_16x16x32_bf16 v[6:9], v[182:185], v[238:241], v[6:9]
	v_mfma_f32_16x16x32_bf16 v[62:65], v[178:181], v[194:197], v[62:65]
	v_mfma_f32_16x16x32_bf16 v[54:57], v[186:189], v[194:197], v[54:57]
	v_mfma_f32_16x16x32_bf16 v[46:49], v[178:181], v[202:205], v[46:49]
	v_mfma_f32_16x16x32_bf16 v[38:41], v[186:189], v[202:205], v[38:41]
	v_mfma_f32_16x16x32_bf16 v[30:33], v[178:181], v[234:237], v[30:33]
	v_mfma_f32_16x16x32_bf16 v[22:25], v[186:189], v[234:237], v[22:25]
	v_mfma_f32_16x16x32_bf16 v[14:17], v[178:181], v[242:245], v[14:17]
	v_mfma_f32_16x16x32_bf16 v[6:9], v[186:189], v[242:245], v[6:9]
	s_barrier
; #define PG8_STAGE(bufoff, gbase, voff) do { _Pragma("unroll") for (int _i = 0; _i < 2; ++_i) \
;         __builtin_amdgcn_global_load_lds((const unsigned*)((const char*)(gbase) + (voff)[_i]), (PG8_LAS unsigned*)(lds + (bufoff) + ldsw + _i * 8192), 16, 0, 0); } while (0)
; #define PG8_LDA(dst, b, h) do { _Pragma("unroll") for (int m = 0; m < 4; ++m) _Pragma("unroll") for (int k = 0; k < 2; ++k) dst[m][k] = *(const PG8_LAS bf16x8*)(lds + PG8_SA(b, h) + aoff + m * 2048 + k * 1024); } while (0)
; #define PG8_WAIT_V(n) asm volatile("s_waitcnt vmcnt(" #n ")" ::: "memory")
; #define PG8_WAIT_L(n) asm volatile("s_waitcnt lgkmcnt(" #n ")" ::: "memory")
; template <class Epi, class Sched, bool ALIGN_EPI = false, bool SP2 = false>
; __device__ __forceinline__ void gemm_phase(PG8_LAS unsigned char* lds, const Gemm g, const Sched& S, const Epi& E) {
;     ...
;         for (int t = 0; t < nt; t += 2) {
;             const bool last = (t == nt - 2);
;             const char* a1 = cA + (size_t)(t + 1) * kstep;
;             const char* a2 = last ? nA : cA + (size_t)(t + 2) * kstep; const char* b2 = last ? nB : cB + (size_t)(t + 2) * kstep;
;             const char* a3 = a2 + kstep; const char* b3 = b2 + kstep;
;             if (last && has_next) S.a_ready(nxt);
;             if constexpr (SP2) {
;             PG8_LDB(B0, 0, 0); PG8_LDB(B1, 0, 1); PG8_SCHED; PG8_LDA(At, 0, 0); PG8_STAGE(PG8_SA(1, 1), a1 + hstep, voffA);
;             PG8_WAIT_V(8); PG8_WAIT_L(0); PG8_BAR; PG8_MMA(0, 0, At, B0); PG8_MMA(0, 1, At, B1); PG8_BAR; PG8_SCHED;
;             PG8_LDA(At, 0, 1); PG8_STAGE(PG8_SB(0, 0), b2, voffB); PG8_STAGE(PG8_SB(0, 1), b2 + hstep, voffB); PG8_STAGE(PG8_SA(0, 0), a2, voffA);
;             PG8_WAIT_V(8); PG8_WAIT_L(0); PG8_BAR; PG8_MMA(1, 0, At, B0); PG8_MMA(1, 1, At, B1); PG8_BAR; PG8_SCHED;
;             PG8_LDB(B0, 1, 0); PG8_LDB(B1, 1, 1); PG8_SCHED; PG8_LDA(At, 1, 0); PG8_STAGE(PG8_SA(0, 1), a2 + hstep, voffA);
;             PG8_WAIT_V(8); PG8_WAIT_L(0); PG8_BAR; PG8_MMA(0, 0, At, B0); PG8_MMA(0, 1, At, B1); PG8_BAR; PG8_SCHED;
;             PG8_LDA(At, 1, 1); PG8_STAGE(PG8_SB(1, 0), b3, voffB); PG8_STAGE(PG8_SB(1, 1), b3 + hstep, voffB); PG8_STAGE(PG8_SA(1, 0), a3, voffA);
;             PG8_WAIT_V(8); PG8_WAIT_L(0); PG8_BAR; PG8_MMA(1, 0, At, B0); PG8_MMA(1, 1, At, B1); PG8_BAR; PG8_SCHED;
;     ...
;         if constexpr (ALIGN_EPI) { if (wr == 0) PG8_BAR; }
	s_add_i32 s83, 0, 0x18000
	v_add_u32_e32 v146, s83, v147
	s_add_i32 s84, 0, 0x1c000
	ds_read_b128 v[142:145], v146
	ds_read_b128 v[162:165], v146 offset:1024
	ds_read_b128 v[166:169], v146 offset:2048
	ds_read_b128 v[170:173], v146 offset:3072
	v_add_u32_e32 v146, s84, v147
	ds_read_b128 v[174:177], v146
	ds_read_b128 v[178:181], v146 offset:1024
	ds_read_b128 v[182:185], v146 offset:2048
	ds_read_b128 v[186:189], v146 offset:3072
	s_add_u32 s40, s40, 0x80000
	s_addc_u32 s41, s41, 0
	s_mov_b32 m0, s52
	ds_read_b128 v[190:193], v152 offset:32768
	ds_read_b128 v[194:197], v152 offset:33792
	ds_read_b128 v[198:201], v152 offset:34816
	ds_read_b128 v[202:205], v152 offset:35840
	ds_read_b128 v[230:233], v152 offset:36864
	ds_read_b128 v[234:237], v152 offset:37888
	ds_read_b128 v[238:241], v152 offset:38912
	ds_read_b128 v[242:245], v152 offset:39936
	global_load_lds_dwordx4 v136, s[40:41]
	s_mov_b32 m0, s53
	s_nop 0
	global_load_lds_dwordx4 v134, s[40:41]
	s_waitcnt vmcnt(8)
	s_waitcnt lgkmcnt(0)
	s_barrier
	s_waitcnt lgkmcnt(0)
	v_mfma_f32_16x16x32_bf16 v[130:133], v[142:145], v[190:193], v[130:133]
	v_mfma_f32_16x16x32_bf16 v[122:125], v[166:169], v[190:193], v[122:125]
	v_mfma_f32_16x16x32_bf16 v[114:117], v[142:145], v[198:201], v[114:117]
	v_mfma_f32_16x16x32_bf16 v[106:109], v[166:169], v[198:201], v[106:109]
	v_mfma_f32_16x16x32_bf16 v[98:101], v[142:145], v[230:233], v[98:101]
	v_mfma_f32_16x16x32_bf16 v[90:93], v[166:169], v[230:233], v[90:93]
	v_mfma_f32_16x16x32_bf16 v[82:85], v[142:145], v[238:241], v[82:85]
	v_mfma_f32_16x16x32_bf16 v[74:77], v[166:169], v[238:241], v[74:77]
	v_mfma_f32_16x16x32_bf16 v[130:133], v[162:165], v[194:197], v[130:133]
	v_mfma_f32_16x16x32_bf16 v[122:125], v[170:173], v[194:197], v[122:125]
	v_mfma_f32_16x16x32_bf16 v[114:117], v[162:165], v[202:205], v[114:117]
	v_mfma_f32_16x16x32_bf16 v[106:109], v[170:173], v[202:205], v[106:109]
	v_mfma_f32_16x16x32_bf16 v[98:101], v[162:165], v[234:237], v[98:101]
	v_mfma_f32_16x16x32_bf16 v[90:93], v[170:173], v[234:237], v[90:93]
	v_mfma_f32_16x16x32_bf16 v[82:85], v[162:165], v[242:245], v[82:85]
	v_mfma_f32_16x16x32_bf16 v[74:77], v[170:173], v[242:245], v[74:77]
	v_mfma_f32_16x16x32_bf16 v[126:129], v[174:177], v[190:193], v[126:129]
	v_mfma_f32_16x16x32_bf16 v[118:121], v[182:185], v[190:193], v[118:121]
	v_mfma_f32_16x16x32_bf16 v[110:113], v[174:177], v[198:201], v[110:113]
	v_mfma_f32_16x16x32_bf16 v[102:105], v[182:185], v[198:201], v[102:105]
	v_mfma_f32_16x16x32_bf16 v[94:97], v[174:177], v[230:233], v[94:97]
	v_mfma_f32_16x16x32_bf16 v[86:89], v[182:185], v[230:233], v[86:89]
	v_mfma_f32_16x16x32_bf16 v[78:81], v[174:177], v[238:241], v[78:81]
	v_mfma_f32_16x16x32_bf16 v[70:73], v[182:185], v[238:241], v[70:73]
	v_mfma_f32_16x16x32_bf16 v[126:129], v[178:181], v[194:197], v[126:129]
	v_mfma_f32_16x16x32_bf16 v[118:121], v[186:189], v[194:197], v[118:121]
	v_mfma_f32_16x16x32_bf16 v[110:113], v[178:181], v[202:205], v[110:113]
	v_mfma_f32_16x16x32_bf16 v[102:105], v[186:189], v[202:205], v[102:105]
	v_mfma_f32_16x16x32_bf16 v[94:97], v[178:181], v[234:237], v[94:97]
	v_mfma_f32_16x16x32_bf16 v[86:89], v[186:189], v[234:237], v[86:89]
	v_mfma_f32_16x16x32_bf16 v[78:81], v[178:181], v[242:245], v[78:81]
	v_mfma_f32_16x16x32_bf16 v[70:73], v[186:189], v[242:245], v[70:73]
	s_barrier
	s_add_u32 vcc_lo, s34, s2
	s_addc_u32 vcc_hi, s35, s3
	s_add_i32 s40, s83, s48
	s_mov_b32 m0, s40
	ds_read_b128 v[190:193], v152 offset:49152
	ds_read_b128 v[194:197], v152 offset:50176
	ds_read_b128 v[198:201], v152 offset:51200
	ds_read_b128 v[202:205], v152 offset:52224
	ds_read_b128 v[230:233], v152 offset:53248
	ds_read_b128 v[234:237], v152 offset:54272
	ds_read_b128 v[238:241], v152 offset:55296
	ds_read_b128 v[242:245], v152 offset:56320
	global_load_lds_dwordx4 v2, vcc
	s_add_i32 m0, s40, 0x2000
	s_add_u32 s34, s34, 0x80080
	s_addc_u32 s35, s35, 0
	s_add_i32 s40, s84, s48
	global_load_lds_dwordx4 v0, vcc
	s_mov_b32 m0, s40
	s_nop 0
	global_load_lds_dwordx4 v2, s[34:35]
	s_add_i32 m0, s40, 0x2000
	s_nop 0
	global_load_lds_dwordx4 v0, s[34:35]
	v_lshl_add_u64 v[158:159], v[248:249], 0, s[2:3]
	s_mov_b32 m0, s66
	s_nop 0
	global_load_lds_dwordx4 v[158:159], off
	v_lshl_add_u64 v[158:159], v[250:251], 0, s[2:3]
	s_mov_b32 m0, s67
	s_nop 0
	global_load_lds_dwordx4 v[158:159], off
	s_waitcnt vmcnt(8)
	s_waitcnt lgkmcnt(0)
	s_barrier
	s_waitcnt lgkmcnt(0)
	v_mfma_f32_16x16x32_bf16 v[66:69], v[142:145], v[190:193], v[66:69]
	v_mfma_f32_16x16x32_bf16 v[58:61], v[166:169], v[190:193], v[58:61]
	v_mfma_f32_16x16x32_bf16 v[50:53], v[142:145], v[198:201], v[50:53]
	v_mfma_f32_16x16x32_bf16 v[42:45], v[166:169], v[198:201], v[42:45]
	v_mfma_f32_16x16x32_bf16 v[34:37], v[142:145], v[230:233], v[34:37]
	v_mfma_f32_16x16x32_bf16 v[26:29], v[166:169], v[230:233], v[26:29]
	v_mfma_f32_16x16x32_bf16 v[18:21], v[142:145], v[238:241], v[18:21]
	v_mfma_f32_16x16x32_bf16 v[10:13], v[166:169], v[238:241], v[10:13]
	v_mfma_f32_16x16x32_bf16 v[66:69], v[162:165], v[194:197], v[66:69]
	v_mfma_f32_16x16x32_bf16 v[58:61], v[170:173], v[194:197], v[58:61]
	v_mfma_f32_16x16x32_bf16 v[50:53], v[162:165], v[202:205], v[50:53]
	v_mfma_f32_16x16x32_bf16 v[42:45], v[170:173], v[202:205], v[42:45]
	v_mfma_f32_16x16x32_bf16 v[34:37], v[162:165], v[234:237], v[34:37]
	v_mfma_f32_16x16x32_bf16 v[26:29], v[170:173], v[234:237], v[26:29]
	v_mfma_f32_16x16x32_bf16 v[18:21], v[162:165], v[242:245], v[18:21]
	v_mfma_f32_16x16x32_bf16 v[10:13], v[170:173], v[242:245], v[10:13]
	v_mfma_f32_16x16x32_bf16 v[62:65], v[174:177], v[190:193], v[62:65]
	v_mfma_f32_16x16x32_bf16 v[54:57], v[182:185], v[190:193], v[54:57]
	v_mfma_f32_16x16x32_bf16 v[46:49], v[174:177], v[198:201], v[46:49]
	v_mfma_f32_16x16x32_bf16 v[38:41], v[182:185], v[198:201], v[38:41]
	v_mfma_f32_16x16x32_bf16 v[30:33], v[174:177], v[230:233], v[30:33]
	v_mfma_f32_16x16x32_bf16 v[22:25], v[182:185], v[230:233], v[22:25]
	v_mfma_f32_16x16x32_bf16 v[14:17], v[174:177], v[238:241], v[14:17]
	v_mfma_f32_16x16x32_bf16 v[6:9], v[182:185], v[238:241], v[6:9]
	v_mfma_f32_16x16x32_bf16 v[62:65], v[178:181], v[194:197], v[62:65]
	v_mfma_f32_16x16x32_bf16 v[54:57], v[186:189], v[194:197], v[54:57]
	v_mfma_f32_16x16x32_bf16 v[46:49], v[178:181], v[202:205], v[46:49]
	v_mfma_f32_16x16x32_bf16 v[38:41], v[186:189], v[202:205], v[38:41]
	v_mfma_f32_16x16x32_bf16 v[30:33], v[178:181], v[234:237], v[30:33]
	v_mfma_f32_16x16x32_bf16 v[22:25], v[186:189], v[234:237], v[22:25]
	v_mfma_f32_16x16x32_bf16 v[14:17], v[178:181], v[242:245], v[14:17]
	v_mfma_f32_16x16x32_bf16 v[6:9], v[186:189], v[242:245], v[6:9]
	s_barrier
	s_add_i32 s82, s82, 2
	s_add_u32 s80, s80, 0x100
	s_addc_u32 s81, s81, 0
	s_add_u32 s8, s8, 0x100
	s_addc_u32 s9, s9, 0
	s_cmp_gt_u32 s82, 29
	s_cbranch_scc0 .LBB0_128
	s_and_b64 vcc, exec, s[22:23]
	s_cbranch_vccz .LBB0_131
	s_barrier

; #define PG8_STAGE(bufoff, gbase, voff) do { _Pragma("unroll") for (int _i = 0; _i < 2; ++_i) \
;         __builtin_amdgcn_global_load_lds((const unsigned*)((const char*)(gbase) + (voff)[_i]), (PG8_LAS unsigned*)(lds + (bufoff) + ldsw + _i * 8192), 16, 0, 0); } while (0)
; #define PG8_LDA(dst, b, h) do { _Pragma("unroll") for (int m = 0; m < 4; ++m) _Pragma("unroll") for (int k = 0; k < 2; ++k) dst[m][k] = *(const PG8_LAS bf16x8*)(lds + PG8_SA(b, h) + aoff + m * 2048 + k * 1024); } while (0)
; #define PG8_LDB(dst, b, h) do { _Pragma("unroll") for (int n = 0; n < 2; ++n) _Pragma("unroll") for (int k = 0; k < 2; ++k) dst[n][k] = *(const PG8_LAS bf16x8*)(lds + PG8_SB(b, h) + boff + n * 2048 + k * 1024); } while (0)
; template <class Epi, class Sched, bool ALIGN_EPI = false, bool SP2 = false>
; __device__ __forceinline__ void gemm_phase(PG8_LAS unsigned char* lds, const Gemm g, const Sched& S, const Epi& E) {
;     ...
;         for (int t = 0; t < nt; t += 2) {
;             const bool last = (t == nt - 2);
;             const char* a1 = cA + (size_t)(t + 1) * kstep;
;             const char* a2 = last ? nA : cA + (size_t)(t + 2) * kstep; const char* b2 = last ? nB : cB + (size_t)(t + 2) * kstep;
;             const char* a3 = a2 + kstep; const char* b3 = b2 + kstep;
;             if (last && has_next) S.a_ready(nxt);
;             if constexpr (SP2) {
;             PG8_LDB(B0, 0, 0); PG8_LDB(B1, 0, 1); PG8_SCHED; PG8_LDA(At, 0, 0); PG8_STAGE(PG8_SA(1, 1), a1 + hstep, voffA);
;             PG8_WAIT_V(8); PG8_WAIT_L(0); PG8_BAR; PG8_MMA(0, 0, At, B0); PG8_MMA(0, 1, At, B1); PG8_BAR; PG8_SCHED;
;             PG8_LDA(At, 0, 1); PG8_STAGE(PG8_SB(0, 0), b2, voffB); PG8_STAGE(PG8_SB(0, 1), b2 + hstep, voffB); PG8_STAGE(PG8_SA(0, 0), a2, voffA);
;             PG8_WAIT_V(8); PG8_WAIT_L(0); PG8_BAR; PG8_MMA(1, 0, At, B0); PG8_MMA(1, 1, At, B1); PG8_BAR; PG8_SCHED;
;             PG8_LDB(B0, 1, 0); PG8_LDB(B1, 1, 1); PG8_SCHED; PG8_LDA(At, 1, 0); PG8_STAGE(PG8_SA(0, 1), a2 + hstep, voffA);
;             PG8_WAIT_V(8); PG8_WAIT_L(0); PG8_BAR; PG8_MMA(0, 0, At, B0); PG8_MMA(0, 1, At, B1); PG8_BAR; PG8_SCHED;
;             PG8_LDA(At, 1, 1); PG8_STAGE(PG8_SB(1, 0), b3, voffB); PG8_STAGE(PG8_SB(1, 1), b3 + hstep, voffB); PG8_STAGE(PG8_SA(1, 0), a3, voffA);
;             PG8_WAIT_V(8); PG8_WAIT_L(0); PG8_BAR; PG8_MMA(1, 0, At, B0); PG8_MMA(1, 1, At, B1); PG8_BAR; PG8_SCHED;
.LBB0_235:
	s_add_u32 s10, s30, 0x100
	s_addc_u32 s11, s31, 0
	s_add_i32 s84, 0, 0x10000
	s_cmpk_eq_i32 s83, 0x54
	s_cselect_b32 s41, s29, s11
	s_cselect_b32 s40, s28, s10
	s_cselect_b32 s35, s1, s82
	s_cselect_b32 s34, s0, s81
	s_add_i32 s86, 0, 0x14000
	v_add_u32_e32 v62, s84, v152
	v_add_u32_e32 v158, s86, v152
	ds_read_b128 v[50:53], v62
	ds_read_b128 v[54:57], v62 offset:1024
	ds_read_b128 v[58:61], v62 offset:2048
	ds_read_b128 v[62:65], v62 offset:3072
	ds_read_b128 v[166:169], v158
	ds_read_b128 v[170:173], v158 offset:1024
	ds_read_b128 v[178:181], v158 offset:2048
	ds_read_b128 v[182:185], v158 offset:3072
	s_add_i32 m0, s51, 0xc000
	ds_read_b128 v[186:189], v177
	ds_read_b128 v[190:193], v177 offset:1024
	ds_read_b128 v[194:197], v177 offset:2048
	ds_read_b128 v[198:201], v177 offset:3072
	ds_read_b128 v[202:205], v177 offset:4096
	ds_read_b128 v[230:233], v177 offset:5120
	ds_read_b128 v[234:237], v177 offset:6144
	ds_read_b128 v[238:241], v177 offset:7168
	global_load_lds_dwordx4 v164, s[30:31]
	s_add_i32 m0, s51, 0xe000
	s_nop 0
	global_load_lds_dwordx4 v162, s[30:31]
	s_waitcnt vmcnt(8)
	s_waitcnt lgkmcnt(0)
	s_barrier
	s_waitcnt lgkmcnt(0)
	v_mfma_f32_16x16x32_bf16 v[146:149], v[50:53], v[186:189], v[146:149]
	v_mfma_f32_16x16x32_bf16 v[142:145], v[58:61], v[186:189], v[142:145]
	v_mfma_f32_16x16x32_bf16 v[130:133], v[50:53], v[194:197], v[130:133]
	v_mfma_f32_16x16x32_bf16 v[126:129], v[58:61], v[194:197], v[126:129]
	v_mfma_f32_16x16x32_bf16 v[114:117], v[50:53], v[202:205], v[114:117]
	v_mfma_f32_16x16x32_bf16 v[110:113], v[58:61], v[202:205], v[110:113]
	v_mfma_f32_16x16x32_bf16 v[98:101], v[50:53], v[234:237], v[98:101]
	v_mfma_f32_16x16x32_bf16 v[94:97], v[58:61], v[234:237], v[94:97]
	v_mfma_f32_16x16x32_bf16 v[146:149], v[54:57], v[190:193], v[146:149]
	v_mfma_f32_16x16x32_bf16 v[142:145], v[62:65], v[190:193], v[142:145]
	v_mfma_f32_16x16x32_bf16 v[130:133], v[54:57], v[198:201], v[130:133]
	v_mfma_f32_16x16x32_bf16 v[126:129], v[62:65], v[198:201], v[126:129]
	v_mfma_f32_16x16x32_bf16 v[114:117], v[54:57], v[230:233], v[114:117]
	v_mfma_f32_16x16x32_bf16 v[110:113], v[62:65], v[230:233], v[110:113]
	v_mfma_f32_16x16x32_bf16 v[98:101], v[54:57], v[238:241], v[98:101]
	v_mfma_f32_16x16x32_bf16 v[94:97], v[62:65], v[238:241], v[94:97]
	v_mfma_f32_16x16x32_bf16 v[138:141], v[166:169], v[186:189], v[138:141]
	v_mfma_f32_16x16x32_bf16 v[134:137], v[178:181], v[186:189], v[134:137]
	v_mfma_f32_16x16x32_bf16 v[122:125], v[166:169], v[194:197], v[122:125]
	v_mfma_f32_16x16x32_bf16 v[118:121], v[178:181], v[194:197], v[118:121]
	v_mfma_f32_16x16x32_bf16 v[106:109], v[166:169], v[202:205], v[106:109]
	v_mfma_f32_16x16x32_bf16 v[102:105], v[178:181], v[202:205], v[102:105]
	v_mfma_f32_16x16x32_bf16 v[90:93], v[166:169], v[234:237], v[90:93]
	v_mfma_f32_16x16x32_bf16 v[86:89], v[178:181], v[234:237], v[86:89]
	v_mfma_f32_16x16x32_bf16 v[138:141], v[170:173], v[190:193], v[138:141]
	v_mfma_f32_16x16x32_bf16 v[134:137], v[182:185], v[190:193], v[134:137]
	v_mfma_f32_16x16x32_bf16 v[122:125], v[170:173], v[198:201], v[122:125]
	v_mfma_f32_16x16x32_bf16 v[118:121], v[182:185], v[198:201], v[118:121]
	v_mfma_f32_16x16x32_bf16 v[106:109], v[170:173], v[230:233], v[106:109]
	v_mfma_f32_16x16x32_bf16 v[102:105], v[182:185], v[230:233], v[102:105]
	v_mfma_f32_16x16x32_bf16 v[90:93], v[170:173], v[238:241], v[90:93]
	v_mfma_f32_16x16x32_bf16 v[86:89], v[182:185], v[238:241], v[86:89]
	s_barrier
	s_add_i32 s30, s84, s49
	s_mov_b32 m0, s30
	ds_read_b128 v[186:189], v177 offset:16384
	ds_read_b128 v[190:193], v177 offset:17408
	ds_read_b128 v[194:197], v177 offset:18432
	ds_read_b128 v[198:201], v177 offset:19456
	ds_read_b128 v[202:205], v177 offset:20480
	ds_read_b128 v[230:233], v177 offset:21504
	ds_read_b128 v[234:237], v177 offset:22528
	ds_read_b128 v[238:241], v177 offset:23552
	global_load_lds_dwordx4 v2, s[34:35]
	s_add_i32 m0, s30, 0x2000
	s_add_u32 s30, s34, 0x160000
	s_addc_u32 s31, s35, 0
	s_add_i32 s84, s86, s49
	global_load_lds_dwordx4 v0, s[34:35]
	s_mov_b32 m0, s84
	s_nop 0
	global_load_lds_dwordx4 v2, s[30:31]
	s_add_i32 m0, s84, 0x2000
	s_nop 0
	global_load_lds_dwordx4 v0, s[30:31]
	s_mov_b32 m0, s51
	s_nop 0
	global_load_lds_dwordx4 v2, s[40:41]
	s_mov_b32 m0, s52
	s_nop 0
	global_load_lds_dwordx4 v0, s[40:41]
	s_waitcnt vmcnt(8)
	s_waitcnt lgkmcnt(0)
	s_barrier
	s_waitcnt lgkmcnt(0)
	v_mfma_f32_16x16x32_bf16 v[82:85], v[50:53], v[186:189], v[82:85]
	v_mfma_f32_16x16x32_bf16 v[78:81], v[58:61], v[186:189], v[78:81]
	v_mfma_f32_16x16x32_bf16 v[66:69], v[50:53], v[194:197], v[66:69]
	v_mfma_f32_16x16x32_bf16 v[46:49], v[58:61], v[194:197], v[46:49]
	v_mfma_f32_16x16x32_bf16 v[34:37], v[50:53], v[202:205], v[34:37]
	v_mfma_f32_16x16x32_bf16 v[30:33], v[58:61], v[202:205], v[30:33]
	v_mfma_f32_16x16x32_bf16 v[18:21], v[50:53], v[234:237], v[18:21]
	v_mfma_f32_16x16x32_bf16 v[14:17], v[58:61], v[234:237], v[14:17]
	v_mfma_f32_16x16x32_bf16 v[82:85], v[54:57], v[190:193], v[82:85]
	v_mfma_f32_16x16x32_bf16 v[78:81], v[62:65], v[190:193], v[78:81]
	v_mfma_f32_16x16x32_bf16 v[66:69], v[54:57], v[198:201], v[66:69]
	v_mfma_f32_16x16x32_bf16 v[46:49], v[62:65], v[198:201], v[46:49]
	v_mfma_f32_16x16x32_bf16 v[34:37], v[54:57], v[230:233], v[34:37]
	v_mfma_f32_16x16x32_bf16 v[30:33], v[62:65], v[230:233], v[30:33]
	v_mfma_f32_16x16x32_bf16 v[18:21], v[54:57], v[238:241], v[18:21]
	v_mfma_f32_16x16x32_bf16 v[14:17], v[62:65], v[238:241], v[14:17]
	v_mfma_f32_16x16x32_bf16 v[42:45], v[166:169], v[194:197], v[42:45]
	v_mfma_f32_16x16x32_bf16 v[38:41], v[178:181], v[194:197], v[38:41]
	v_mfma_f32_16x16x32_bf16 v[26:29], v[166:169], v[202:205], v[26:29]
	v_mfma_f32_16x16x32_bf16 v[22:25], v[178:181], v[202:205], v[22:25]
	v_mfma_f32_16x16x32_bf16 v[10:13], v[166:169], v[234:237], v[10:13]
	v_mfma_f32_16x16x32_bf16 v[6:9], v[178:181], v[234:237], v[6:9]
	v_mfma_f32_16x16x32_bf16 v[50:53], v[166:169], v[186:189], v[74:77]
	v_mfma_f32_16x16x32_bf16 v[54:57], v[178:181], v[186:189], v[70:73]
	v_mfma_f32_16x16x32_bf16 v[42:45], v[170:173], v[198:201], v[42:45]
	v_mfma_f32_16x16x32_bf16 v[38:41], v[182:185], v[198:201], v[38:41]
	v_mfma_f32_16x16x32_bf16 v[26:29], v[170:173], v[230:233], v[26:29]
	v_mfma_f32_16x16x32_bf16 v[22:25], v[182:185], v[230:233], v[22:25]
	v_mfma_f32_16x16x32_bf16 v[10:13], v[170:173], v[238:241], v[10:13]
	v_mfma_f32_16x16x32_bf16 v[6:9], v[182:185], v[238:241], v[6:9]
	v_mfma_f32_16x16x32_bf16 v[50:53], v[170:173], v[190:193], v[50:53]
	v_mfma_f32_16x16x32_bf16 v[54:57], v[182:185], v[190:193], v[54:57]
	s_barrier
; #define PG8_STAGE(bufoff, gbase, voff) do { _Pragma("unroll") for (int _i = 0; _i < 2; ++_i) \
;         __builtin_amdgcn_global_load_lds((const unsigned*)((const char*)(gbase) + (voff)[_i]), (PG8_LAS unsigned*)(lds + (bufoff) + ldsw + _i * 8192), 16, 0, 0); } while (0)
; #define PG8_LDA(dst, b, h) do { _Pragma("unroll") for (int m = 0; m < 4; ++m) _Pragma("unroll") for (int k = 0; k < 2; ++k) dst[m][k] = *(const PG8_LAS bf16x8*)(lds + PG8_SA(b, h) + aoff + m * 2048 + k * 1024); } while (0)
; #define PG8_LDB(dst, b, h) do { _Pragma("unroll") for (int n = 0; n < 2; ++n) _Pragma("unroll") for (int k = 0; k < 2; ++k) dst[n][k] = *(const PG8_LAS bf16x8*)(lds + PG8_SB(b, h) + boff + n * 2048 + k * 1024); } while (0)
; template <class Epi, class Sched, bool ALIGN_EPI = false, bool SP2 = false>
; __device__ __forceinline__ void gemm_phase(PG8_LAS unsigned char* lds, const Gemm g, const Sched& S, const Epi& E) {
;     ...
;         for (int t = 0; t < nt; t += 2) {
;             const bool last = (t == nt - 2);
;             const char* a1 = cA + (size_t)(t + 1) * kstep;
;             const char* a2 = last ? nA : cA + (size_t)(t + 2) * kstep; const char* b2 = last ? nB : cB + (size_t)(t + 2) * kstep;
;             const char* a3 = a2 + kstep; const char* b3 = b2 + kstep;
;             if (last && has_next) S.a_ready(nxt);
;             if constexpr (SP2) {
;             PG8_LDB(B0, 0, 0); PG8_LDB(B1, 0, 1); PG8_SCHED; PG8_LDA(At, 0, 0); PG8_STAGE(PG8_SA(1, 1), a1 + hstep, voffA);
;             PG8_WAIT_V(8); PG8_WAIT_L(0); PG8_BAR; PG8_MMA(0, 0, At, B0); PG8_MMA(0, 1, At, B1); PG8_BAR; PG8_SCHED;
;             PG8_LDA(At, 0, 1); PG8_STAGE(PG8_SB(0, 0), b2, voffB); PG8_STAGE(PG8_SB(0, 1), b2 + hstep, voffB); PG8_STAGE(PG8_SA(0, 0), a2, voffA);
;             PG8_WAIT_V(8); PG8_WAIT_L(0); PG8_BAR; PG8_MMA(1, 0, At, B0); PG8_MMA(1, 1, At, B1); PG8_BAR; PG8_SCHED;
;             PG8_LDB(B0, 1, 0); PG8_LDB(B1, 1, 1); PG8_SCHED; PG8_LDA(At, 1, 0); PG8_STAGE(PG8_SA(0, 1), a2 + hstep, voffA);
;             PG8_WAIT_V(8); PG8_WAIT_L(0); PG8_BAR; PG8_MMA(0, 0, At, B0); PG8_MMA(0, 1, At, B1); PG8_BAR; PG8_SCHED;
;             PG8_LDA(At, 1, 1); PG8_STAGE(PG8_SB(1, 0), b3, voffB); PG8_STAGE(PG8_SB(1, 1), b3 + hstep, voffB); PG8_STAGE(PG8_SA(1, 0), a3, voffA);
;             PG8_WAIT_V(8); PG8_WAIT_L(0); PG8_BAR; PG8_MMA(1, 0, At, B0); PG8_MMA(1, 1, At, B1); PG8_BAR; PG8_SCHED;
	s_add_i32 s84, 0, 0x18000
	s_add_i32 s86, 0, 0x1c000
	v_add_u32_e32 v74, s84, v152
	v_add_u32_e32 v160, s86, v152
	ds_read_b128 v[58:61], v74
	ds_read_b128 v[62:65], v74 offset:1024
	ds_read_b128 v[70:73], v74 offset:2048
	ds_read_b128 v[74:77], v74 offset:3072
	ds_read_b128 v[166:169], v160
	ds_read_b128 v[170:173], v160 offset:1024
	ds_read_b128 v[178:181], v160 offset:2048
	ds_read_b128 v[182:185], v160 offset:3072
	s_add_u32 s30, s40, 0x160000
	s_addc_u32 s31, s41, 0
	s_mov_b32 m0, s53
	ds_read_b128 v[186:189], v177 offset:32768
	ds_read_b128 v[190:193], v177 offset:33792
	ds_read_b128 v[194:197], v177 offset:34816
	ds_read_b128 v[198:201], v177 offset:35840
	ds_read_b128 v[202:205], v177 offset:36864
	ds_read_b128 v[230:233], v177 offset:37888
	ds_read_b128 v[234:237], v177 offset:38912
	ds_read_b128 v[238:241], v177 offset:39936
	global_load_lds_dwordx4 v2, s[30:31]
	s_mov_b32 m0, s66
	s_nop 0
	global_load_lds_dwordx4 v0, s[30:31]
	s_waitcnt vmcnt(8)
	s_waitcnt lgkmcnt(0)
	s_barrier
	s_waitcnt lgkmcnt(0)
	v_mfma_f32_16x16x32_bf16 v[146:149], v[58:61], v[186:189], v[146:149]
	v_mfma_f32_16x16x32_bf16 v[142:145], v[70:73], v[186:189], v[142:145]
	v_mfma_f32_16x16x32_bf16 v[130:133], v[58:61], v[194:197], v[130:133]
	v_mfma_f32_16x16x32_bf16 v[126:129], v[70:73], v[194:197], v[126:129]
	v_mfma_f32_16x16x32_bf16 v[114:117], v[58:61], v[202:205], v[114:117]
	v_mfma_f32_16x16x32_bf16 v[110:113], v[70:73], v[202:205], v[110:113]
	v_mfma_f32_16x16x32_bf16 v[98:101], v[58:61], v[234:237], v[98:101]
	v_mfma_f32_16x16x32_bf16 v[94:97], v[70:73], v[234:237], v[94:97]
	v_mfma_f32_16x16x32_bf16 v[146:149], v[62:65], v[190:193], v[146:149]
	v_mfma_f32_16x16x32_bf16 v[142:145], v[74:77], v[190:193], v[142:145]
	v_mfma_f32_16x16x32_bf16 v[130:133], v[62:65], v[198:201], v[130:133]
	v_mfma_f32_16x16x32_bf16 v[126:129], v[74:77], v[198:201], v[126:129]
	v_mfma_f32_16x16x32_bf16 v[114:117], v[62:65], v[230:233], v[114:117]
	v_mfma_f32_16x16x32_bf16 v[110:113], v[74:77], v[230:233], v[110:113]
	v_mfma_f32_16x16x32_bf16 v[98:101], v[62:65], v[238:241], v[98:101]
	v_mfma_f32_16x16x32_bf16 v[94:97], v[74:77], v[238:241], v[94:97]
	v_mfma_f32_16x16x32_bf16 v[138:141], v[166:169], v[186:189], v[138:141]
	v_mfma_f32_16x16x32_bf16 v[134:137], v[178:181], v[186:189], v[134:137]
	v_mfma_f32_16x16x32_bf16 v[122:125], v[166:169], v[194:197], v[122:125]
	v_mfma_f32_16x16x32_bf16 v[118:121], v[178:181], v[194:197], v[118:121]
	v_mfma_f32_16x16x32_bf16 v[106:109], v[166:169], v[202:205], v[106:109]
	v_mfma_f32_16x16x32_bf16 v[102:105], v[178:181], v[202:205], v[102:105]
	v_mfma_f32_16x16x32_bf16 v[90:93], v[166:169], v[234:237], v[90:93]
	v_mfma_f32_16x16x32_bf16 v[86:89], v[178:181], v[234:237], v[86:89]
	v_mfma_f32_16x16x32_bf16 v[138:141], v[170:173], v[190:193], v[138:141]
	v_mfma_f32_16x16x32_bf16 v[134:137], v[182:185], v[190:193], v[134:137]
	v_mfma_f32_16x16x32_bf16 v[122:125], v[170:173], v[198:201], v[122:125]
	v_mfma_f32_16x16x32_bf16 v[118:121], v[182:185], v[198:201], v[118:121]
	v_mfma_f32_16x16x32_bf16 v[106:109], v[170:173], v[230:233], v[106:109]
	v_mfma_f32_16x16x32_bf16 v[102:105], v[182:185], v[230:233], v[102:105]
	v_mfma_f32_16x16x32_bf16 v[90:93], v[170:173], v[238:241], v[90:93]
	v_mfma_f32_16x16x32_bf16 v[86:89], v[182:185], v[238:241], v[86:89]
	s_barrier
; #define PG8_STAGE(bufoff, gbase, voff) do { _Pragma("unroll") for (int _i = 0; _i < 2; ++_i) \
;         __builtin_amdgcn_global_load_lds((const unsigned*)((const char*)(gbase) + (voff)[_i]), (PG8_LAS unsigned*)(lds + (bufoff) + ldsw + _i * 8192), 16, 0, 0); } while (0)
; #define PG8_LDA(dst, b, h) do { _Pragma("unroll") for (int m = 0; m < 4; ++m) _Pragma("unroll") for (int k = 0; k < 2; ++k) dst[m][k] = *(const PG8_LAS bf16x8*)(lds + PG8_SA(b, h) + aoff + m * 2048 + k * 1024); } while (0)
; #define PG8_WAIT_V(n) asm volatile("s_waitcnt vmcnt(" #n ")" ::: "memory")
; #define PG8_WAIT_L(n) asm volatile("s_waitcnt lgkmcnt(" #n ")" ::: "memory")
; #define PG8_BAR __builtin_amdgcn_s_barrier()
;     __device__ __forceinline__ void operator()(const f32x4 (&acc)[2][2][4][2], const Unit& u, int wr, int wc, int fr, int fq) const {
;         const int row0 = u.pm * BM + wr * 64 + fr; const int col0 = u.pn * BM + wc * 32 + 4 * fq;
;         f32x4 gv[2][2];
; #pragma unroll
;         for (int bj = 0; bj < 2; ++bj)
; #pragma unroll
;             for (int n = 0; n < 2; ++n) gv[bj][n] = xg ? *(const f32x4*)(gn + col0 + bj * HALF + n * 16) : (f32x4){0.f, 0.f, 0.f, 0.f};
; template <class Epi, class Sched, bool ALIGN_EPI = false, bool SP2 = false>
; __device__ __forceinline__ void gemm_phase(PG8_LAS unsigned char* lds, const Gemm g, const Sched& S, const Epi& E) {
;     ...
;             PG8_LDB(B0, 0, 0); PG8_LDB(B1, 0, 1); PG8_SCHED; PG8_LDA(At, 0, 0); PG8_STAGE(PG8_SA(1, 1), a1 + hstep, voffA);
;             PG8_WAIT_V(8); PG8_WAIT_L(0); PG8_BAR; PG8_MMA(0, 0, At, B0); PG8_MMA(0, 1, At, B1); PG8_BAR; PG8_SCHED;
;             PG8_LDA(At, 0, 1); PG8_STAGE(PG8_SB(0, 0), b2, voffB); PG8_STAGE(PG8_SB(0, 1), b2 + hstep, voffB); PG8_STAGE(PG8_SA(0, 0), a2, voffA);
;             PG8_WAIT_V(8); PG8_WAIT_L(0); PG8_BAR; PG8_MMA(1, 0, At, B0); PG8_MMA(1, 1, At, B1); PG8_BAR; PG8_SCHED;
;             PG8_LDB(B0, 1, 0); PG8_LDB(B1, 1, 1); PG8_SCHED; PG8_LDA(At, 1, 0); PG8_STAGE(PG8_SA(0, 1), a2 + hstep, voffA);
;             PG8_WAIT_V(8); PG8_WAIT_L(0); PG8_BAR; PG8_MMA(0, 0, At, B0); PG8_MMA(0, 1, At, B1); PG8_BAR; PG8_SCHED;
;             PG8_LDA(At, 1, 1); PG8_STAGE(PG8_SB(1, 0), b3, voffB); PG8_STAGE(PG8_SB(1, 1), b3 + hstep, voffB); PG8_STAGE(PG8_SA(1, 0), a3, voffA);
;             PG8_WAIT_V(8); PG8_WAIT_L(0); PG8_BAR; PG8_MMA(1, 0, At, B0); PG8_MMA(1, 1, At, B1); PG8_BAR; PG8_SCHED;
	s_add_u32 vcc_lo, s34, s2
	s_addc_u32 vcc_hi, s35, s3
	s_add_i32 s30, s84, s49
	s_mov_b32 m0, s30
	ds_read_b128 v[186:189], v177 offset:49152
	ds_read_b128 v[190:193], v177 offset:50176
	ds_read_b128 v[194:197], v177 offset:51200
	ds_read_b128 v[198:201], v177 offset:52224
	ds_read_b128 v[202:205], v177 offset:53248
	ds_read_b128 v[230:233], v177 offset:54272
	ds_read_b128 v[234:237], v177 offset:55296
	ds_read_b128 v[238:241], v177 offset:56320
	global_load_lds_dwordx4 v2, vcc
	s_add_i32 m0, s30, 0x2000
	s_add_u32 s30, s34, 0x160080
	s_addc_u32 s31, s35, 0
	s_add_i32 s34, s86, s49
	global_load_lds_dwordx4 v0, vcc
	s_mov_b32 m0, s34
	s_nop 0
	global_load_lds_dwordx4 v2, s[30:31]
	s_add_i32 m0, s34, 0x2000
	s_nop 0
	global_load_lds_dwordx4 v0, s[30:31]
	s_add_u32 vcc_lo, s40, s2
	s_addc_u32 vcc_hi, s41, s3
	s_mov_b32 m0, s67
	s_nop 0
	global_load_lds_dwordx4 v2, vcc
	s_mov_b32 m0, s69
	s_nop 0
	global_load_lds_dwordx4 v0, vcc
	s_waitcnt vmcnt(8)
	s_waitcnt lgkmcnt(0)
	s_barrier
	s_waitcnt lgkmcnt(0)
	v_mfma_f32_16x16x32_bf16 v[82:85], v[58:61], v[186:189], v[82:85]
	v_mfma_f32_16x16x32_bf16 v[78:81], v[70:73], v[186:189], v[78:81]
	v_mfma_f32_16x16x32_bf16 v[66:69], v[58:61], v[194:197], v[66:69]
	v_mfma_f32_16x16x32_bf16 v[46:49], v[70:73], v[194:197], v[46:49]
	v_mfma_f32_16x16x32_bf16 v[34:37], v[58:61], v[202:205], v[34:37]
	v_mfma_f32_16x16x32_bf16 v[30:33], v[70:73], v[202:205], v[30:33]
	v_mfma_f32_16x16x32_bf16 v[18:21], v[58:61], v[234:237], v[18:21]
	v_mfma_f32_16x16x32_bf16 v[14:17], v[70:73], v[234:237], v[14:17]
	v_mfma_f32_16x16x32_bf16 v[82:85], v[62:65], v[190:193], v[82:85]
	v_mfma_f32_16x16x32_bf16 v[78:81], v[74:77], v[190:193], v[78:81]
	v_mfma_f32_16x16x32_bf16 v[66:69], v[62:65], v[198:201], v[66:69]
	v_mfma_f32_16x16x32_bf16 v[46:49], v[74:77], v[198:201], v[46:49]
	v_mfma_f32_16x16x32_bf16 v[34:37], v[62:65], v[230:233], v[34:37]
	v_mfma_f32_16x16x32_bf16 v[30:33], v[74:77], v[230:233], v[30:33]
	v_mfma_f32_16x16x32_bf16 v[18:21], v[62:65], v[238:241], v[18:21]
	v_mfma_f32_16x16x32_bf16 v[14:17], v[74:77], v[238:241], v[14:17]
	v_mfma_f32_16x16x32_bf16 v[50:53], v[166:169], v[186:189], v[50:53]
	v_mfma_f32_16x16x32_bf16 v[74:77], v[170:173], v[190:193], v[50:53]
	v_mfma_f32_16x16x32_bf16 v[50:53], v[178:181], v[186:189], v[54:57]
	v_mfma_f32_16x16x32_bf16 v[42:45], v[166:169], v[194:197], v[42:45]
	v_mfma_f32_16x16x32_bf16 v[38:41], v[178:181], v[194:197], v[38:41]
	v_mfma_f32_16x16x32_bf16 v[26:29], v[166:169], v[202:205], v[26:29]
	v_mfma_f32_16x16x32_bf16 v[22:25], v[178:181], v[202:205], v[22:25]
	v_mfma_f32_16x16x32_bf16 v[10:13], v[166:169], v[234:237], v[10:13]
	v_mfma_f32_16x16x32_bf16 v[6:9], v[178:181], v[234:237], v[6:9]
	v_mfma_f32_16x16x32_bf16 v[70:73], v[182:185], v[190:193], v[50:53]
	v_mfma_f32_16x16x32_bf16 v[42:45], v[170:173], v[198:201], v[42:45]
	v_mfma_f32_16x16x32_bf16 v[38:41], v[182:185], v[198:201], v[38:41]
	v_mfma_f32_16x16x32_bf16 v[26:29], v[170:173], v[230:233], v[26:29]
	v_mfma_f32_16x16x32_bf16 v[22:25], v[182:185], v[230:233], v[22:25]
	v_mfma_f32_16x16x32_bf16 v[10:13], v[170:173], v[238:241], v[10:13]
	v_mfma_f32_16x16x32_bf16 v[6:9], v[182:185], v[238:241], v[6:9]
	s_barrier
	s_add_i32 s83, s83, 2
	s_add_u32 s81, s81, 0x100
	s_addc_u32 s82, s82, 0
	s_cmpk_gt_u32 s83, 0x55
	s_mov_b64 s[30:31], s[10:11]
	s_cbranch_scc0 .LBB0_235
	v_lshl_or_b32 v170, s80, 8, v176
	v_ashrrev_i32_e32 v171, 31, v170
	v_mov_b32_e32 v54, 0
	v_cndmask_b32_e64 v50, 0, 1, s[20:21]
	v_lshl_add_u64 v[166:167], v[170:171], 2, s[24:25]
	v_cmp_ne_u32_e64 s[10:11], 1, v50
	s_andn2_b64 vcc, exec, s[20:21]
	v_mov_b32_e32 v62, 0
	v_mov_b32_e32 v63, v54
	v_mov_b32_e32 v64, 0
	v_mov_b32_e32 v65, 0
	s_cbranch_vccnz .LBB0_238
	global_load_dwordx4 v[62:65], v[166:167], off

; #define PG8_STAGE(bufoff, gbase, voff) do { _Pragma("unroll") for (int _i = 0; _i < 2; ++_i) \
;         __builtin_amdgcn_global_load_lds((const unsigned*)((const char*)(gbase) + (voff)[_i]), (PG8_LAS unsigned*)(lds + (bufoff) + ldsw + _i * 8192), 16, 0, 0); } while (0)
; #define PG8_LDA(dst, b, h) do { _Pragma("unroll") for (int m = 0; m < 4; ++m) _Pragma("unroll") for (int k = 0; k < 2; ++k) dst[m][k] = *(const PG8_LAS bf16x8*)(lds + PG8_SA(b, h) + aoff + m * 2048 + k * 1024); } while (0)
; #define PG8_LDB(dst, b, h) do { _Pragma("unroll") for (int n = 0; n < 2; ++n) _Pragma("unroll") for (int k = 0; k < 2; ++k) dst[n][k] = *(const PG8_LAS bf16x8*)(lds + PG8_SB(b, h) + boff + n * 2048 + k * 1024); } while (0)
; template <class Epi, class Sched, bool ALIGN_EPI = false, bool SP2 = false>
; __device__ __forceinline__ void gemm_phase(PG8_LAS unsigned char* lds, const Gemm g, const Sched& S, const Epi& E) {
;     ...
;         for (int t = 0; t < nt; t += 2) {
;             const bool last = (t == nt - 2);
;             const char* a1 = cA + (size_t)(t + 1) * kstep;
;             const char* a2 = last ? nA : cA + (size_t)(t + 2) * kstep; const char* b2 = last ? nB : cB + (size_t)(t + 2) * kstep;
;             const char* a3 = a2 + kstep; const char* b3 = b2 + kstep;
;             if (last && has_next) S.a_ready(nxt);
;             if constexpr (SP2) {
;             PG8_LDB(B0, 0, 0); PG8_LDB(B1, 0, 1); PG8_SCHED; PG8_LDA(At, 0, 0); PG8_STAGE(PG8_SA(1, 1), a1 + hstep, voffA);
;             PG8_WAIT_V(8); PG8_WAIT_L(0); PG8_BAR; PG8_MMA(0, 0, At, B0); PG8_MMA(0, 1, At, B1); PG8_BAR; PG8_SCHED;
;             PG8_LDA(At, 0, 1); PG8_STAGE(PG8_SB(0, 0), b2, voffB); PG8_STAGE(PG8_SB(0, 1), b2 + hstep, voffB); PG8_STAGE(PG8_SA(0, 0), a2, voffA);
;             PG8_WAIT_V(8); PG8_WAIT_L(0); PG8_BAR; PG8_MMA(1, 0, At, B0); PG8_MMA(1, 1, At, B1); PG8_BAR; PG8_SCHED;
;             PG8_LDB(B0, 1, 0); PG8_LDB(B1, 1, 1); PG8_SCHED; PG8_LDA(At, 1, 0); PG8_STAGE(PG8_SA(0, 1), a2 + hstep, voffA);
;             PG8_WAIT_V(8); PG8_WAIT_L(0); PG8_BAR; PG8_MMA(0, 0, At, B0); PG8_MMA(0, 1, At, B1); PG8_BAR; PG8_SCHED;
;             PG8_LDA(At, 1, 1); PG8_STAGE(PG8_SB(1, 0), b3, voffB); PG8_STAGE(PG8_SB(1, 1), b3 + hstep, voffB); PG8_STAGE(PG8_SA(1, 0), a3, voffA);
;             PG8_WAIT_V(8); PG8_WAIT_L(0); PG8_BAR; PG8_MMA(1, 0, At, B0); PG8_MMA(1, 1, At, B1); PG8_BAR; PG8_SCHED;
.LBB0_396:
	s_add_u32 s30, s10, 0xfff80080
	s_addc_u32 s31, s11, -1
	s_add_i32 s78, 0, 0x10000
	s_cmp_eq_u32 s71, 28
	s_cselect_b32 s35, s23, s31
	s_cselect_b32 s34, s66, s30
	v_add_u32_e32 v2, s78, v141
	s_cselect_b32 s31, s21, s70
	s_cselect_b32 s30, s67, s69
	s_add_i32 s80, 0, 0x14000
	ds_read_b128 v[146:149], v2
	ds_read_b128 v[162:165], v2 offset:1024
	ds_read_b128 v[166:169], v2 offset:2048
	ds_read_b128 v[172:175], v2 offset:3072
	v_add_u32_e32 v2, s80, v141
	ds_read_b128 v[176:179], v2
	ds_read_b128 v[180:183], v2 offset:1024
	ds_read_b128 v[184:187], v2 offset:2048
	ds_read_b128 v[188:191], v2 offset:3072
	s_add_i32 m0, s45, 0xc000
	ds_read_b128 v[192:195], v170
	ds_read_b128 v[196:199], v170 offset:1024
	ds_read_b128 v[200:203], v170 offset:2048
	ds_read_b128 v[204:207], v170 offset:3072
	ds_read_b128 v[230:233], v170 offset:4096
	ds_read_b128 v[234:237], v170 offset:5120
	ds_read_b128 v[238:241], v170 offset:6144
	ds_read_b128 v[242:245], v170 offset:7168
	global_load_lds_dwordx4 v144, s[10:11]
	s_add_i32 m0, s45, 0xe000
	s_nop 0
	global_load_lds_dwordx4 v142, s[10:11]
	s_waitcnt vmcnt(8)
	s_waitcnt lgkmcnt(0)
	s_barrier
	s_waitcnt lgkmcnt(0)
	v_mfma_f32_16x16x32_bf16 v[130:133], v[146:149], v[192:195], v[130:133]
	v_mfma_f32_16x16x32_bf16 v[126:129], v[166:169], v[192:195], v[126:129]
	v_mfma_f32_16x16x32_bf16 v[114:117], v[146:149], v[200:203], v[114:117]
	v_mfma_f32_16x16x32_bf16 v[110:113], v[166:169], v[200:203], v[110:113]
	v_mfma_f32_16x16x32_bf16 v[98:101], v[146:149], v[230:233], v[98:101]
	v_mfma_f32_16x16x32_bf16 v[94:97], v[166:169], v[230:233], v[94:97]
	v_mfma_f32_16x16x32_bf16 v[82:85], v[146:149], v[238:241], v[82:85]
	v_mfma_f32_16x16x32_bf16 v[78:81], v[166:169], v[238:241], v[78:81]
	v_mfma_f32_16x16x32_bf16 v[130:133], v[162:165], v[196:199], v[130:133]
	v_mfma_f32_16x16x32_bf16 v[126:129], v[172:175], v[196:199], v[126:129]
	v_mfma_f32_16x16x32_bf16 v[114:117], v[162:165], v[204:207], v[114:117]
	v_mfma_f32_16x16x32_bf16 v[110:113], v[172:175], v[204:207], v[110:113]
	v_mfma_f32_16x16x32_bf16 v[98:101], v[162:165], v[234:237], v[98:101]
	v_mfma_f32_16x16x32_bf16 v[94:97], v[172:175], v[234:237], v[94:97]
	v_mfma_f32_16x16x32_bf16 v[82:85], v[162:165], v[242:245], v[82:85]
	v_mfma_f32_16x16x32_bf16 v[78:81], v[172:175], v[242:245], v[78:81]
	v_mfma_f32_16x16x32_bf16 v[122:125], v[176:179], v[192:195], v[122:125]
	v_mfma_f32_16x16x32_bf16 v[118:121], v[184:187], v[192:195], v[118:121]
	v_mfma_f32_16x16x32_bf16 v[106:109], v[176:179], v[200:203], v[106:109]
	v_mfma_f32_16x16x32_bf16 v[102:105], v[184:187], v[200:203], v[102:105]
	v_mfma_f32_16x16x32_bf16 v[90:93], v[176:179], v[230:233], v[90:93]
	v_mfma_f32_16x16x32_bf16 v[86:89], v[184:187], v[230:233], v[86:89]
	v_mfma_f32_16x16x32_bf16 v[74:77], v[176:179], v[238:241], v[74:77]
	v_mfma_f32_16x16x32_bf16 v[70:73], v[184:187], v[238:241], v[70:73]
	v_mfma_f32_16x16x32_bf16 v[122:125], v[180:183], v[196:199], v[122:125]
	v_mfma_f32_16x16x32_bf16 v[118:121], v[188:191], v[196:199], v[118:121]
	v_mfma_f32_16x16x32_bf16 v[106:109], v[180:183], v[204:207], v[106:109]
	v_mfma_f32_16x16x32_bf16 v[102:105], v[188:191], v[204:207], v[102:105]
	v_mfma_f32_16x16x32_bf16 v[90:93], v[180:183], v[234:237], v[90:93]
	v_mfma_f32_16x16x32_bf16 v[86:89], v[188:191], v[234:237], v[86:89]
	v_mfma_f32_16x16x32_bf16 v[74:77], v[180:183], v[242:245], v[74:77]
	v_mfma_f32_16x16x32_bf16 v[70:73], v[188:191], v[242:245], v[70:73]
	s_barrier
	s_add_i32 s78, s78, s40
	s_mov_b32 m0, s78
	ds_read_b128 v[192:195], v170 offset:16384
	ds_read_b128 v[196:199], v170 offset:17408
	ds_read_b128 v[200:203], v170 offset:18432
	ds_read_b128 v[204:207], v170 offset:19456
	ds_read_b128 v[230:233], v170 offset:20480
	ds_read_b128 v[234:237], v170 offset:21504
	ds_read_b128 v[238:241], v170 offset:22528
	ds_read_b128 v[242:245], v170 offset:23552
	global_load_lds_dwordx4 v136, s[30:31]
	s_add_i32 m0, s78, 0x2000
	s_add_u32 s78, s30, 0x80000
	s_addc_u32 s79, s31, 0
	s_add_i32 s80, s80, s40
	global_load_lds_dwordx4 v0, s[30:31]
	s_mov_b32 m0, s80
	v_lshl_add_u64 v[250:251], s[34:35], 0, v[134:135]
	global_load_lds_dwordx4 v136, s[78:79]
	s_add_i32 m0, s80, 0x2000
	s_nop 0
	global_load_lds_dwordx4 v0, s[78:79]
	v_lshl_add_u64 v[248:249], s[34:35], 0, v[138:139]
	s_mov_b32 m0, s45
	s_nop 0
	global_load_lds_dwordx4 v138, s[34:35]
	s_mov_b32 m0, s46
	s_nop 0
	global_load_lds_dwordx4 v134, s[34:35]
	s_waitcnt vmcnt(8)
	s_waitcnt lgkmcnt(0)
	s_barrier
	s_waitcnt lgkmcnt(0)
	v_mfma_f32_16x16x32_bf16 v[66:69], v[146:149], v[192:195], v[66:69]
	v_mfma_f32_16x16x32_bf16 v[62:65], v[166:169], v[192:195], v[62:65]
	v_mfma_f32_16x16x32_bf16 v[50:53], v[146:149], v[200:203], v[50:53]
	v_mfma_f32_16x16x32_bf16 v[46:49], v[166:169], v[200:203], v[46:49]
	v_mfma_f32_16x16x32_bf16 v[34:37], v[146:149], v[230:233], v[34:37]
	v_mfma_f32_16x16x32_bf16 v[30:33], v[166:169], v[230:233], v[30:33]
	v_mfma_f32_16x16x32_bf16 v[18:21], v[146:149], v[238:241], v[18:21]
	v_mfma_f32_16x16x32_bf16 v[14:17], v[166:169], v[238:241], v[14:17]
	v_mfma_f32_16x16x32_bf16 v[66:69], v[162:165], v[196:199], v[66:69]
	v_mfma_f32_16x16x32_bf16 v[62:65], v[172:175], v[196:199], v[62:65]
	v_mfma_f32_16x16x32_bf16 v[50:53], v[162:165], v[204:207], v[50:53]
	v_mfma_f32_16x16x32_bf16 v[46:49], v[172:175], v[204:207], v[46:49]
	v_mfma_f32_16x16x32_bf16 v[34:37], v[162:165], v[234:237], v[34:37]
	v_mfma_f32_16x16x32_bf16 v[30:33], v[172:175], v[234:237], v[30:33]
	v_mfma_f32_16x16x32_bf16 v[18:21], v[162:165], v[242:245], v[18:21]
	v_mfma_f32_16x16x32_bf16 v[14:17], v[172:175], v[242:245], v[14:17]
	v_mfma_f32_16x16x32_bf16 v[58:61], v[176:179], v[192:195], v[58:61]
	v_mfma_f32_16x16x32_bf16 v[54:57], v[184:187], v[192:195], v[54:57]
	v_mfma_f32_16x16x32_bf16 v[42:45], v[176:179], v[200:203], v[42:45]
	v_mfma_f32_16x16x32_bf16 v[38:41], v[184:187], v[200:203], v[38:41]
	v_mfma_f32_16x16x32_bf16 v[26:29], v[176:179], v[230:233], v[26:29]
	v_mfma_f32_16x16x32_bf16 v[22:25], v[184:187], v[230:233], v[22:25]
	v_mfma_f32_16x16x32_bf16 v[10:13], v[176:179], v[238:241], v[10:13]
	v_mfma_f32_16x16x32_bf16 v[6:9], v[184:187], v[238:241], v[6:9]
	v_mfma_f32_16x16x32_bf16 v[58:61], v[180:183], v[196:199], v[58:61]
	v_mfma_f32_16x16x32_bf16 v[54:57], v[188:191], v[196:199], v[54:57]
	v_mfma_f32_16x16x32_bf16 v[42:45], v[180:183], v[204:207], v[42:45]
	v_mfma_f32_16x16x32_bf16 v[38:41], v[188:191], v[204:207], v[38:41]
	v_mfma_f32_16x16x32_bf16 v[26:29], v[180:183], v[234:237], v[26:29]
	v_mfma_f32_16x16x32_bf16 v[22:25], v[188:191], v[234:237], v[22:25]
	v_mfma_f32_16x16x32_bf16 v[10:13], v[180:183], v[242:245], v[10:13]
	v_mfma_f32_16x16x32_bf16 v[6:9], v[188:191], v[242:245], v[6:9]
	s_barrier
; #define PG8_STAGE(bufoff, gbase, voff) do { _Pragma("unroll") for (int _i = 0; _i < 2; ++_i) \
;         __builtin_amdgcn_global_load_lds((const unsigned*)((const char*)(gbase) + (voff)[_i]), (PG8_LAS unsigned*)(lds + (bufoff) + ldsw + _i * 8192), 16, 0, 0); } while (0)
; #define PG8_LDA(dst, b, h) do { _Pragma("unroll") for (int m = 0; m < 4; ++m) _Pragma("unroll") for (int k = 0; k < 2; ++k) dst[m][k] = *(const PG8_LAS bf16x8*)(lds + PG8_SA(b, h) + aoff + m * 2048 + k * 1024); } while (0)
; #define PG8_WAIT_V(n) asm volatile("s_waitcnt vmcnt(" #n ")" ::: "memory")
; #define PG8_WAIT_L(n) asm volatile("s_waitcnt lgkmcnt(" #n ")" ::: "memory")
; template <class Epi, class Sched, bool ALIGN_EPI = false, bool SP2 = false>
; __device__ __forceinline__ void gemm_phase(PG8_LAS unsigned char* lds, const Gemm g, const Sched& S, const Epi& E) {
;     ...
;         for (int t = 0; t < nt; t += 2) {
;             const bool last = (t == nt - 2);
;             const char* a1 = cA + (size_t)(t + 1) * kstep;
;             const char* a2 = last ? nA : cA + (size_t)(t + 2) * kstep; const char* b2 = last ? nB : cB + (size_t)(t + 2) * kstep;
;             const char* a3 = a2 + kstep; const char* b3 = b2 + kstep;
;             if (last && has_next) S.a_ready(nxt);
;             if constexpr (SP2) {
;             PG8_LDB(B0, 0, 0); PG8_LDB(B1, 0, 1); PG8_SCHED; PG8_LDA(At, 0, 0); PG8_STAGE(PG8_SA(1, 1), a1 + hstep, voffA);
;             PG8_WAIT_V(8); PG8_WAIT_L(0); PG8_BAR; PG8_MMA(0, 0, At, B0); PG8_MMA(0, 1, At, B1); PG8_BAR; PG8_SCHED;
;             PG8_LDA(At, 0, 1); PG8_STAGE(PG8_SB(0, 0), b2, voffB); PG8_STAGE(PG8_SB(0, 1), b2 + hstep, voffB); PG8_STAGE(PG8_SA(0, 0), a2, voffA);
;             PG8_WAIT_V(8); PG8_WAIT_L(0); PG8_BAR; PG8_MMA(1, 0, At, B0); PG8_MMA(1, 1, At, B1); PG8_BAR; PG8_SCHED;
;             PG8_LDB(B0, 1, 0); PG8_LDB(B1, 1, 1); PG8_SCHED; PG8_LDA(At, 1, 0); PG8_STAGE(PG8_SA(0, 1), a2 + hstep, voffA);
;             PG8_WAIT_V(8); PG8_WAIT_L(0); PG8_BAR; PG8_MMA(0, 0, At, B0); PG8_MMA(0, 1, At, B1); PG8_BAR; PG8_SCHED;
;             PG8_LDA(At, 1, 1); PG8_STAGE(PG8_SB(1, 0), b3, voffB); PG8_STAGE(PG8_SB(1, 1), b3 + hstep, voffB); PG8_STAGE(PG8_SA(1, 0), a3, voffA);
;             PG8_WAIT_V(8); PG8_WAIT_L(0); PG8_BAR; PG8_MMA(1, 0, At, B0); PG8_MMA(1, 1, At, B1); PG8_BAR; PG8_SCHED;
;     ...
;         if constexpr (ALIGN_EPI) { if (wr == 0) PG8_BAR; }
	s_add_i32 s78, 0, 0x18000
	v_add_u32_e32 v2, s78, v141
	s_add_i32 s79, 0, 0x1c000
	ds_read_b128 v[146:149], v2
	ds_read_b128 v[162:165], v2 offset:1024
	ds_read_b128 v[166:169], v2 offset:2048
	ds_read_b128 v[172:175], v2 offset:3072
	v_add_u32_e32 v2, s79, v141
	ds_read_b128 v[176:179], v2
	ds_read_b128 v[180:183], v2 offset:1024
	ds_read_b128 v[184:187], v2 offset:2048
	ds_read_b128 v[188:191], v2 offset:3072
	s_add_u32 s34, s34, 0x80000
	s_addc_u32 s35, s35, 0
	s_mov_b32 m0, s47
	ds_read_b128 v[192:195], v170 offset:32768
	ds_read_b128 v[196:199], v170 offset:33792
	ds_read_b128 v[200:203], v170 offset:34816
	ds_read_b128 v[204:207], v170 offset:35840
	ds_read_b128 v[230:233], v170 offset:36864
	ds_read_b128 v[234:237], v170 offset:37888
	ds_read_b128 v[238:241], v170 offset:38912
	ds_read_b128 v[242:245], v170 offset:39936
	global_load_lds_dwordx4 v138, s[34:35]
	s_mov_b32 m0, s48
	s_nop 0
	global_load_lds_dwordx4 v134, s[34:35]
	s_waitcnt vmcnt(8)
	s_waitcnt lgkmcnt(0)
	s_barrier
	s_waitcnt lgkmcnt(0)
	v_mfma_f32_16x16x32_bf16 v[130:133], v[146:149], v[192:195], v[130:133]
	v_mfma_f32_16x16x32_bf16 v[126:129], v[166:169], v[192:195], v[126:129]
	v_mfma_f32_16x16x32_bf16 v[114:117], v[146:149], v[200:203], v[114:117]
	v_mfma_f32_16x16x32_bf16 v[110:113], v[166:169], v[200:203], v[110:113]
	v_mfma_f32_16x16x32_bf16 v[98:101], v[146:149], v[230:233], v[98:101]
	v_mfma_f32_16x16x32_bf16 v[94:97], v[166:169], v[230:233], v[94:97]
	v_mfma_f32_16x16x32_bf16 v[82:85], v[146:149], v[238:241], v[82:85]
	v_mfma_f32_16x16x32_bf16 v[78:81], v[166:169], v[238:241], v[78:81]
	v_mfma_f32_16x16x32_bf16 v[130:133], v[162:165], v[196:199], v[130:133]
	v_mfma_f32_16x16x32_bf16 v[126:129], v[172:175], v[196:199], v[126:129]
	v_mfma_f32_16x16x32_bf16 v[114:117], v[162:165], v[204:207], v[114:117]
	v_mfma_f32_16x16x32_bf16 v[110:113], v[172:175], v[204:207], v[110:113]
	v_mfma_f32_16x16x32_bf16 v[98:101], v[162:165], v[234:237], v[98:101]
	v_mfma_f32_16x16x32_bf16 v[94:97], v[172:175], v[234:237], v[94:97]
	v_mfma_f32_16x16x32_bf16 v[82:85], v[162:165], v[242:245], v[82:85]
	v_mfma_f32_16x16x32_bf16 v[78:81], v[172:175], v[242:245], v[78:81]
	v_mfma_f32_16x16x32_bf16 v[122:125], v[176:179], v[192:195], v[122:125]
	v_mfma_f32_16x16x32_bf16 v[118:121], v[184:187], v[192:195], v[118:121]
	v_mfma_f32_16x16x32_bf16 v[106:109], v[176:179], v[200:203], v[106:109]
	v_mfma_f32_16x16x32_bf16 v[102:105], v[184:187], v[200:203], v[102:105]
	v_mfma_f32_16x16x32_bf16 v[90:93], v[176:179], v[230:233], v[90:93]
	v_mfma_f32_16x16x32_bf16 v[86:89], v[184:187], v[230:233], v[86:89]
	v_mfma_f32_16x16x32_bf16 v[74:77], v[176:179], v[238:241], v[74:77]
	v_mfma_f32_16x16x32_bf16 v[70:73], v[184:187], v[238:241], v[70:73]
	v_mfma_f32_16x16x32_bf16 v[122:125], v[180:183], v[196:199], v[122:125]
	v_mfma_f32_16x16x32_bf16 v[118:121], v[188:191], v[196:199], v[118:121]
	v_mfma_f32_16x16x32_bf16 v[106:109], v[180:183], v[204:207], v[106:109]
	v_mfma_f32_16x16x32_bf16 v[102:105], v[188:191], v[204:207], v[102:105]
	v_mfma_f32_16x16x32_bf16 v[90:93], v[180:183], v[234:237], v[90:93]
	v_mfma_f32_16x16x32_bf16 v[86:89], v[188:191], v[234:237], v[86:89]
	v_mfma_f32_16x16x32_bf16 v[74:77], v[180:183], v[242:245], v[74:77]
	v_mfma_f32_16x16x32_bf16 v[70:73], v[188:191], v[242:245], v[70:73]
	s_barrier
	s_add_u32 vcc_lo, s30, s2
	s_addc_u32 vcc_hi, s31, s3
	s_add_i32 s34, s78, s40
	s_mov_b32 m0, s34
	ds_read_b128 v[192:195], v170 offset:49152
	ds_read_b128 v[196:199], v170 offset:50176
	ds_read_b128 v[200:203], v170 offset:51200
	ds_read_b128 v[204:207], v170 offset:52224
	ds_read_b128 v[230:233], v170 offset:53248
	ds_read_b128 v[234:237], v170 offset:54272
	ds_read_b128 v[238:241], v170 offset:55296
	ds_read_b128 v[242:245], v170 offset:56320
	global_load_lds_dwordx4 v136, vcc
	s_add_i32 m0, s34, 0x2000
	s_add_u32 s30, s30, 0x80080
	s_addc_u32 s31, s31, 0
	s_add_i32 s34, s79, s40
	global_load_lds_dwordx4 v0, vcc
	s_mov_b32 m0, s34
	s_nop 0
	global_load_lds_dwordx4 v136, s[30:31]
	s_add_i32 m0, s34, 0x2000
	s_nop 0
	global_load_lds_dwordx4 v0, s[30:31]
	v_lshl_add_u64 v[158:159], v[248:249], 0, s[2:3]
	s_mov_b32 m0, s49
	s_nop 0
	global_load_lds_dwordx4 v[158:159], off
	v_lshl_add_u64 v[158:159], v[250:251], 0, s[2:3]
	s_mov_b32 m0, s50
	s_nop 0
	global_load_lds_dwordx4 v[158:159], off
	s_waitcnt vmcnt(8)
	s_waitcnt lgkmcnt(0)
	s_barrier
	s_waitcnt lgkmcnt(0)
	v_mfma_f32_16x16x32_bf16 v[66:69], v[146:149], v[192:195], v[66:69]
	v_mfma_f32_16x16x32_bf16 v[62:65], v[166:169], v[192:195], v[62:65]
	v_mfma_f32_16x16x32_bf16 v[50:53], v[146:149], v[200:203], v[50:53]
	v_mfma_f32_16x16x32_bf16 v[46:49], v[166:169], v[200:203], v[46:49]
	v_mfma_f32_16x16x32_bf16 v[34:37], v[146:149], v[230:233], v[34:37]
	v_mfma_f32_16x16x32_bf16 v[30:33], v[166:169], v[230:233], v[30:33]
	v_mfma_f32_16x16x32_bf16 v[18:21], v[146:149], v[238:241], v[18:21]
	v_mfma_f32_16x16x32_bf16 v[14:17], v[166:169], v[238:241], v[14:17]
	v_mfma_f32_16x16x32_bf16 v[66:69], v[162:165], v[196:199], v[66:69]
	v_mfma_f32_16x16x32_bf16 v[62:65], v[172:175], v[196:199], v[62:65]
	v_mfma_f32_16x16x32_bf16 v[50:53], v[162:165], v[204:207], v[50:53]
	v_mfma_f32_16x16x32_bf16 v[46:49], v[172:175], v[204:207], v[46:49]
	v_mfma_f32_16x16x32_bf16 v[34:37], v[162:165], v[234:237], v[34:37]
	v_mfma_f32_16x16x32_bf16 v[30:33], v[172:175], v[234:237], v[30:33]
	v_mfma_f32_16x16x32_bf16 v[18:21], v[162:165], v[242:245], v[18:21]
	v_mfma_f32_16x16x32_bf16 v[14:17], v[172:175], v[242:245], v[14:17]
	v_mfma_f32_16x16x32_bf16 v[58:61], v[176:179], v[192:195], v[58:61]
	v_mfma_f32_16x16x32_bf16 v[54:57], v[184:187], v[192:195], v[54:57]
	v_mfma_f32_16x16x32_bf16 v[42:45], v[176:179], v[200:203], v[42:45]
	v_mfma_f32_16x16x32_bf16 v[38:41], v[184:187], v[200:203], v[38:41]
	v_mfma_f32_16x16x32_bf16 v[26:29], v[176:179], v[230:233], v[26:29]
	v_mfma_f32_16x16x32_bf16 v[22:25], v[184:187], v[230:233], v[22:25]
	v_mfma_f32_16x16x32_bf16 v[10:13], v[176:179], v[238:241], v[10:13]
	v_mfma_f32_16x16x32_bf16 v[6:9], v[184:187], v[238:241], v[6:9]
	v_mfma_f32_16x16x32_bf16 v[58:61], v[180:183], v[196:199], v[58:61]
	v_mfma_f32_16x16x32_bf16 v[54:57], v[188:191], v[196:199], v[54:57]
	v_mfma_f32_16x16x32_bf16 v[42:45], v[180:183], v[204:207], v[42:45]
	v_mfma_f32_16x16x32_bf16 v[38:41], v[188:191], v[204:207], v[38:41]
	v_mfma_f32_16x16x32_bf16 v[26:29], v[180:183], v[234:237], v[26:29]
	v_mfma_f32_16x16x32_bf16 v[22:25], v[188:191], v[234:237], v[22:25]
	v_mfma_f32_16x16x32_bf16 v[10:13], v[180:183], v[242:245], v[10:13]
	v_mfma_f32_16x16x32_bf16 v[6:9], v[188:191], v[242:245], v[6:9]
	s_barrier
	s_add_i32 s71, s71, 2
	s_add_u32 s69, s69, 0x100
	s_addc_u32 s70, s70, 0
	s_add_u32 s10, s10, 0x100
	s_addc_u32 s11, s11, 0
	s_cmp_gt_u32 s71, 29
	s_cbranch_scc0 .LBB0_396
	s_and_b64 vcc, exec, s[18:19]
	s_cbranch_vccz .LBB0_399
	s_barrier

; #define PG8_STAGE(bufoff, gbase, voff) do { _Pragma("unroll") for (int _i = 0; _i < 2; ++_i) \
;         __builtin_amdgcn_global_load_lds((const unsigned*)((const char*)(gbase) + (voff)[_i]), (PG8_LAS unsigned*)(lds + (bufoff) + ldsw + _i * 8192), 16, 0, 0); } while (0)
; #define PG8_LDA(dst, b, h) do { _Pragma("unroll") for (int m = 0; m < 4; ++m) _Pragma("unroll") for (int k = 0; k < 2; ++k) dst[m][k] = *(const PG8_LAS bf16x8*)(lds + PG8_SA(b, h) + aoff + m * 2048 + k * 1024); } while (0)
; #define PG8_LDB(dst, b, h) do { _Pragma("unroll") for (int n = 0; n < 2; ++n) _Pragma("unroll") for (int k = 0; k < 2; ++k) dst[n][k] = *(const PG8_LAS bf16x8*)(lds + PG8_SB(b, h) + boff + n * 2048 + k * 1024); } while (0)
; template <class Epi, class Sched, bool ALIGN_EPI = false, bool SP2 = false>
; __device__ __forceinline__ void gemm_phase(PG8_LAS unsigned char* lds, const Gemm g, const Sched& S, const Epi& E) {
;     ...
;         for (int t = 0; t < nt; t += 2) {
;             const bool last = (t == nt - 2);
;             const char* a1 = cA + (size_t)(t + 1) * kstep;
;             const char* a2 = last ? nA : cA + (size_t)(t + 2) * kstep; const char* b2 = last ? nB : cB + (size_t)(t + 2) * kstep;
;             const char* a3 = a2 + kstep; const char* b3 = b2 + kstep;
;             if (last && has_next) S.a_ready(nxt);
;             if constexpr (SP2) {
;             PG8_LDB(B0, 0, 0); PG8_LDB(B1, 0, 1); PG8_SCHED; PG8_LDA(At, 0, 0); PG8_STAGE(PG8_SA(1, 1), a1 + hstep, voffA);
;             PG8_WAIT_V(8); PG8_WAIT_L(0); PG8_BAR; PG8_MMA(0, 0, At, B0); PG8_MMA(0, 1, At, B1); PG8_BAR; PG8_SCHED;
;             PG8_LDA(At, 0, 1); PG8_STAGE(PG8_SB(0, 0), b2, voffB); PG8_STAGE(PG8_SB(0, 1), b2 + hstep, voffB); PG8_STAGE(PG8_SA(0, 0), a2, voffA);
;             PG8_WAIT_V(8); PG8_WAIT_L(0); PG8_BAR; PG8_MMA(1, 0, At, B0); PG8_MMA(1, 1, At, B1); PG8_BAR; PG8_SCHED;
;             PG8_LDB(B0, 1, 0); PG8_LDB(B1, 1, 1); PG8_SCHED; PG8_LDA(At, 1, 0); PG8_STAGE(PG8_SA(0, 1), a2 + hstep, voffA);
;             PG8_WAIT_V(8); PG8_WAIT_L(0); PG8_BAR; PG8_MMA(0, 0, At, B0); PG8_MMA(0, 1, At, B1); PG8_BAR; PG8_SCHED;
;             PG8_LDA(At, 1, 1); PG8_STAGE(PG8_SB(1, 0), b3, voffB); PG8_STAGE(PG8_SB(1, 1), b3 + hstep, voffB); PG8_STAGE(PG8_SA(1, 0), a3, voffA);
;             PG8_WAIT_V(8); PG8_WAIT_L(0); PG8_BAR; PG8_MMA(1, 0, At, B0); PG8_MMA(1, 1, At, B1); PG8_BAR; PG8_SCHED;
.LBB0_818:
	s_add_u32 s30, s26, 0xfffc0080
	s_addc_u32 s31, s27, -1
	s_add_i32 s78, 0, 0x10000
	s_cmp_eq_u32 s71, 12
	s_cselect_b32 s35, s21, s31
	s_cselect_b32 s34, s66, s30
	v_add_u32_e32 v149, s78, v146
	s_cselect_b32 s31, s19, s70
	s_cselect_b32 s30, s67, s69
	s_add_i32 s80, 0, 0x14000
	ds_read_b128 v[142:145], v149
	ds_read_b128 v[162:165], v149 offset:1024
	ds_read_b128 v[166:169], v149 offset:2048
	ds_read_b128 v[170:173], v149 offset:3072
	v_add_u32_e32 v149, s80, v146
	ds_read_b128 v[174:177], v149
	ds_read_b128 v[178:181], v149 offset:1024
	ds_read_b128 v[182:185], v149 offset:2048
	ds_read_b128 v[186:189], v149 offset:3072
	s_add_i32 m0, s44, 0xc000
	ds_read_b128 v[190:193], v148
	ds_read_b128 v[194:197], v148 offset:1024
	ds_read_b128 v[198:201], v148 offset:2048
	ds_read_b128 v[202:205], v148 offset:3072
	ds_read_b128 v[230:233], v148 offset:4096
	ds_read_b128 v[234:237], v148 offset:5120
	ds_read_b128 v[238:241], v148 offset:6144
	ds_read_b128 v[242:245], v148 offset:7168
	global_load_lds_dwordx4 v140, s[26:27]
	s_add_i32 m0, s44, 0xe000
	s_nop 0
	global_load_lds_dwordx4 v138, s[26:27]
	s_waitcnt vmcnt(8)
	s_waitcnt lgkmcnt(0)
	s_barrier
	s_waitcnt lgkmcnt(0)
	v_mfma_f32_16x16x32_bf16 v[130:133], v[142:145], v[190:193], v[130:133]
	v_mfma_f32_16x16x32_bf16 v[126:129], v[166:169], v[190:193], v[126:129]
	v_mfma_f32_16x16x32_bf16 v[118:121], v[142:145], v[198:201], v[118:121]
	v_mfma_f32_16x16x32_bf16 v[110:113], v[166:169], v[198:201], v[110:113]
	v_mfma_f32_16x16x32_bf16 v[98:101], v[142:145], v[230:233], v[98:101]
	v_mfma_f32_16x16x32_bf16 v[94:97], v[166:169], v[230:233], v[94:97]
	v_mfma_f32_16x16x32_bf16 v[82:85], v[142:145], v[238:241], v[82:85]
	v_mfma_f32_16x16x32_bf16 v[78:81], v[166:169], v[238:241], v[78:81]
	v_mfma_f32_16x16x32_bf16 v[130:133], v[162:165], v[194:197], v[130:133]
	v_mfma_f32_16x16x32_bf16 v[126:129], v[170:173], v[194:197], v[126:129]
	v_mfma_f32_16x16x32_bf16 v[118:121], v[162:165], v[202:205], v[118:121]
	v_mfma_f32_16x16x32_bf16 v[110:113], v[170:173], v[202:205], v[110:113]
	v_mfma_f32_16x16x32_bf16 v[98:101], v[162:165], v[234:237], v[98:101]
	v_mfma_f32_16x16x32_bf16 v[94:97], v[170:173], v[234:237], v[94:97]
	v_mfma_f32_16x16x32_bf16 v[82:85], v[162:165], v[242:245], v[82:85]
	v_mfma_f32_16x16x32_bf16 v[78:81], v[170:173], v[242:245], v[78:81]
	v_mfma_f32_16x16x32_bf16 v[122:125], v[174:177], v[190:193], v[122:125]
	v_mfma_f32_16x16x32_bf16 v[114:117], v[182:185], v[190:193], v[114:117]
	v_mfma_f32_16x16x32_bf16 v[106:109], v[174:177], v[198:201], v[106:109]
	v_mfma_f32_16x16x32_bf16 v[102:105], v[182:185], v[198:201], v[102:105]
	v_mfma_f32_16x16x32_bf16 v[90:93], v[174:177], v[230:233], v[90:93]
	v_mfma_f32_16x16x32_bf16 v[86:89], v[182:185], v[230:233], v[86:89]
	v_mfma_f32_16x16x32_bf16 v[74:77], v[174:177], v[238:241], v[74:77]
	v_mfma_f32_16x16x32_bf16 v[70:73], v[182:185], v[238:241], v[70:73]
	v_mfma_f32_16x16x32_bf16 v[122:125], v[178:181], v[194:197], v[122:125]
	v_mfma_f32_16x16x32_bf16 v[114:117], v[186:189], v[194:197], v[114:117]
	v_mfma_f32_16x16x32_bf16 v[106:109], v[178:181], v[202:205], v[106:109]
	v_mfma_f32_16x16x32_bf16 v[102:105], v[186:189], v[202:205], v[102:105]
	v_mfma_f32_16x16x32_bf16 v[90:93], v[178:181], v[234:237], v[90:93]
	v_mfma_f32_16x16x32_bf16 v[86:89], v[186:189], v[234:237], v[86:89]
	v_mfma_f32_16x16x32_bf16 v[74:77], v[178:181], v[242:245], v[74:77]
	v_mfma_f32_16x16x32_bf16 v[70:73], v[186:189], v[242:245], v[70:73]
	s_barrier
	s_add_i32 s78, s78, s41
	s_mov_b32 m0, s78
	ds_read_b128 v[190:193], v148 offset:16384
	ds_read_b128 v[194:197], v148 offset:17408
	ds_read_b128 v[198:201], v148 offset:18432
	ds_read_b128 v[202:205], v148 offset:19456
	ds_read_b128 v[230:233], v148 offset:20480
	ds_read_b128 v[234:237], v148 offset:21504
	ds_read_b128 v[238:241], v148 offset:22528
	ds_read_b128 v[242:245], v148 offset:23552
	global_load_lds_dwordx4 v2, s[30:31]
	s_add_i32 m0, s78, 0x2000
	s_add_u32 s78, s30, 0x40000
	s_addc_u32 s79, s31, 0
	s_add_i32 s80, s80, s41
	global_load_lds_dwordx4 v0, s[30:31]
	s_mov_b32 m0, s80
	v_lshl_add_u64 v[246:247], s[34:35], 0, v[134:135]
	global_load_lds_dwordx4 v2, s[78:79]
	s_add_i32 m0, s80, 0x2000
	s_nop 0
	global_load_lds_dwordx4 v0, s[78:79]
	v_lshl_add_u64 v[206:207], s[34:35], 0, v[136:137]
	s_mov_b32 m0, s44
	s_nop 0
	global_load_lds_dwordx4 v136, s[34:35]
	s_mov_b32 m0, s45
	s_nop 0
	global_load_lds_dwordx4 v134, s[34:35]
	s_waitcnt vmcnt(8)
	s_waitcnt lgkmcnt(0)
	s_barrier
	s_waitcnt lgkmcnt(0)
	v_mfma_f32_16x16x32_bf16 v[66:69], v[142:145], v[190:193], v[66:69]
	v_mfma_f32_16x16x32_bf16 v[62:65], v[166:169], v[190:193], v[62:65]
	v_mfma_f32_16x16x32_bf16 v[50:53], v[142:145], v[198:201], v[50:53]
	v_mfma_f32_16x16x32_bf16 v[46:49], v[166:169], v[198:201], v[46:49]
	v_mfma_f32_16x16x32_bf16 v[34:37], v[142:145], v[230:233], v[34:37]
	v_mfma_f32_16x16x32_bf16 v[30:33], v[166:169], v[230:233], v[30:33]
	v_mfma_f32_16x16x32_bf16 v[18:21], v[142:145], v[238:241], v[18:21]
	v_mfma_f32_16x16x32_bf16 v[14:17], v[166:169], v[238:241], v[14:17]
	v_mfma_f32_16x16x32_bf16 v[66:69], v[162:165], v[194:197], v[66:69]
	v_mfma_f32_16x16x32_bf16 v[62:65], v[170:173], v[194:197], v[62:65]
	v_mfma_f32_16x16x32_bf16 v[50:53], v[162:165], v[202:205], v[50:53]
	v_mfma_f32_16x16x32_bf16 v[46:49], v[170:173], v[202:205], v[46:49]
	v_mfma_f32_16x16x32_bf16 v[34:37], v[162:165], v[234:237], v[34:37]
	v_mfma_f32_16x16x32_bf16 v[30:33], v[170:173], v[234:237], v[30:33]
	v_mfma_f32_16x16x32_bf16 v[18:21], v[162:165], v[242:245], v[18:21]
	v_mfma_f32_16x16x32_bf16 v[14:17], v[170:173], v[242:245], v[14:17]
	v_mfma_f32_16x16x32_bf16 v[58:61], v[174:177], v[190:193], v[58:61]
	v_mfma_f32_16x16x32_bf16 v[54:57], v[182:185], v[190:193], v[54:57]
	v_mfma_f32_16x16x32_bf16 v[42:45], v[174:177], v[198:201], v[42:45]
	v_mfma_f32_16x16x32_bf16 v[38:41], v[182:185], v[198:201], v[38:41]
	v_mfma_f32_16x16x32_bf16 v[26:29], v[174:177], v[230:233], v[26:29]
	v_mfma_f32_16x16x32_bf16 v[22:25], v[182:185], v[230:233], v[22:25]
	v_mfma_f32_16x16x32_bf16 v[10:13], v[174:177], v[238:241], v[10:13]
	v_mfma_f32_16x16x32_bf16 v[6:9], v[182:185], v[238:241], v[6:9]
	v_mfma_f32_16x16x32_bf16 v[58:61], v[178:181], v[194:197], v[58:61]
	v_mfma_f32_16x16x32_bf16 v[54:57], v[186:189], v[194:197], v[54:57]
	v_mfma_f32_16x16x32_bf16 v[42:45], v[178:181], v[202:205], v[42:45]
	v_mfma_f32_16x16x32_bf16 v[38:41], v[186:189], v[202:205], v[38:41]
	v_mfma_f32_16x16x32_bf16 v[26:29], v[178:181], v[234:237], v[26:29]
	v_mfma_f32_16x16x32_bf16 v[22:25], v[186:189], v[234:237], v[22:25]
	v_mfma_f32_16x16x32_bf16 v[10:13], v[178:181], v[242:245], v[10:13]
	v_mfma_f32_16x16x32_bf16 v[6:9], v[186:189], v[242:245], v[6:9]
	s_barrier
; #define PG8_STAGE(bufoff, gbase, voff) do { _Pragma("unroll") for (int _i = 0; _i < 2; ++_i) \
;         __builtin_amdgcn_global_load_lds((const unsigned*)((const char*)(gbase) + (voff)[_i]), (PG8_LAS unsigned*)(lds + (bufoff) + ldsw + _i * 8192), 16, 0, 0); } while (0)
; #define PG8_LDA(dst, b, h) do { _Pragma("unroll") for (int m = 0; m < 4; ++m) _Pragma("unroll") for (int k = 0; k < 2; ++k) dst[m][k] = *(const PG8_LAS bf16x8*)(lds + PG8_SA(b, h) + aoff + m * 2048 + k * 1024); } while (0)
; #define PG8_WAIT_V(n) asm volatile("s_waitcnt vmcnt(" #n ")" ::: "memory")
; #define PG8_WAIT_L(n) asm volatile("s_waitcnt lgkmcnt(" #n ")" ::: "memory")
; template <class Epi, class Sched, bool ALIGN_EPI = false, bool SP2 = false>
; __device__ __forceinline__ void gemm_phase(PG8_LAS unsigned char* lds, const Gemm g, const Sched& S, const Epi& E) {
;     ...
;         for (int t = 0; t < nt; t += 2) {
;             const bool last = (t == nt - 2);
;             const char* a1 = cA + (size_t)(t + 1) * kstep;
;             const char* a2 = last ? nA : cA + (size_t)(t + 2) * kstep; const char* b2 = last ? nB : cB + (size_t)(t + 2) * kstep;
;             const char* a3 = a2 + kstep; const char* b3 = b2 + kstep;
;             if (last && has_next) S.a_ready(nxt);
;             if constexpr (SP2) {
;             PG8_LDB(B0, 0, 0); PG8_LDB(B1, 0, 1); PG8_SCHED; PG8_LDA(At, 0, 0); PG8_STAGE(PG8_SA(1, 1), a1 + hstep, voffA);
;             PG8_WAIT_V(8); PG8_WAIT_L(0); PG8_BAR; PG8_MMA(0, 0, At, B0); PG8_MMA(0, 1, At, B1); PG8_BAR; PG8_SCHED;
;             PG8_LDA(At, 0, 1); PG8_STAGE(PG8_SB(0, 0), b2, voffB); PG8_STAGE(PG8_SB(0, 1), b2 + hstep, voffB); PG8_STAGE(PG8_SA(0, 0), a2, voffA);
;             PG8_WAIT_V(8); PG8_WAIT_L(0); PG8_BAR; PG8_MMA(1, 0, At, B0); PG8_MMA(1, 1, At, B1); PG8_BAR; PG8_SCHED;
;             PG8_LDB(B0, 1, 0); PG8_LDB(B1, 1, 1); PG8_SCHED; PG8_LDA(At, 1, 0); PG8_STAGE(PG8_SA(0, 1), a2 + hstep, voffA);
;             PG8_WAIT_V(8); PG8_WAIT_L(0); PG8_BAR; PG8_MMA(0, 0, At, B0); PG8_MMA(0, 1, At, B1); PG8_BAR; PG8_SCHED;
;             PG8_LDA(At, 1, 1); PG8_STAGE(PG8_SB(1, 0), b3, voffB); PG8_STAGE(PG8_SB(1, 1), b3 + hstep, voffB); PG8_STAGE(PG8_SA(1, 0), a3, voffA);
;             PG8_WAIT_V(8); PG8_WAIT_L(0); PG8_BAR; PG8_MMA(1, 0, At, B0); PG8_MMA(1, 1, At, B1); PG8_BAR; PG8_SCHED;
;     ...
;         if constexpr (ALIGN_EPI) { if (wr == 0) PG8_BAR; }
	s_add_i32 s78, 0, 0x18000
	v_add_u32_e32 v149, s78, v146
	s_add_i32 s79, 0, 0x1c000
	ds_read_b128 v[142:145], v149
	ds_read_b128 v[162:165], v149 offset:1024
	ds_read_b128 v[166:169], v149 offset:2048
	ds_read_b128 v[170:173], v149 offset:3072
	v_add_u32_e32 v149, s79, v146
	ds_read_b128 v[174:177], v149
	ds_read_b128 v[178:181], v149 offset:1024
	ds_read_b128 v[182:185], v149 offset:2048
	ds_read_b128 v[186:189], v149 offset:3072
	s_add_u32 s34, s34, 0x40000
	s_addc_u32 s35, s35, 0
	s_mov_b32 m0, s46
	ds_read_b128 v[190:193], v148 offset:32768
	ds_read_b128 v[194:197], v148 offset:33792
	ds_read_b128 v[198:201], v148 offset:34816
	ds_read_b128 v[202:205], v148 offset:35840
	ds_read_b128 v[230:233], v148 offset:36864
	ds_read_b128 v[234:237], v148 offset:37888
	ds_read_b128 v[238:241], v148 offset:38912
	ds_read_b128 v[242:245], v148 offset:39936
	global_load_lds_dwordx4 v136, s[34:35]
	s_mov_b32 m0, s47
	s_nop 0
	global_load_lds_dwordx4 v134, s[34:35]
	s_waitcnt vmcnt(8)
	s_waitcnt lgkmcnt(0)
	s_barrier
	s_waitcnt lgkmcnt(0)
	v_mfma_f32_16x16x32_bf16 v[130:133], v[142:145], v[190:193], v[130:133]
	v_mfma_f32_16x16x32_bf16 v[126:129], v[166:169], v[190:193], v[126:129]
	v_mfma_f32_16x16x32_bf16 v[118:121], v[142:145], v[198:201], v[118:121]
	v_mfma_f32_16x16x32_bf16 v[110:113], v[166:169], v[198:201], v[110:113]
	v_mfma_f32_16x16x32_bf16 v[98:101], v[142:145], v[230:233], v[98:101]
	v_mfma_f32_16x16x32_bf16 v[94:97], v[166:169], v[230:233], v[94:97]
	v_mfma_f32_16x16x32_bf16 v[82:85], v[142:145], v[238:241], v[82:85]
	v_mfma_f32_16x16x32_bf16 v[78:81], v[166:169], v[238:241], v[78:81]
	v_mfma_f32_16x16x32_bf16 v[130:133], v[162:165], v[194:197], v[130:133]
	v_mfma_f32_16x16x32_bf16 v[126:129], v[170:173], v[194:197], v[126:129]
	v_mfma_f32_16x16x32_bf16 v[118:121], v[162:165], v[202:205], v[118:121]
	v_mfma_f32_16x16x32_bf16 v[110:113], v[170:173], v[202:205], v[110:113]
	v_mfma_f32_16x16x32_bf16 v[98:101], v[162:165], v[234:237], v[98:101]
	v_mfma_f32_16x16x32_bf16 v[94:97], v[170:173], v[234:237], v[94:97]
	v_mfma_f32_16x16x32_bf16 v[82:85], v[162:165], v[242:245], v[82:85]
	v_mfma_f32_16x16x32_bf16 v[78:81], v[170:173], v[242:245], v[78:81]
	v_mfma_f32_16x16x32_bf16 v[122:125], v[174:177], v[190:193], v[122:125]
	v_mfma_f32_16x16x32_bf16 v[114:117], v[182:185], v[190:193], v[114:117]
	v_mfma_f32_16x16x32_bf16 v[106:109], v[174:177], v[198:201], v[106:109]
	v_mfma_f32_16x16x32_bf16 v[102:105], v[182:185], v[198:201], v[102:105]
	v_mfma_f32_16x16x32_bf16 v[90:93], v[174:177], v[230:233], v[90:93]
	v_mfma_f32_16x16x32_bf16 v[86:89], v[182:185], v[230:233], v[86:89]
	v_mfma_f32_16x16x32_bf16 v[74:77], v[174:177], v[238:241], v[74:77]
	v_mfma_f32_16x16x32_bf16 v[70:73], v[182:185], v[238:241], v[70:73]
	v_mfma_f32_16x16x32_bf16 v[122:125], v[178:181], v[194:197], v[122:125]
	v_mfma_f32_16x16x32_bf16 v[114:117], v[186:189], v[194:197], v[114:117]
	v_mfma_f32_16x16x32_bf16 v[106:109], v[178:181], v[202:205], v[106:109]
	v_mfma_f32_16x16x32_bf16 v[102:105], v[186:189], v[202:205], v[102:105]
	v_mfma_f32_16x16x32_bf16 v[90:93], v[178:181], v[234:237], v[90:93]
	v_mfma_f32_16x16x32_bf16 v[86:89], v[186:189], v[234:237], v[86:89]
	v_mfma_f32_16x16x32_bf16 v[74:77], v[178:181], v[242:245], v[74:77]
	v_mfma_f32_16x16x32_bf16 v[70:73], v[186:189], v[242:245], v[70:73]
	s_barrier
	s_add_u32 vcc_lo, s30, s2
	s_addc_u32 vcc_hi, s31, s3
	s_add_i32 s34, s78, s41
	s_mov_b32 m0, s34
	ds_read_b128 v[190:193], v148 offset:49152
	ds_read_b128 v[194:197], v148 offset:50176
	ds_read_b128 v[198:201], v148 offset:51200
	ds_read_b128 v[202:205], v148 offset:52224
	ds_read_b128 v[230:233], v148 offset:53248
	ds_read_b128 v[234:237], v148 offset:54272
	ds_read_b128 v[238:241], v148 offset:55296
	ds_read_b128 v[242:245], v148 offset:56320
	global_load_lds_dwordx4 v2, vcc
	s_add_i32 m0, s34, 0x2000
	s_add_u32 s30, s30, 0x40080
	s_addc_u32 s31, s31, 0
	s_add_i32 s34, s79, s41
	global_load_lds_dwordx4 v0, vcc
	s_mov_b32 m0, s34
	s_nop 0
	global_load_lds_dwordx4 v2, s[30:31]
	s_add_i32 m0, s34, 0x2000
	s_nop 0
	global_load_lds_dwordx4 v0, s[30:31]
	v_lshl_add_u64 v[158:159], v[206:207], 0, s[2:3]
	s_mov_b32 m0, s48
	s_nop 0
	global_load_lds_dwordx4 v[158:159], off
	v_lshl_add_u64 v[158:159], v[246:247], 0, s[2:3]
	s_mov_b32 m0, s49
	s_nop 0
	global_load_lds_dwordx4 v[158:159], off
	s_waitcnt vmcnt(8)
	s_waitcnt lgkmcnt(0)
	s_barrier
	s_waitcnt lgkmcnt(0)
	v_mfma_f32_16x16x32_bf16 v[66:69], v[142:145], v[190:193], v[66:69]
	v_mfma_f32_16x16x32_bf16 v[62:65], v[166:169], v[190:193], v[62:65]
	v_mfma_f32_16x16x32_bf16 v[50:53], v[142:145], v[198:201], v[50:53]
	v_mfma_f32_16x16x32_bf16 v[46:49], v[166:169], v[198:201], v[46:49]
	v_mfma_f32_16x16x32_bf16 v[34:37], v[142:145], v[230:233], v[34:37]
	v_mfma_f32_16x16x32_bf16 v[30:33], v[166:169], v[230:233], v[30:33]
	v_mfma_f32_16x16x32_bf16 v[18:21], v[142:145], v[238:241], v[18:21]
	v_mfma_f32_16x16x32_bf16 v[14:17], v[166:169], v[238:241], v[14:17]
	v_mfma_f32_16x16x32_bf16 v[66:69], v[162:165], v[194:197], v[66:69]
	v_mfma_f32_16x16x32_bf16 v[62:65], v[170:173], v[194:197], v[62:65]
	v_mfma_f32_16x16x32_bf16 v[50:53], v[162:165], v[202:205], v[50:53]
	v_mfma_f32_16x16x32_bf16 v[46:49], v[170:173], v[202:205], v[46:49]
	v_mfma_f32_16x16x32_bf16 v[34:37], v[162:165], v[234:237], v[34:37]
	v_mfma_f32_16x16x32_bf16 v[30:33], v[170:173], v[234:237], v[30:33]
	v_mfma_f32_16x16x32_bf16 v[18:21], v[162:165], v[242:245], v[18:21]
	v_mfma_f32_16x16x32_bf16 v[14:17], v[170:173], v[242:245], v[14:17]
	v_mfma_f32_16x16x32_bf16 v[58:61], v[174:177], v[190:193], v[58:61]
	v_mfma_f32_16x16x32_bf16 v[54:57], v[182:185], v[190:193], v[54:57]
	v_mfma_f32_16x16x32_bf16 v[42:45], v[174:177], v[198:201], v[42:45]
	v_mfma_f32_16x16x32_bf16 v[38:41], v[182:185], v[198:201], v[38:41]
	v_mfma_f32_16x16x32_bf16 v[26:29], v[174:177], v[230:233], v[26:29]
	v_mfma_f32_16x16x32_bf16 v[22:25], v[182:185], v[230:233], v[22:25]
	v_mfma_f32_16x16x32_bf16 v[10:13], v[174:177], v[238:241], v[10:13]
	v_mfma_f32_16x16x32_bf16 v[6:9], v[182:185], v[238:241], v[6:9]
	v_mfma_f32_16x16x32_bf16 v[58:61], v[178:181], v[194:197], v[58:61]
	v_mfma_f32_16x16x32_bf16 v[54:57], v[186:189], v[194:197], v[54:57]
	v_mfma_f32_16x16x32_bf16 v[42:45], v[178:181], v[202:205], v[42:45]
	v_mfma_f32_16x16x32_bf16 v[38:41], v[186:189], v[202:205], v[38:41]
	v_mfma_f32_16x16x32_bf16 v[26:29], v[178:181], v[234:237], v[26:29]
	v_mfma_f32_16x16x32_bf16 v[22:25], v[186:189], v[234:237], v[22:25]
	v_mfma_f32_16x16x32_bf16 v[10:13], v[178:181], v[242:245], v[10:13]
	v_mfma_f32_16x16x32_bf16 v[6:9], v[186:189], v[242:245], v[6:9]
	s_barrier
	s_add_i32 s71, s71, 2
	s_add_u32 s69, s69, 0x100
	s_addc_u32 s70, s70, 0
	s_add_u32 s26, s26, 0x100
	s_addc_u32 s27, s27, 0
	s_cmp_gt_u32 s71, 13
	s_cbranch_scc0 .LBB0_818
	s_and_b64 vcc, exec, s[16:17]
	s_cbranch_vccz .LBB0_821
	s_barrier

; #define PG8_STAGE(bufoff, gbase, voff) do { _Pragma("unroll") for (int _i = 0; _i < 2; ++_i) \
;         __builtin_amdgcn_global_load_lds((const unsigned*)((const char*)(gbase) + (voff)[_i]), (PG8_LAS unsigned*)(lds + (bufoff) + ldsw + _i * 8192), 16, 0, 0); } while (0)
; #define PG8_LDA(dst, b, h) do { _Pragma("unroll") for (int m = 0; m < 4; ++m) _Pragma("unroll") for (int k = 0; k < 2; ++k) dst[m][k] = *(const PG8_LAS bf16x8*)(lds + PG8_SA(b, h) + aoff + m * 2048 + k * 1024); } while (0)
; #define PG8_LDB(dst, b, h) do { _Pragma("unroll") for (int n = 0; n < 2; ++n) _Pragma("unroll") for (int k = 0; k < 2; ++k) dst[n][k] = *(const PG8_LAS bf16x8*)(lds + PG8_SB(b, h) + boff + n * 2048 + k * 1024); } while (0)
; template <class Epi, class Sched, bool ALIGN_EPI = false, bool SP2 = false>
; __device__ __forceinline__ void gemm_phase(PG8_LAS unsigned char* lds, const Gemm g, const Sched& S, const Epi& E) {
;     ...
;         for (int t = 0; t < nt; t += 2) {
;             const bool last = (t == nt - 2);
;             const char* a1 = cA + (size_t)(t + 1) * kstep;
;             const char* a2 = last ? nA : cA + (size_t)(t + 2) * kstep; const char* b2 = last ? nB : cB + (size_t)(t + 2) * kstep;
;             const char* a3 = a2 + kstep; const char* b3 = b2 + kstep;
;             if (last && has_next) S.a_ready(nxt);
;             if constexpr (SP2) {
;             PG8_LDB(B0, 0, 0); PG8_LDB(B1, 0, 1); PG8_SCHED; PG8_LDA(At, 0, 0); PG8_STAGE(PG8_SA(1, 1), a1 + hstep, voffA);
;             PG8_WAIT_V(8); PG8_WAIT_L(0); PG8_BAR; PG8_MMA(0, 0, At, B0); PG8_MMA(0, 1, At, B1); PG8_BAR; PG8_SCHED;
;             PG8_LDA(At, 0, 1); PG8_STAGE(PG8_SB(0, 0), b2, voffB); PG8_STAGE(PG8_SB(0, 1), b2 + hstep, voffB); PG8_STAGE(PG8_SA(0, 0), a2, voffA);
;             PG8_WAIT_V(8); PG8_WAIT_L(0); PG8_BAR; PG8_MMA(1, 0, At, B0); PG8_MMA(1, 1, At, B1); PG8_BAR; PG8_SCHED;
;             PG8_LDB(B0, 1, 0); PG8_LDB(B1, 1, 1); PG8_SCHED; PG8_LDA(At, 1, 0); PG8_STAGE(PG8_SA(0, 1), a2 + hstep, voffA);
;             PG8_WAIT_V(8); PG8_WAIT_L(0); PG8_BAR; PG8_MMA(0, 0, At, B0); PG8_MMA(0, 1, At, B1); PG8_BAR; PG8_SCHED;
;             PG8_LDA(At, 1, 1); PG8_STAGE(PG8_SB(1, 0), b3, voffB); PG8_STAGE(PG8_SB(1, 1), b3 + hstep, voffB); PG8_STAGE(PG8_SA(1, 0), a3, voffA);
;             PG8_WAIT_V(8); PG8_WAIT_L(0); PG8_BAR; PG8_MMA(1, 0, At, B0); PG8_MMA(1, 1, At, B1); PG8_BAR; PG8_SCHED;
.LBB0_905:
	s_add_u32 s30, s26, 0x100
	s_addc_u32 s31, s27, 0
	s_add_i32 s83, 0, 0x10000
	s_cmp_eq_u32 s82, 28
	s_cselect_b32 s41, s21, s31
	s_cselect_b32 s40, s78, s30
	s_cselect_b32 s35, s19, s81
	s_cselect_b32 s34, s79, s80
	s_add_i32 s84, 0, 0x14000
	v_add_u32_e32 v98, s83, v152
	v_add_u32_e32 v158, s84, v152
	ds_read_b128 v[78:81], v98
	ds_read_b128 v[86:89], v98 offset:1024
	ds_read_b128 v[94:97], v98 offset:2048
	ds_read_b128 v[98:101], v98 offset:3072
	ds_read_b128 v[166:169], v158
	ds_read_b128 v[174:177], v158 offset:1024
	ds_read_b128 v[178:181], v158 offset:2048
	ds_read_b128 v[182:185], v158 offset:3072
	s_add_i32 m0, s49, 0xc000
	ds_read_b128 v[186:189], v173
	ds_read_b128 v[190:193], v173 offset:1024
	ds_read_b128 v[194:197], v173 offset:2048
	ds_read_b128 v[198:201], v173 offset:3072
	ds_read_b128 v[202:205], v173 offset:4096
	ds_read_b128 v[230:233], v173 offset:5120
	ds_read_b128 v[234:237], v173 offset:6144
	ds_read_b128 v[238:241], v173 offset:7168
	global_load_lds_dwordx4 v164, s[26:27]
	s_add_i32 m0, s49, 0xe000
	s_nop 0
	global_load_lds_dwordx4 v162, s[26:27]
	s_waitcnt vmcnt(8)
	s_waitcnt lgkmcnt(0)
	s_barrier
	s_waitcnt lgkmcnt(0)
	v_mfma_f32_16x16x32_bf16 v[146:149], v[78:81], v[186:189], v[146:149]
	v_mfma_f32_16x16x32_bf16 v[142:145], v[94:97], v[186:189], v[142:145]
	v_mfma_f32_16x16x32_bf16 v[130:133], v[78:81], v[194:197], v[130:133]
	v_mfma_f32_16x16x32_bf16 v[126:129], v[94:97], v[194:197], v[126:129]
	v_mfma_f32_16x16x32_bf16 v[114:117], v[78:81], v[202:205], v[114:117]
	v_mfma_f32_16x16x32_bf16 v[110:113], v[94:97], v[202:205], v[110:113]
	v_mfma_f32_16x16x32_bf16 v[90:93], v[78:81], v[234:237], v[90:93]
	v_mfma_f32_16x16x32_bf16 v[82:85], v[94:97], v[234:237], v[82:85]
	v_mfma_f32_16x16x32_bf16 v[146:149], v[86:89], v[190:193], v[146:149]
	v_mfma_f32_16x16x32_bf16 v[142:145], v[98:101], v[190:193], v[142:145]
	v_mfma_f32_16x16x32_bf16 v[130:133], v[86:89], v[198:201], v[130:133]
	v_mfma_f32_16x16x32_bf16 v[126:129], v[98:101], v[198:201], v[126:129]
	v_mfma_f32_16x16x32_bf16 v[114:117], v[86:89], v[230:233], v[114:117]
	v_mfma_f32_16x16x32_bf16 v[110:113], v[98:101], v[230:233], v[110:113]
	v_mfma_f32_16x16x32_bf16 v[90:93], v[86:89], v[238:241], v[90:93]
	v_mfma_f32_16x16x32_bf16 v[82:85], v[98:101], v[238:241], v[82:85]
	v_mfma_f32_16x16x32_bf16 v[138:141], v[166:169], v[186:189], v[138:141]
	v_mfma_f32_16x16x32_bf16 v[134:137], v[178:181], v[186:189], v[134:137]
	v_mfma_f32_16x16x32_bf16 v[122:125], v[166:169], v[194:197], v[122:125]
	v_mfma_f32_16x16x32_bf16 v[118:121], v[178:181], v[194:197], v[118:121]
	v_mfma_f32_16x16x32_bf16 v[106:109], v[166:169], v[202:205], v[106:109]
	v_mfma_f32_16x16x32_bf16 v[102:105], v[178:181], v[202:205], v[102:105]
	v_mfma_f32_16x16x32_bf16 v[74:77], v[166:169], v[234:237], v[74:77]
	v_mfma_f32_16x16x32_bf16 v[70:73], v[178:181], v[234:237], v[70:73]
	v_mfma_f32_16x16x32_bf16 v[138:141], v[174:177], v[190:193], v[138:141]
	v_mfma_f32_16x16x32_bf16 v[134:137], v[182:185], v[190:193], v[134:137]
	v_mfma_f32_16x16x32_bf16 v[122:125], v[174:177], v[198:201], v[122:125]
	v_mfma_f32_16x16x32_bf16 v[118:121], v[182:185], v[198:201], v[118:121]
	v_mfma_f32_16x16x32_bf16 v[106:109], v[174:177], v[230:233], v[106:109]
	v_mfma_f32_16x16x32_bf16 v[102:105], v[182:185], v[230:233], v[102:105]
	v_mfma_f32_16x16x32_bf16 v[74:77], v[174:177], v[238:241], v[74:77]
	v_mfma_f32_16x16x32_bf16 v[70:73], v[182:185], v[238:241], v[70:73]
	s_barrier
	s_add_i32 s26, s83, s48
	s_mov_b32 m0, s26
	ds_read_b128 v[186:189], v173 offset:16384
	ds_read_b128 v[190:193], v173 offset:17408
	ds_read_b128 v[194:197], v173 offset:18432
	ds_read_b128 v[198:201], v173 offset:19456
	ds_read_b128 v[202:205], v173 offset:20480
	ds_read_b128 v[230:233], v173 offset:21504
	ds_read_b128 v[234:237], v173 offset:22528
	ds_read_b128 v[238:241], v173 offset:23552
	global_load_lds_dwordx4 v2, s[34:35]
	s_add_i32 m0, s26, 0x2000
	s_add_u32 s26, s34, 0x80000
	s_addc_u32 s27, s35, 0
	s_add_i32 s83, s84, s48
	global_load_lds_dwordx4 v0, s[34:35]
	s_mov_b32 m0, s83
	s_nop 0
	global_load_lds_dwordx4 v2, s[26:27]
	s_add_i32 m0, s83, 0x2000
	s_nop 0
	global_load_lds_dwordx4 v0, s[26:27]
	s_mov_b32 m0, s49
	s_nop 0
	global_load_lds_dwordx4 v2, s[40:41]
	s_mov_b32 m0, s51
	s_nop 0
	global_load_lds_dwordx4 v0, s[40:41]
	s_waitcnt vmcnt(8)
	s_waitcnt lgkmcnt(0)
	s_barrier
	s_waitcnt lgkmcnt(0)
	v_mfma_f32_16x16x32_bf16 v[66:69], v[78:81], v[186:189], v[66:69]
	v_mfma_f32_16x16x32_bf16 v[62:65], v[94:97], v[186:189], v[62:65]
	v_mfma_f32_16x16x32_bf16 v[50:53], v[78:81], v[194:197], v[50:53]
	v_mfma_f32_16x16x32_bf16 v[46:49], v[94:97], v[194:197], v[46:49]
	v_mfma_f32_16x16x32_bf16 v[34:37], v[78:81], v[202:205], v[34:37]
	v_mfma_f32_16x16x32_bf16 v[30:33], v[94:97], v[202:205], v[30:33]
	v_mfma_f32_16x16x32_bf16 v[18:21], v[78:81], v[234:237], v[18:21]
	v_mfma_f32_16x16x32_bf16 v[14:17], v[94:97], v[234:237], v[14:17]
	v_mfma_f32_16x16x32_bf16 v[66:69], v[86:89], v[190:193], v[66:69]
	v_mfma_f32_16x16x32_bf16 v[62:65], v[98:101], v[190:193], v[62:65]
	v_mfma_f32_16x16x32_bf16 v[50:53], v[86:89], v[198:201], v[50:53]
	v_mfma_f32_16x16x32_bf16 v[46:49], v[98:101], v[198:201], v[46:49]
	v_mfma_f32_16x16x32_bf16 v[34:37], v[86:89], v[230:233], v[34:37]
	v_mfma_f32_16x16x32_bf16 v[30:33], v[98:101], v[230:233], v[30:33]
	v_mfma_f32_16x16x32_bf16 v[18:21], v[86:89], v[238:241], v[18:21]
	v_mfma_f32_16x16x32_bf16 v[14:17], v[98:101], v[238:241], v[14:17]
	v_mfma_f32_16x16x32_bf16 v[58:61], v[166:169], v[186:189], v[58:61]
	v_mfma_f32_16x16x32_bf16 v[54:57], v[178:181], v[186:189], v[54:57]
	v_mfma_f32_16x16x32_bf16 v[42:45], v[166:169], v[194:197], v[42:45]
	v_mfma_f32_16x16x32_bf16 v[38:41], v[178:181], v[194:197], v[38:41]
	v_mfma_f32_16x16x32_bf16 v[26:29], v[166:169], v[202:205], v[26:29]
	v_mfma_f32_16x16x32_bf16 v[22:25], v[178:181], v[202:205], v[22:25]
	v_mfma_f32_16x16x32_bf16 v[10:13], v[166:169], v[234:237], v[10:13]
	v_mfma_f32_16x16x32_bf16 v[6:9], v[178:181], v[234:237], v[6:9]
	v_mfma_f32_16x16x32_bf16 v[58:61], v[174:177], v[190:193], v[58:61]
	v_mfma_f32_16x16x32_bf16 v[54:57], v[182:185], v[190:193], v[54:57]
	v_mfma_f32_16x16x32_bf16 v[42:45], v[174:177], v[198:201], v[42:45]
	v_mfma_f32_16x16x32_bf16 v[38:41], v[182:185], v[198:201], v[38:41]
	v_mfma_f32_16x16x32_bf16 v[26:29], v[174:177], v[230:233], v[26:29]
	v_mfma_f32_16x16x32_bf16 v[22:25], v[182:185], v[230:233], v[22:25]
	v_mfma_f32_16x16x32_bf16 v[10:13], v[174:177], v[238:241], v[10:13]
	v_mfma_f32_16x16x32_bf16 v[6:9], v[182:185], v[238:241], v[6:9]
	s_barrier
; #define PG8_STAGE(bufoff, gbase, voff) do { _Pragma("unroll") for (int _i = 0; _i < 2; ++_i) \
;         __builtin_amdgcn_global_load_lds((const unsigned*)((const char*)(gbase) + (voff)[_i]), (PG8_LAS unsigned*)(lds + (bufoff) + ldsw + _i * 8192), 16, 0, 0); } while (0)
; #define PG8_LDA(dst, b, h) do { _Pragma("unroll") for (int m = 0; m < 4; ++m) _Pragma("unroll") for (int k = 0; k < 2; ++k) dst[m][k] = *(const PG8_LAS bf16x8*)(lds + PG8_SA(b, h) + aoff + m * 2048 + k * 1024); } while (0)
; #define PG8_LDB(dst, b, h) do { _Pragma("unroll") for (int n = 0; n < 2; ++n) _Pragma("unroll") for (int k = 0; k < 2; ++k) dst[n][k] = *(const PG8_LAS bf16x8*)(lds + PG8_SB(b, h) + boff + n * 2048 + k * 1024); } while (0)
; template <class Epi, class Sched, bool ALIGN_EPI = false, bool SP2 = false>
; __device__ __forceinline__ void gemm_phase(PG8_LAS unsigned char* lds, const Gemm g, const Sched& S, const Epi& E) {
;     ...
;         for (int t = 0; t < nt; t += 2) {
;             const bool last = (t == nt - 2);
;             const char* a1 = cA + (size_t)(t + 1) * kstep;
;             const char* a2 = last ? nA : cA + (size_t)(t + 2) * kstep; const char* b2 = last ? nB : cB + (size_t)(t + 2) * kstep;
;             const char* a3 = a2 + kstep; const char* b3 = b2 + kstep;
;             if (last && has_next) S.a_ready(nxt);
;             if constexpr (SP2) {
;             PG8_LDB(B0, 0, 0); PG8_LDB(B1, 0, 1); PG8_SCHED; PG8_LDA(At, 0, 0); PG8_STAGE(PG8_SA(1, 1), a1 + hstep, voffA);
;             PG8_WAIT_V(8); PG8_WAIT_L(0); PG8_BAR; PG8_MMA(0, 0, At, B0); PG8_MMA(0, 1, At, B1); PG8_BAR; PG8_SCHED;
;             PG8_LDA(At, 0, 1); PG8_STAGE(PG8_SB(0, 0), b2, voffB); PG8_STAGE(PG8_SB(0, 1), b2 + hstep, voffB); PG8_STAGE(PG8_SA(0, 0), a2, voffA);
;             PG8_WAIT_V(8); PG8_WAIT_L(0); PG8_BAR; PG8_MMA(1, 0, At, B0); PG8_MMA(1, 1, At, B1); PG8_BAR; PG8_SCHED;
;             PG8_LDB(B0, 1, 0); PG8_LDB(B1, 1, 1); PG8_SCHED; PG8_LDA(At, 1, 0); PG8_STAGE(PG8_SA(0, 1), a2 + hstep, voffA);
;             PG8_WAIT_V(8); PG8_WAIT_L(0); PG8_BAR; PG8_MMA(0, 0, At, B0); PG8_MMA(0, 1, At, B1); PG8_BAR; PG8_SCHED;
;             PG8_LDA(At, 1, 1); PG8_STAGE(PG8_SB(1, 0), b3, voffB); PG8_STAGE(PG8_SB(1, 1), b3 + hstep, voffB); PG8_STAGE(PG8_SA(1, 0), a3, voffA);
;             PG8_WAIT_V(8); PG8_WAIT_L(0); PG8_BAR; PG8_MMA(1, 0, At, B0); PG8_MMA(1, 1, At, B1); PG8_BAR; PG8_SCHED;
	s_add_i32 s83, 0, 0x18000
	s_add_i32 s84, 0, 0x1c000
	v_add_u32_e32 v98, s83, v152
	v_add_u32_e32 v182, s84, v152
	ds_read_b128 v[78:81], v98
	ds_read_b128 v[86:89], v98 offset:1024
	ds_read_b128 v[94:97], v98 offset:2048
	ds_read_b128 v[98:101], v98 offset:3072
	ds_read_b128 v[166:169], v182
	ds_read_b128 v[174:177], v182 offset:1024
	ds_read_b128 v[178:181], v182 offset:2048
	ds_read_b128 v[182:185], v182 offset:3072
	s_add_u32 s26, s40, 0x80000
	s_addc_u32 s27, s41, 0
	s_mov_b32 m0, s52
	ds_read_b128 v[186:189], v173 offset:32768
	ds_read_b128 v[190:193], v173 offset:33792
	ds_read_b128 v[194:197], v173 offset:34816
	ds_read_b128 v[198:201], v173 offset:35840
	ds_read_b128 v[202:205], v173 offset:36864
	ds_read_b128 v[230:233], v173 offset:37888
	ds_read_b128 v[234:237], v173 offset:38912
	ds_read_b128 v[238:241], v173 offset:39936
	global_load_lds_dwordx4 v2, s[26:27]
	s_mov_b32 m0, s53
	s_nop 0
	global_load_lds_dwordx4 v0, s[26:27]
	s_waitcnt vmcnt(8)
	s_waitcnt lgkmcnt(0)
	s_barrier
	s_waitcnt lgkmcnt(0)
	v_mfma_f32_16x16x32_bf16 v[146:149], v[78:81], v[186:189], v[146:149]
	v_mfma_f32_16x16x32_bf16 v[142:145], v[94:97], v[186:189], v[142:145]
	v_mfma_f32_16x16x32_bf16 v[130:133], v[78:81], v[194:197], v[130:133]
	v_mfma_f32_16x16x32_bf16 v[126:129], v[94:97], v[194:197], v[126:129]
	v_mfma_f32_16x16x32_bf16 v[114:117], v[78:81], v[202:205], v[114:117]
	v_mfma_f32_16x16x32_bf16 v[110:113], v[94:97], v[202:205], v[110:113]
	v_mfma_f32_16x16x32_bf16 v[90:93], v[78:81], v[234:237], v[90:93]
	v_mfma_f32_16x16x32_bf16 v[82:85], v[94:97], v[234:237], v[82:85]
	v_mfma_f32_16x16x32_bf16 v[146:149], v[86:89], v[190:193], v[146:149]
	v_mfma_f32_16x16x32_bf16 v[142:145], v[98:101], v[190:193], v[142:145]
	v_mfma_f32_16x16x32_bf16 v[130:133], v[86:89], v[198:201], v[130:133]
	v_mfma_f32_16x16x32_bf16 v[126:129], v[98:101], v[198:201], v[126:129]
	v_mfma_f32_16x16x32_bf16 v[114:117], v[86:89], v[230:233], v[114:117]
	v_mfma_f32_16x16x32_bf16 v[110:113], v[98:101], v[230:233], v[110:113]
	v_mfma_f32_16x16x32_bf16 v[90:93], v[86:89], v[238:241], v[90:93]
	v_mfma_f32_16x16x32_bf16 v[82:85], v[98:101], v[238:241], v[82:85]
	v_mfma_f32_16x16x32_bf16 v[138:141], v[166:169], v[186:189], v[138:141]
	v_mfma_f32_16x16x32_bf16 v[134:137], v[178:181], v[186:189], v[134:137]
	v_mfma_f32_16x16x32_bf16 v[122:125], v[166:169], v[194:197], v[122:125]
	v_mfma_f32_16x16x32_bf16 v[118:121], v[178:181], v[194:197], v[118:121]
	v_mfma_f32_16x16x32_bf16 v[106:109], v[166:169], v[202:205], v[106:109]
	v_mfma_f32_16x16x32_bf16 v[102:105], v[178:181], v[202:205], v[102:105]
	v_mfma_f32_16x16x32_bf16 v[74:77], v[166:169], v[234:237], v[74:77]
	v_mfma_f32_16x16x32_bf16 v[70:73], v[178:181], v[234:237], v[70:73]
	v_mfma_f32_16x16x32_bf16 v[138:141], v[174:177], v[190:193], v[138:141]
	v_mfma_f32_16x16x32_bf16 v[134:137], v[182:185], v[190:193], v[134:137]
	v_mfma_f32_16x16x32_bf16 v[122:125], v[174:177], v[198:201], v[122:125]
	v_mfma_f32_16x16x32_bf16 v[118:121], v[182:185], v[198:201], v[118:121]
	v_mfma_f32_16x16x32_bf16 v[106:109], v[174:177], v[230:233], v[106:109]
	v_mfma_f32_16x16x32_bf16 v[102:105], v[182:185], v[230:233], v[102:105]
	v_mfma_f32_16x16x32_bf16 v[74:77], v[174:177], v[238:241], v[74:77]
	v_mfma_f32_16x16x32_bf16 v[70:73], v[182:185], v[238:241], v[70:73]
	s_barrier
	s_add_u32 vcc_lo, s34, s2
	s_addc_u32 vcc_hi, s35, s3
	s_add_i32 s26, s83, s48
	s_mov_b32 m0, s26
	ds_read_b128 v[186:189], v173 offset:49152
	ds_read_b128 v[190:193], v173 offset:50176
	ds_read_b128 v[194:197], v173 offset:51200
	ds_read_b128 v[198:201], v173 offset:52224
	ds_read_b128 v[202:205], v173 offset:53248
	ds_read_b128 v[230:233], v173 offset:54272
	ds_read_b128 v[234:237], v173 offset:55296
	ds_read_b128 v[238:241], v173 offset:56320
	global_load_lds_dwordx4 v2, vcc
	s_add_i32 m0, s26, 0x2000
	s_add_u32 s26, s34, 0x80080
	s_addc_u32 s27, s35, 0
	s_add_i32 s34, s84, s48
	global_load_lds_dwordx4 v0, vcc
	s_mov_b32 m0, s34
	s_nop 0
	global_load_lds_dwordx4 v2, s[26:27]
	s_add_i32 m0, s34, 0x2000
	s_nop 0
	global_load_lds_dwordx4 v0, s[26:27]
	s_add_u32 vcc_lo, s40, s2
	s_addc_u32 vcc_hi, s41, s3
	s_mov_b32 m0, s66
	s_nop 0
	global_load_lds_dwordx4 v2, vcc
	s_mov_b32 m0, s67
	s_nop 0
	global_load_lds_dwordx4 v0, vcc
	s_waitcnt vmcnt(8)
	s_waitcnt lgkmcnt(0)
	s_barrier
	s_waitcnt lgkmcnt(0)
	v_mfma_f32_16x16x32_bf16 v[66:69], v[78:81], v[186:189], v[66:69]
	v_mfma_f32_16x16x32_bf16 v[62:65], v[94:97], v[186:189], v[62:65]
	v_mfma_f32_16x16x32_bf16 v[50:53], v[78:81], v[194:197], v[50:53]
	v_mfma_f32_16x16x32_bf16 v[46:49], v[94:97], v[194:197], v[46:49]
	v_mfma_f32_16x16x32_bf16 v[34:37], v[78:81], v[202:205], v[34:37]
	v_mfma_f32_16x16x32_bf16 v[30:33], v[94:97], v[202:205], v[30:33]
	v_mfma_f32_16x16x32_bf16 v[18:21], v[78:81], v[234:237], v[18:21]
	v_mfma_f32_16x16x32_bf16 v[14:17], v[94:97], v[234:237], v[14:17]
	v_mfma_f32_16x16x32_bf16 v[66:69], v[86:89], v[190:193], v[66:69]
	v_mfma_f32_16x16x32_bf16 v[62:65], v[98:101], v[190:193], v[62:65]
	v_mfma_f32_16x16x32_bf16 v[50:53], v[86:89], v[198:201], v[50:53]
	v_mfma_f32_16x16x32_bf16 v[46:49], v[98:101], v[198:201], v[46:49]
	v_mfma_f32_16x16x32_bf16 v[34:37], v[86:89], v[230:233], v[34:37]
	v_mfma_f32_16x16x32_bf16 v[30:33], v[98:101], v[230:233], v[30:33]
	v_mfma_f32_16x16x32_bf16 v[18:21], v[86:89], v[238:241], v[18:21]
	v_mfma_f32_16x16x32_bf16 v[14:17], v[98:101], v[238:241], v[14:17]
	v_mfma_f32_16x16x32_bf16 v[58:61], v[166:169], v[186:189], v[58:61]
	v_mfma_f32_16x16x32_bf16 v[54:57], v[178:181], v[186:189], v[54:57]
	v_mfma_f32_16x16x32_bf16 v[42:45], v[166:169], v[194:197], v[42:45]
	v_mfma_f32_16x16x32_bf16 v[38:41], v[178:181], v[194:197], v[38:41]
	v_mfma_f32_16x16x32_bf16 v[26:29], v[166:169], v[202:205], v[26:29]
	v_mfma_f32_16x16x32_bf16 v[22:25], v[178:181], v[202:205], v[22:25]
	v_mfma_f32_16x16x32_bf16 v[10:13], v[166:169], v[234:237], v[10:13]
	v_mfma_f32_16x16x32_bf16 v[6:9], v[178:181], v[234:237], v[6:9]
	v_mfma_f32_16x16x32_bf16 v[58:61], v[174:177], v[190:193], v[58:61]
	v_mfma_f32_16x16x32_bf16 v[54:57], v[182:185], v[190:193], v[54:57]
	v_mfma_f32_16x16x32_bf16 v[42:45], v[174:177], v[198:201], v[42:45]
	v_mfma_f32_16x16x32_bf16 v[38:41], v[182:185], v[198:201], v[38:41]
	v_mfma_f32_16x16x32_bf16 v[26:29], v[174:177], v[230:233], v[26:29]
	v_mfma_f32_16x16x32_bf16 v[22:25], v[182:185], v[230:233], v[22:25]
	v_mfma_f32_16x16x32_bf16 v[10:13], v[174:177], v[238:241], v[10:13]
	v_mfma_f32_16x16x32_bf16 v[6:9], v[182:185], v[238:241], v[6:9]
	s_barrier
;     __device__ __forceinline__ void operator()(const f32x4 (&acc)[2][2][4][2], const Unit& u, int wr, int wc, int fr, int fq) const {
;         const int row0 = u.pm * BM + wr * 64 + fr; const int col0 = u.pn * BM + wc * 32 + 4 * fq;
;         f32x4 gv[2][2];
; #pragma unroll
;         for (int bj = 0; bj < 2; ++bj)
; #pragma unroll
;             for (int n = 0; n < 2; ++n) gv[bj][n] = xg ? *(const f32x4*)(gn + col0 + bj * HALF + n * 16) : (f32x4){0.f, 0.f, 0.f, 0.f};
; #pragma unroll
;         for (int ai = 0; ai < 2; ++ai)
; #pragma unroll
;             for (int m = 0; m < 4; ++m) { const size_t off = (size_t)(row0 + ai * HALF + m * 16) * ldc + col0; float ss = 0.f;
; #pragma unroll
;                 for (int bj = 0; bj < 2; ++bj)
; #pragma unroll
;                     for (int n = 0; n < 2; ++n) { const f32x4 bs = *(const f32x4*)(base + off + bj * HALF + n * 16); const f32x4 o = bs + acc[ai][bj][m][n] * scale;
;                         *(f32x4*)(out + off + bj * HALF + n * 16) = o;
;                         if (xg) { ss += (o[0] * o[0] + o[1] * o[1]) + (o[2] * o[2] + o[3] * o[3]); const f32x4 og = o * gv[bj][n];
;                             typedef unsigned u32x2v __attribute__((ext_vector_type(2))); u32x2v w; w.x = cvt_pk_bf16(og[0], og[1]); w.y = cvt_pk_bf16(og[2], og[3]); *(u32x2v*)(xg + off + bj * HALF + n * 16) = w; } }
;                 if (xg) { ss += __shfl_xor(ss, 16); ss += __shfl_xor(ss, 32); if (fq == 0) atomicAdd(rowss + row0 + ai * HALF + m * 16, (rowss_t)(ss * 16777216.0f)); } }
	s_add_i32 s82, s82, 2
	s_add_u32 s80, s80, 0x100
	s_addc_u32 s81, s81, 0
	s_cmp_gt_u32 s82, 29
	s_mov_b64 s[26:27], s[30:31]
	s_cbranch_scc0 .LBB0_905
	v_lshl_add_u32 v170, s70, 8, v5
	v_lshl_or_b32 v168, s71, 8, v172
	v_ashrrev_i32_e32 v171, 31, v170
	v_ashrrev_i32_e32 v169, 31, v168
	v_readlane_b32 s6, v252, 59
	v_lshlrev_b64 v[158:159], 11, v[170:171]
	v_readlane_b32 s7, v252, 60
	v_lshl_add_u64 v[166:167], v[158:159], 0, v[168:169]
	v_lshl_add_u64 v[158:159], v[166:167], 2, s[12:13]
	v_lshl_add_u64 v[78:79], v[168:169], 2, s[6:7]
	global_load_dwordx4 v[98:101], v[78:79], off
	global_load_dwordx4 v[94:97], v[78:79], off offset:64
	global_load_dwordx4 v[86:89], v[78:79], off offset:512
	s_nop 0
	global_load_dwordx4 v[78:81], v[78:79], off offset:576
	s_nop 0
	global_load_dwordx4 v[174:177], v[158:159], off
	global_load_dwordx4 v[182:185], v[158:159], off offset:64
	global_load_dwordx4 v[186:189], v[158:159], off offset:512
	global_load_dwordx4 v[190:193], v[158:159], off offset:576
	s_waitcnt vmcnt(3) lgkmcnt(0)
	v_pk_add_f32 v[148:149], v[148:149], v[176:177]
	v_pk_add_f32 v[146:147], v[146:147], v[174:175]
	v_mul_f32_e32 v161, v149, v149
	v_mul_f32_e32 v160, v147, v147
	global_store_dwordx4 v[158:159], v[146:149], off
	v_fmac_f32_e32 v160, v146, v146
	v_fmac_f32_e32 v161, v148, v148
	v_pk_mul_f32 v[148:149], v[100:101], v[148:149]
	v_pk_mul_f32 v[146:147], v[98:99], v[146:147]
	v_add_f32_e32 v174, v160, v161
	v_cvt_pk_bf16_f32 v146, v146, v147
	v_cvt_pk_bf16_f32 v147, v148, v149
	v_lshl_add_u64 v[160:161], v[166:167], 1, s[14:15]
	global_store_dwordx2 v[160:161], v[146:147], off
	s_waitcnt vmcnt(4) lgkmcnt(0)
	v_pk_add_f32 v[144:145], v[144:145], v[184:185]
	v_pk_add_f32 v[142:143], v[142:143], v[182:183]
	v_mul_f32_e32 v147, v145, v145
	v_mul_f32_e32 v146, v143, v143
	global_store_dwordx4 v[158:159], v[142:145], off offset:64
	v_fmac_f32_e32 v146, v142, v142
	v_fmac_f32_e32 v147, v144, v144
	v_pk_mul_f32 v[144:145], v[96:97], v[144:145]
	v_pk_mul_f32 v[142:143], v[94:95], v[142:143]
	v_add_f32_e32 v146, v146, v147
	v_cvt_pk_bf16_f32 v142, v142, v143
	v_cvt_pk_bf16_f32 v143, v144, v145
	global_store_dwordx2 v[160:161], v[142:143], off offset:32
	v_add_f32_e32 v146, v174, v146
	s_waitcnt vmcnt(5) lgkmcnt(0)
	v_pk_add_f32 v[140:141], v[140:141], v[188:189]
	v_pk_add_f32 v[138:139], v[138:139], v[186:187]
	v_mul_f32_e32 v143, v141, v141
	v_mul_f32_e32 v142, v139, v139
	global_store_dwordx4 v[158:159], v[138:141], off offset:512
	v_fmac_f32_e32 v142, v138, v138
	v_fmac_f32_e32 v143, v140, v140
	v_pk_mul_f32 v[140:141], v[88:89], v[140:141]
	v_pk_mul_f32 v[138:139], v[86:87], v[138:139]
	v_add_f32_e32 v142, v142, v143
	v_cvt_pk_bf16_f32 v138, v138, v139
	v_cvt_pk_bf16_f32 v139, v140, v141
	global_store_dwordx2 v[160:161], v[138:139], off offset:256
	v_add_f32_e32 v142, v146, v142
	s_waitcnt vmcnt(6) lgkmcnt(0)
	v_pk_add_f32 v[136:137], v[136:137], v[192:193]
	v_pk_add_f32 v[134:135], v[134:135], v[190:191]
	global_store_dwordx4 v[158:159], v[134:137], off offset:576
	v_pk_mul_f32 v[140:141], v[78:79], v[134:135]
	v_pk_mul_f32 v[138:139], v[80:81], v[136:137]
	v_mul_f32_e32 v135, v135, v135
	v_fmac_f32_e32 v135, v134, v134
	v_mul_f32_e32 v134, v137, v137
	v_fmac_f32_e32 v134, v136, v136
	v_and_b32_e32 v136, 64, v218
	v_add_f32_e32 v134, v135, v134
	v_xor_b32_e32 v135, 16, v218
	v_add_u32_e32 v137, 64, v136
	v_cmp_lt_i32_e32 vcc, v135, v137
	v_add_f32_e32 v134, v142, v134
	v_cvt_pk_bf16_f32 v140, v140, v141
	v_cndmask_b32_e32 v135, v218, v135, vcc
	v_lshlrev_b32_e32 v136, 2, v135
	ds_bpermute_b32 v135, v136, v134
	v_cvt_pk_bf16_f32 v141, v138, v139
	global_store_dwordx2 v[160:161], v[140:141], off offset:288
	s_waitcnt lgkmcnt(0)
	v_add_f32_e32 v138, v134, v135
	v_xor_b32_e32 v134, 32, v218
	v_cmp_lt_i32_e32 vcc, v134, v137
	s_nop 1
	v_cndmask_b32_e32 v134, v218, v134, vcc
	v_lshlrev_b32_e32 v137, 2, v134
	ds_bpermute_b32 v139, v137, v138
	v_lshl_add_u64 v[134:135], v[170:171], 3, s[16:17]
	s_and_saveexec_b64 s[26:27], s[8:9]
	s_cbranch_execz .LBB0_908
	s_waitcnt lgkmcnt(0)
	v_add_f32_e32 v138, v138, v139
	v_mul_f32_e32 v138, 0x4b800000, v138
	v_trunc_f32_e32 v138, v138
	v_mul_f32_e32 v139, 0x2f800000, v138
	v_floor_f32_e32 v139, v139
	v_fmac_f32_e32 v138, 0xcf800000, v139
	v_cvt_u32_f32_e32 v138, v138
	v_cvt_u32_f32_e32 v139, v139
	global_atomic_add_x2 v[134:135], v[138:139], off

; #define PG8_STAGE(bufoff, gbase, voff) do { _Pragma("unroll") for (int _i = 0; _i < 2; ++_i) \
;         __builtin_amdgcn_global_load_lds((const unsigned*)((const char*)(gbase) + (voff)[_i]), (PG8_LAS unsigned*)(lds + (bufoff) + ldsw + _i * 8192), 16, 0, 0); } while (0)
; #define PG8_LDA(dst, b, h) do { _Pragma("unroll") for (int m = 0; m < 4; ++m) _Pragma("unroll") for (int k = 0; k < 2; ++k) dst[m][k] = *(const PG8_LAS bf16x8*)(lds + PG8_SA(b, h) + aoff + m * 2048 + k * 1024); } while (0)
; #define PG8_LDB(dst, b, h) do { _Pragma("unroll") for (int n = 0; n < 2; ++n) _Pragma("unroll") for (int k = 0; k < 2; ++k) dst[n][k] = *(const PG8_LAS bf16x8*)(lds + PG8_SB(b, h) + boff + n * 2048 + k * 1024); } while (0)
; template <class Epi, class Sched, bool ALIGN_EPI = false, bool SP2 = false>
; __device__ __forceinline__ void gemm_phase(PG8_LAS unsigned char* lds, const Gemm g, const Sched& S, const Epi& E) {
;     ...
;         for (int t = 0; t < nt; t += 2) {
;             const bool last = (t == nt - 2);
;             const char* a1 = cA + (size_t)(t + 1) * kstep;
;             const char* a2 = last ? nA : cA + (size_t)(t + 2) * kstep; const char* b2 = last ? nB : cB + (size_t)(t + 2) * kstep;
;             const char* a3 = a2 + kstep; const char* b3 = b2 + kstep;
;             if (last && has_next) S.a_ready(nxt);
;             if constexpr (SP2) {
;             PG8_LDB(B0, 0, 0); PG8_LDB(B1, 0, 1); PG8_SCHED; PG8_LDA(At, 0, 0); PG8_STAGE(PG8_SA(1, 1), a1 + hstep, voffA);
;             PG8_WAIT_V(8); PG8_WAIT_L(0); PG8_BAR; PG8_MMA(0, 0, At, B0); PG8_MMA(0, 1, At, B1); PG8_BAR; PG8_SCHED;
;             PG8_LDA(At, 0, 1); PG8_STAGE(PG8_SB(0, 0), b2, voffB); PG8_STAGE(PG8_SB(0, 1), b2 + hstep, voffB); PG8_STAGE(PG8_SA(0, 0), a2, voffA);
;             PG8_WAIT_V(8); PG8_WAIT_L(0); PG8_BAR; PG8_MMA(1, 0, At, B0); PG8_MMA(1, 1, At, B1); PG8_BAR; PG8_SCHED;
;             PG8_LDB(B0, 1, 0); PG8_LDB(B1, 1, 1); PG8_SCHED; PG8_LDA(At, 1, 0); PG8_STAGE(PG8_SA(0, 1), a2 + hstep, voffA);
;             PG8_WAIT_V(8); PG8_WAIT_L(0); PG8_BAR; PG8_MMA(0, 0, At, B0); PG8_MMA(0, 1, At, B1); PG8_BAR; PG8_SCHED;
;             PG8_LDA(At, 1, 1); PG8_STAGE(PG8_SB(1, 0), b3, voffB); PG8_STAGE(PG8_SB(1, 1), b3 + hstep, voffB); PG8_STAGE(PG8_SA(1, 0), a3, voffA);
;             PG8_WAIT_V(8); PG8_WAIT_L(0); PG8_BAR; PG8_MMA(1, 0, At, B0); PG8_MMA(1, 1, At, B1); PG8_BAR; PG8_SCHED;
.LBB0_1016:
	s_add_u32 s24, s22, 0xfff80080
	s_addc_u32 s25, s23, -1
	s_add_i32 s67, 0, 0x10000
	s_cmp_eq_u32 s66, 28
	s_cselect_b32 s27, s17, s25
	s_cselect_b32 s26, s50, s24
	v_add_u32_e32 v158, s67, v152
	s_cselect_b32 s25, s15, s53
	s_cselect_b32 s24, s51, s52
	s_add_i32 s69, 0, 0x14000
	ds_read_b128 v[142:145], v158
	ds_read_b128 v[146:149], v158 offset:1024
	ds_read_b128 v[164:167], v158 offset:2048
	ds_read_b128 v[168:171], v158 offset:3072
	v_add_u32_e32 v158, s69, v152
	ds_read_b128 v[172:175], v158
	ds_read_b128 v[176:179], v158 offset:1024
	ds_read_b128 v[180:183], v158 offset:2048
	ds_read_b128 v[184:187], v158 offset:3072
	s_add_i32 m0, s41, 0xc000
	ds_read_b128 v[188:191], v163
	ds_read_b128 v[192:195], v163 offset:1024
	ds_read_b128 v[196:199], v163 offset:2048
	ds_read_b128 v[200:203], v163 offset:3072
	ds_read_b128 v[204:207], v163 offset:4096
	ds_read_b128 v[230:233], v163 offset:5120
	ds_read_b128 v[234:237], v163 offset:6144
	ds_read_b128 v[238:241], v163 offset:7168
	global_load_lds_dwordx4 v140, s[22:23]
	s_add_i32 m0, s41, 0xe000
	s_nop 0
	global_load_lds_dwordx4 v138, s[22:23]
	s_waitcnt vmcnt(8)
	s_waitcnt lgkmcnt(0)
	s_barrier
	s_waitcnt lgkmcnt(0)
	v_mfma_f32_16x16x32_bf16 v[130:133], v[142:145], v[188:191], v[130:133]
	v_mfma_f32_16x16x32_bf16 v[126:129], v[164:167], v[188:191], v[126:129]
	v_mfma_f32_16x16x32_bf16 v[114:117], v[142:145], v[196:199], v[114:117]
	v_mfma_f32_16x16x32_bf16 v[110:113], v[164:167], v[196:199], v[110:113]
	v_mfma_f32_16x16x32_bf16 v[98:101], v[142:145], v[204:207], v[98:101]
	v_mfma_f32_16x16x32_bf16 v[94:97], v[164:167], v[204:207], v[94:97]
	v_mfma_f32_16x16x32_bf16 v[82:85], v[142:145], v[234:237], v[82:85]
	v_mfma_f32_16x16x32_bf16 v[78:81], v[164:167], v[234:237], v[78:81]
	v_mfma_f32_16x16x32_bf16 v[130:133], v[146:149], v[192:195], v[130:133]
	v_mfma_f32_16x16x32_bf16 v[126:129], v[168:171], v[192:195], v[126:129]
	v_mfma_f32_16x16x32_bf16 v[114:117], v[146:149], v[200:203], v[114:117]
	v_mfma_f32_16x16x32_bf16 v[110:113], v[168:171], v[200:203], v[110:113]
	v_mfma_f32_16x16x32_bf16 v[98:101], v[146:149], v[230:233], v[98:101]
	v_mfma_f32_16x16x32_bf16 v[94:97], v[168:171], v[230:233], v[94:97]
	v_mfma_f32_16x16x32_bf16 v[82:85], v[146:149], v[238:241], v[82:85]
	v_mfma_f32_16x16x32_bf16 v[78:81], v[168:171], v[238:241], v[78:81]
	v_mfma_f32_16x16x32_bf16 v[122:125], v[172:175], v[188:191], v[122:125]
	v_mfma_f32_16x16x32_bf16 v[118:121], v[180:183], v[188:191], v[118:121]
	v_mfma_f32_16x16x32_bf16 v[106:109], v[172:175], v[196:199], v[106:109]
	v_mfma_f32_16x16x32_bf16 v[102:105], v[180:183], v[196:199], v[102:105]
	v_mfma_f32_16x16x32_bf16 v[90:93], v[172:175], v[204:207], v[90:93]
	v_mfma_f32_16x16x32_bf16 v[86:89], v[180:183], v[204:207], v[86:89]
	v_mfma_f32_16x16x32_bf16 v[74:77], v[172:175], v[234:237], v[74:77]
	v_mfma_f32_16x16x32_bf16 v[70:73], v[180:183], v[234:237], v[70:73]
	v_mfma_f32_16x16x32_bf16 v[122:125], v[176:179], v[192:195], v[122:125]
	v_mfma_f32_16x16x32_bf16 v[118:121], v[184:187], v[192:195], v[118:121]
	v_mfma_f32_16x16x32_bf16 v[106:109], v[176:179], v[200:203], v[106:109]
	v_mfma_f32_16x16x32_bf16 v[102:105], v[184:187], v[200:203], v[102:105]
	v_mfma_f32_16x16x32_bf16 v[90:93], v[176:179], v[230:233], v[90:93]
	v_mfma_f32_16x16x32_bf16 v[86:89], v[184:187], v[230:233], v[86:89]
	v_mfma_f32_16x16x32_bf16 v[74:77], v[176:179], v[238:241], v[74:77]
	v_mfma_f32_16x16x32_bf16 v[70:73], v[184:187], v[238:241], v[70:73]
	s_barrier
	s_add_i32 s67, s67, s30
	s_mov_b32 m0, s67
	ds_read_b128 v[188:191], v163 offset:16384
	ds_read_b128 v[192:195], v163 offset:17408
	ds_read_b128 v[196:199], v163 offset:18432
	ds_read_b128 v[200:203], v163 offset:19456
	ds_read_b128 v[204:207], v163 offset:20480
	ds_read_b128 v[230:233], v163 offset:21504
	ds_read_b128 v[234:237], v163 offset:22528
	ds_read_b128 v[238:241], v163 offset:23552
	global_load_lds_dwordx4 v2, s[24:25]
	s_add_i32 m0, s67, 0x2000
	s_add_u32 s70, s24, 0x80000
	s_addc_u32 s71, s25, 0
	s_add_i32 s67, s69, s30
	global_load_lds_dwordx4 v0, s[24:25]
	s_mov_b32 m0, s67
	v_lshl_add_u64 v[246:247], s[26:27], 0, v[134:135]
	global_load_lds_dwordx4 v2, s[70:71]
	s_add_i32 m0, s67, 0x2000
	s_nop 0
	global_load_lds_dwordx4 v0, s[70:71]
	v_lshl_add_u64 v[244:245], s[26:27], 0, v[136:137]
	s_mov_b32 m0, s41
	s_nop 0
	global_load_lds_dwordx4 v136, s[26:27]
	s_mov_b32 m0, s42
	s_nop 0
	global_load_lds_dwordx4 v134, s[26:27]
	s_waitcnt vmcnt(8)
	s_waitcnt lgkmcnt(0)
	s_barrier
	s_waitcnt lgkmcnt(0)
	v_mfma_f32_16x16x32_bf16 v[66:69], v[142:145], v[188:191], v[66:69]
	v_mfma_f32_16x16x32_bf16 v[62:65], v[164:167], v[188:191], v[62:65]
	v_mfma_f32_16x16x32_bf16 v[50:53], v[142:145], v[196:199], v[50:53]
	v_mfma_f32_16x16x32_bf16 v[46:49], v[164:167], v[196:199], v[46:49]
	v_mfma_f32_16x16x32_bf16 v[34:37], v[142:145], v[204:207], v[34:37]
	v_mfma_f32_16x16x32_bf16 v[30:33], v[164:167], v[204:207], v[30:33]
	v_mfma_f32_16x16x32_bf16 v[18:21], v[142:145], v[234:237], v[18:21]
	v_mfma_f32_16x16x32_bf16 v[14:17], v[164:167], v[234:237], v[14:17]
	v_mfma_f32_16x16x32_bf16 v[66:69], v[146:149], v[192:195], v[66:69]
	v_mfma_f32_16x16x32_bf16 v[62:65], v[168:171], v[192:195], v[62:65]
	v_mfma_f32_16x16x32_bf16 v[50:53], v[146:149], v[200:203], v[50:53]
	v_mfma_f32_16x16x32_bf16 v[46:49], v[168:171], v[200:203], v[46:49]
	v_mfma_f32_16x16x32_bf16 v[34:37], v[146:149], v[230:233], v[34:37]
	v_mfma_f32_16x16x32_bf16 v[30:33], v[168:171], v[230:233], v[30:33]
	v_mfma_f32_16x16x32_bf16 v[18:21], v[146:149], v[238:241], v[18:21]
	v_mfma_f32_16x16x32_bf16 v[14:17], v[168:171], v[238:241], v[14:17]
	v_mfma_f32_16x16x32_bf16 v[58:61], v[172:175], v[188:191], v[58:61]
	v_mfma_f32_16x16x32_bf16 v[54:57], v[180:183], v[188:191], v[54:57]
	v_mfma_f32_16x16x32_bf16 v[42:45], v[172:175], v[196:199], v[42:45]
	v_mfma_f32_16x16x32_bf16 v[38:41], v[180:183], v[196:199], v[38:41]
	v_mfma_f32_16x16x32_bf16 v[26:29], v[172:175], v[204:207], v[26:29]
	v_mfma_f32_16x16x32_bf16 v[22:25], v[180:183], v[204:207], v[22:25]
	v_mfma_f32_16x16x32_bf16 v[10:13], v[172:175], v[234:237], v[10:13]
	v_mfma_f32_16x16x32_bf16 v[6:9], v[180:183], v[234:237], v[6:9]
	v_mfma_f32_16x16x32_bf16 v[58:61], v[176:179], v[192:195], v[58:61]
	v_mfma_f32_16x16x32_bf16 v[54:57], v[184:187], v[192:195], v[54:57]
	v_mfma_f32_16x16x32_bf16 v[42:45], v[176:179], v[200:203], v[42:45]
	v_mfma_f32_16x16x32_bf16 v[38:41], v[184:187], v[200:203], v[38:41]
	v_mfma_f32_16x16x32_bf16 v[26:29], v[176:179], v[230:233], v[26:29]
	v_mfma_f32_16x16x32_bf16 v[22:25], v[184:187], v[230:233], v[22:25]
	v_mfma_f32_16x16x32_bf16 v[10:13], v[176:179], v[238:241], v[10:13]
	v_mfma_f32_16x16x32_bf16 v[6:9], v[184:187], v[238:241], v[6:9]
	s_barrier
; #define PG8_STAGE(bufoff, gbase, voff) do { _Pragma("unroll") for (int _i = 0; _i < 2; ++_i) \
;         __builtin_amdgcn_global_load_lds((const unsigned*)((const char*)(gbase) + (voff)[_i]), (PG8_LAS unsigned*)(lds + (bufoff) + ldsw + _i * 8192), 16, 0, 0); } while (0)
; #define PG8_LDA(dst, b, h) do { _Pragma("unroll") for (int m = 0; m < 4; ++m) _Pragma("unroll") for (int k = 0; k < 2; ++k) dst[m][k] = *(const PG8_LAS bf16x8*)(lds + PG8_SA(b, h) + aoff + m * 2048 + k * 1024); } while (0)
; #define PG8_WAIT_V(n) asm volatile("s_waitcnt vmcnt(" #n ")" ::: "memory")
; #define PG8_WAIT_L(n) asm volatile("s_waitcnt lgkmcnt(" #n ")" ::: "memory")
; template <class Epi, class Sched, bool ALIGN_EPI = false, bool SP2 = false>
; __device__ __forceinline__ void gemm_phase(PG8_LAS unsigned char* lds, const Gemm g, const Sched& S, const Epi& E) {
;     ...
;         for (int t = 0; t < nt; t += 2) {
;             const bool last = (t == nt - 2);
;             const char* a1 = cA + (size_t)(t + 1) * kstep;
;             const char* a2 = last ? nA : cA + (size_t)(t + 2) * kstep; const char* b2 = last ? nB : cB + (size_t)(t + 2) * kstep;
;             const char* a3 = a2 + kstep; const char* b3 = b2 + kstep;
;             if (last && has_next) S.a_ready(nxt);
;             if constexpr (SP2) {
;             PG8_LDB(B0, 0, 0); PG8_LDB(B1, 0, 1); PG8_SCHED; PG8_LDA(At, 0, 0); PG8_STAGE(PG8_SA(1, 1), a1 + hstep, voffA);
;             PG8_WAIT_V(8); PG8_WAIT_L(0); PG8_BAR; PG8_MMA(0, 0, At, B0); PG8_MMA(0, 1, At, B1); PG8_BAR; PG8_SCHED;
;             PG8_LDA(At, 0, 1); PG8_STAGE(PG8_SB(0, 0), b2, voffB); PG8_STAGE(PG8_SB(0, 1), b2 + hstep, voffB); PG8_STAGE(PG8_SA(0, 0), a2, voffA);
;             PG8_WAIT_V(8); PG8_WAIT_L(0); PG8_BAR; PG8_MMA(1, 0, At, B0); PG8_MMA(1, 1, At, B1); PG8_BAR; PG8_SCHED;
;             PG8_LDB(B0, 1, 0); PG8_LDB(B1, 1, 1); PG8_SCHED; PG8_LDA(At, 1, 0); PG8_STAGE(PG8_SA(0, 1), a2 + hstep, voffA);
;             PG8_WAIT_V(8); PG8_WAIT_L(0); PG8_BAR; PG8_MMA(0, 0, At, B0); PG8_MMA(0, 1, At, B1); PG8_BAR; PG8_SCHED;
;             PG8_LDA(At, 1, 1); PG8_STAGE(PG8_SB(1, 0), b3, voffB); PG8_STAGE(PG8_SB(1, 1), b3 + hstep, voffB); PG8_STAGE(PG8_SA(1, 0), a3, voffA);
;             PG8_WAIT_V(8); PG8_WAIT_L(0); PG8_BAR; PG8_MMA(1, 0, At, B0); PG8_MMA(1, 1, At, B1); PG8_BAR; PG8_SCHED;
;     ...
;         if constexpr (ALIGN_EPI) { if (wr == 0) PG8_BAR; }
	s_add_i32 s67, 0, 0x18000
	v_add_u32_e32 v160, s67, v152
	s_add_i32 s69, 0, 0x1c000
	ds_read_b128 v[142:145], v160
	ds_read_b128 v[146:149], v160 offset:1024
	ds_read_b128 v[164:167], v160 offset:2048
	ds_read_b128 v[168:171], v160 offset:3072
	v_add_u32_e32 v160, s69, v152
	ds_read_b128 v[172:175], v160
	ds_read_b128 v[176:179], v160 offset:1024
	ds_read_b128 v[180:183], v160 offset:2048
	ds_read_b128 v[184:187], v160 offset:3072
	s_add_u32 s26, s26, 0x80000
	s_addc_u32 s27, s27, 0
	s_mov_b32 m0, s43
	ds_read_b128 v[188:191], v163 offset:32768
	ds_read_b128 v[192:195], v163 offset:33792
	ds_read_b128 v[196:199], v163 offset:34816
	ds_read_b128 v[200:203], v163 offset:35840
	ds_read_b128 v[204:207], v163 offset:36864
	ds_read_b128 v[230:233], v163 offset:37888
	ds_read_b128 v[234:237], v163 offset:38912
	ds_read_b128 v[238:241], v163 offset:39936
	global_load_lds_dwordx4 v136, s[26:27]
	s_mov_b32 m0, s44
	s_nop 0
	global_load_lds_dwordx4 v134, s[26:27]
	s_waitcnt vmcnt(8)
	s_waitcnt lgkmcnt(0)
	s_barrier
	s_waitcnt lgkmcnt(0)
	v_mfma_f32_16x16x32_bf16 v[130:133], v[142:145], v[188:191], v[130:133]
	v_mfma_f32_16x16x32_bf16 v[126:129], v[164:167], v[188:191], v[126:129]
	v_mfma_f32_16x16x32_bf16 v[114:117], v[142:145], v[196:199], v[114:117]
	v_mfma_f32_16x16x32_bf16 v[110:113], v[164:167], v[196:199], v[110:113]
	v_mfma_f32_16x16x32_bf16 v[98:101], v[142:145], v[204:207], v[98:101]
	v_mfma_f32_16x16x32_bf16 v[94:97], v[164:167], v[204:207], v[94:97]
	v_mfma_f32_16x16x32_bf16 v[82:85], v[142:145], v[234:237], v[82:85]
	v_mfma_f32_16x16x32_bf16 v[78:81], v[164:167], v[234:237], v[78:81]
	v_mfma_f32_16x16x32_bf16 v[130:133], v[146:149], v[192:195], v[130:133]
	v_mfma_f32_16x16x32_bf16 v[126:129], v[168:171], v[192:195], v[126:129]
	v_mfma_f32_16x16x32_bf16 v[114:117], v[146:149], v[200:203], v[114:117]
	v_mfma_f32_16x16x32_bf16 v[110:113], v[168:171], v[200:203], v[110:113]
	v_mfma_f32_16x16x32_bf16 v[98:101], v[146:149], v[230:233], v[98:101]
	v_mfma_f32_16x16x32_bf16 v[94:97], v[168:171], v[230:233], v[94:97]
	v_mfma_f32_16x16x32_bf16 v[82:85], v[146:149], v[238:241], v[82:85]
	v_mfma_f32_16x16x32_bf16 v[78:81], v[168:171], v[238:241], v[78:81]
	v_mfma_f32_16x16x32_bf16 v[122:125], v[172:175], v[188:191], v[122:125]
	v_mfma_f32_16x16x32_bf16 v[118:121], v[180:183], v[188:191], v[118:121]
	v_mfma_f32_16x16x32_bf16 v[106:109], v[172:175], v[196:199], v[106:109]
	v_mfma_f32_16x16x32_bf16 v[102:105], v[180:183], v[196:199], v[102:105]
	v_mfma_f32_16x16x32_bf16 v[90:93], v[172:175], v[204:207], v[90:93]
	v_mfma_f32_16x16x32_bf16 v[86:89], v[180:183], v[204:207], v[86:89]
	v_mfma_f32_16x16x32_bf16 v[74:77], v[172:175], v[234:237], v[74:77]
	v_mfma_f32_16x16x32_bf16 v[70:73], v[180:183], v[234:237], v[70:73]
	v_mfma_f32_16x16x32_bf16 v[122:125], v[176:179], v[192:195], v[122:125]
	v_mfma_f32_16x16x32_bf16 v[118:121], v[184:187], v[192:195], v[118:121]
	v_mfma_f32_16x16x32_bf16 v[106:109], v[176:179], v[200:203], v[106:109]
	v_mfma_f32_16x16x32_bf16 v[102:105], v[184:187], v[200:203], v[102:105]
	v_mfma_f32_16x16x32_bf16 v[90:93], v[176:179], v[230:233], v[90:93]
	v_mfma_f32_16x16x32_bf16 v[86:89], v[184:187], v[230:233], v[86:89]
	v_mfma_f32_16x16x32_bf16 v[74:77], v[176:179], v[238:241], v[74:77]
	v_mfma_f32_16x16x32_bf16 v[70:73], v[184:187], v[238:241], v[70:73]
	s_barrier
	s_add_u32 vcc_lo, s24, s2
	s_addc_u32 vcc_hi, s25, s3
	s_add_i32 s26, s67, s30
	s_mov_b32 m0, s26
	ds_read_b128 v[188:191], v163 offset:49152
	ds_read_b128 v[192:195], v163 offset:50176
	ds_read_b128 v[196:199], v163 offset:51200
	ds_read_b128 v[200:203], v163 offset:52224
	ds_read_b128 v[204:207], v163 offset:53248
	ds_read_b128 v[230:233], v163 offset:54272
	ds_read_b128 v[234:237], v163 offset:55296
	ds_read_b128 v[238:241], v163 offset:56320
	global_load_lds_dwordx4 v2, vcc
	s_add_i32 m0, s26, 0x2000
	s_add_u32 s24, s24, 0x80080
	s_addc_u32 s25, s25, 0
	s_add_i32 s26, s69, s30
	global_load_lds_dwordx4 v0, vcc
	s_mov_b32 m0, s26
	s_nop 0
	global_load_lds_dwordx4 v2, s[24:25]
	s_add_i32 m0, s26, 0x2000
	s_nop 0
	global_load_lds_dwordx4 v0, s[24:25]
	v_lshl_add_u64 v[158:159], v[244:245], 0, s[2:3]
	s_mov_b32 m0, s45
	s_nop 0
	global_load_lds_dwordx4 v[158:159], off
	v_lshl_add_u64 v[158:159], v[246:247], 0, s[2:3]
	s_mov_b32 m0, s46
	s_nop 0
	global_load_lds_dwordx4 v[158:159], off
	s_waitcnt vmcnt(8)
	s_waitcnt lgkmcnt(0)
	s_barrier
	s_waitcnt lgkmcnt(0)
	v_mfma_f32_16x16x32_bf16 v[66:69], v[142:145], v[188:191], v[66:69]
	v_mfma_f32_16x16x32_bf16 v[62:65], v[164:167], v[188:191], v[62:65]
	v_mfma_f32_16x16x32_bf16 v[50:53], v[142:145], v[196:199], v[50:53]
	v_mfma_f32_16x16x32_bf16 v[46:49], v[164:167], v[196:199], v[46:49]
	v_mfma_f32_16x16x32_bf16 v[34:37], v[142:145], v[204:207], v[34:37]
	v_mfma_f32_16x16x32_bf16 v[30:33], v[164:167], v[204:207], v[30:33]
	v_mfma_f32_16x16x32_bf16 v[18:21], v[142:145], v[234:237], v[18:21]
	v_mfma_f32_16x16x32_bf16 v[14:17], v[164:167], v[234:237], v[14:17]
	v_mfma_f32_16x16x32_bf16 v[66:69], v[146:149], v[192:195], v[66:69]
	v_mfma_f32_16x16x32_bf16 v[62:65], v[168:171], v[192:195], v[62:65]
	v_mfma_f32_16x16x32_bf16 v[50:53], v[146:149], v[200:203], v[50:53]
	v_mfma_f32_16x16x32_bf16 v[46:49], v[168:171], v[200:203], v[46:49]
	v_mfma_f32_16x16x32_bf16 v[34:37], v[146:149], v[230:233], v[34:37]
	v_mfma_f32_16x16x32_bf16 v[30:33], v[168:171], v[230:233], v[30:33]
	v_mfma_f32_16x16x32_bf16 v[18:21], v[146:149], v[238:241], v[18:21]
	v_mfma_f32_16x16x32_bf16 v[14:17], v[168:171], v[238:241], v[14:17]
	v_mfma_f32_16x16x32_bf16 v[58:61], v[172:175], v[188:191], v[58:61]
	v_mfma_f32_16x16x32_bf16 v[54:57], v[180:183], v[188:191], v[54:57]
	v_mfma_f32_16x16x32_bf16 v[42:45], v[172:175], v[196:199], v[42:45]
	v_mfma_f32_16x16x32_bf16 v[38:41], v[180:183], v[196:199], v[38:41]
	v_mfma_f32_16x16x32_bf16 v[26:29], v[172:175], v[204:207], v[26:29]
	v_mfma_f32_16x16x32_bf16 v[22:25], v[180:183], v[204:207], v[22:25]
	v_mfma_f32_16x16x32_bf16 v[10:13], v[172:175], v[234:237], v[10:13]
	v_mfma_f32_16x16x32_bf16 v[6:9], v[180:183], v[234:237], v[6:9]
	v_mfma_f32_16x16x32_bf16 v[58:61], v[176:179], v[192:195], v[58:61]
	v_mfma_f32_16x16x32_bf16 v[54:57], v[184:187], v[192:195], v[54:57]
	v_mfma_f32_16x16x32_bf16 v[42:45], v[176:179], v[200:203], v[42:45]
	v_mfma_f32_16x16x32_bf16 v[38:41], v[184:187], v[200:203], v[38:41]
	v_mfma_f32_16x16x32_bf16 v[26:29], v[176:179], v[230:233], v[26:29]
	v_mfma_f32_16x16x32_bf16 v[22:25], v[184:187], v[230:233], v[22:25]
	v_mfma_f32_16x16x32_bf16 v[10:13], v[176:179], v[238:241], v[10:13]
	v_mfma_f32_16x16x32_bf16 v[6:9], v[184:187], v[238:241], v[6:9]
	s_barrier
	s_add_i32 s66, s66, 2
	s_add_u32 s52, s52, 0x100
	s_addc_u32 s53, s53, 0
	s_add_u32 s22, s22, 0x100
	s_addc_u32 s23, s23, 0
	s_cmp_gt_u32 s66, 29
	s_cbranch_scc0 .LBB0_1016
	s_and_b64 vcc, exec, s[12:13]
	s_cbranch_vccz .LBB0_1019
	s_barrier

; #define PG8_STAGE(bufoff, gbase, voff) do { _Pragma("unroll") for (int _i = 0; _i < 2; ++_i) \
;         __builtin_amdgcn_global_load_lds((const unsigned*)((const char*)(gbase) + (voff)[_i]), (PG8_LAS unsigned*)(lds + (bufoff) + ldsw + _i * 8192), 16, 0, 0); } while (0)
; #define PG8_LDA(dst, b, h) do { _Pragma("unroll") for (int m = 0; m < 4; ++m) _Pragma("unroll") for (int k = 0; k < 2; ++k) dst[m][k] = *(const PG8_LAS bf16x8*)(lds + PG8_SA(b, h) + aoff + m * 2048 + k * 1024); } while (0)
; #define PG8_LDB(dst, b, h) do { _Pragma("unroll") for (int n = 0; n < 2; ++n) _Pragma("unroll") for (int k = 0; k < 2; ++k) dst[n][k] = *(const PG8_LAS bf16x8*)(lds + PG8_SB(b, h) + boff + n * 2048 + k * 1024); } while (0)
; #define PG8_MMA(ai, bj, At, Bt) do { __builtin_amdgcn_s_setprio(1); _Pragma("unroll") for (int m = 0; m < 4; ++m) _Pragma("unroll") for (int n = 0; n < 2; ++n) _Pragma("unroll") for (int k = 0; k < 2; ++k) \
;         acc[ai][bj][m][n] = __builtin_amdgcn_mfma_f32_16x16x32_bf16(Bt[n][k], At[m][k], acc[ai][bj][m][n], 0, 0, 0); __builtin_amdgcn_s_setprio(0); } while (0)
; #define PG8_WAIT_V(n) asm volatile("s_waitcnt vmcnt(" #n ")" ::: "memory")
; #define PG8_WAIT_L(n) asm volatile("s_waitcnt lgkmcnt(" #n ")" ::: "memory")
; #define PG8_BAR __builtin_amdgcn_s_barrier()
; #define PG8_SCHED __builtin_amdgcn_sched_barrier(0)
; template <class Epi, class Sched, bool ALIGN_EPI = false, bool SP2 = false>
; __device__ __forceinline__ void gemm_phase(PG8_LAS unsigned char* lds, const Gemm g, const Sched& S, const Epi& E) {
;     ...
;             PG8_LDB(B0, 0, 0); PG8_LDB(B1, 0, 1); PG8_SCHED; PG8_LDA(At, 0, 0); PG8_STAGE(PG8_SA(1, 1), a1 + hstep, voffA);
;             PG8_WAIT_V(8); PG8_WAIT_L(0); PG8_BAR; PG8_MMA(0, 0, At, B0); PG8_MMA(0, 1, At, B1); PG8_BAR; PG8_SCHED;
;             PG8_LDA(At, 0, 1); PG8_STAGE(PG8_SB(0, 0), b2, voffB); PG8_STAGE(PG8_SB(0, 1), b2 + hstep, voffB); PG8_STAGE(PG8_SA(0, 0), a2, voffA);
;             PG8_WAIT_V(8); PG8_WAIT_L(0); PG8_BAR; PG8_MMA(1, 0, At, B0); PG8_MMA(1, 1, At, B1); PG8_BAR; PG8_SCHED;
.LBB0_1630:
	s_add_u32 s26, s24, 0x100
	s_addc_u32 s27, s25, 0
	s_add_i32 s78, 0, 0x10000
	s_cmp_eq_u32 s71, 28
	s_cselect_b32 s31, s19, s27
	s_cselect_b32 s30, s66, s26
	s_cselect_b32 s29, s17, s70
	s_cselect_b32 s28, s67, s69
	s_add_i32 s79, 0, 0x14000
	v_add_u32_e32 v98, s78, v152
	v_add_u32_e32 v158, s79, v152
	ds_read_b128 v[78:81], v98
	ds_read_b128 v[90:93], v98 offset:1024
	ds_read_b128 v[94:97], v98 offset:2048
	ds_read_b128 v[98:101], v98 offset:3072
	ds_read_b128 v[166:169], v158
	ds_read_b128 v[174:177], v158 offset:1024
	ds_read_b128 v[178:181], v158 offset:2048
	ds_read_b128 v[182:185], v158 offset:3072
	s_add_i32 m0, s45, 0xc000
	ds_read_b128 v[186:189], v173
	ds_read_b128 v[190:193], v173 offset:1024
	ds_read_b128 v[194:197], v173 offset:2048
	ds_read_b128 v[198:201], v173 offset:3072
	ds_read_b128 v[202:205], v173 offset:4096
	ds_read_b128 v[230:233], v173 offset:5120
	ds_read_b128 v[234:237], v173 offset:6144
	ds_read_b128 v[238:241], v173 offset:7168
	global_load_lds_dwordx4 v164, s[24:25]
	s_add_i32 m0, s45, 0xe000
	s_nop 0
	global_load_lds_dwordx4 v162, s[24:25]
	s_waitcnt vmcnt(8)
	s_waitcnt lgkmcnt(0)
	s_barrier
	s_waitcnt lgkmcnt(0)
	v_mfma_f32_16x16x32_bf16 v[146:149], v[78:81], v[186:189], v[146:149]
	v_mfma_f32_16x16x32_bf16 v[142:145], v[94:97], v[186:189], v[142:145]
	v_mfma_f32_16x16x32_bf16 v[130:133], v[78:81], v[194:197], v[130:133]
	v_mfma_f32_16x16x32_bf16 v[126:129], v[94:97], v[194:197], v[126:129]
	v_mfma_f32_16x16x32_bf16 v[114:117], v[78:81], v[202:205], v[114:117]
	v_mfma_f32_16x16x32_bf16 v[110:113], v[94:97], v[202:205], v[110:113]
	v_mfma_f32_16x16x32_bf16 v[86:89], v[78:81], v[234:237], v[86:89]
	v_mfma_f32_16x16x32_bf16 v[82:85], v[94:97], v[234:237], v[82:85]
	v_mfma_f32_16x16x32_bf16 v[146:149], v[90:93], v[190:193], v[146:149]
	v_mfma_f32_16x16x32_bf16 v[142:145], v[98:101], v[190:193], v[142:145]
	v_mfma_f32_16x16x32_bf16 v[130:133], v[90:93], v[198:201], v[130:133]
	v_mfma_f32_16x16x32_bf16 v[126:129], v[98:101], v[198:201], v[126:129]
	v_mfma_f32_16x16x32_bf16 v[114:117], v[90:93], v[230:233], v[114:117]
	v_mfma_f32_16x16x32_bf16 v[110:113], v[98:101], v[230:233], v[110:113]
	v_mfma_f32_16x16x32_bf16 v[86:89], v[90:93], v[238:241], v[86:89]
	v_mfma_f32_16x16x32_bf16 v[82:85], v[98:101], v[238:241], v[82:85]
	v_mfma_f32_16x16x32_bf16 v[138:141], v[166:169], v[186:189], v[138:141]
	v_mfma_f32_16x16x32_bf16 v[134:137], v[178:181], v[186:189], v[134:137]
	v_mfma_f32_16x16x32_bf16 v[122:125], v[166:169], v[194:197], v[122:125]
	v_mfma_f32_16x16x32_bf16 v[118:121], v[178:181], v[194:197], v[118:121]
	v_mfma_f32_16x16x32_bf16 v[106:109], v[166:169], v[202:205], v[106:109]
	v_mfma_f32_16x16x32_bf16 v[102:105], v[178:181], v[202:205], v[102:105]
	v_mfma_f32_16x16x32_bf16 v[74:77], v[166:169], v[234:237], v[74:77]
	v_mfma_f32_16x16x32_bf16 v[70:73], v[178:181], v[234:237], v[70:73]
	v_mfma_f32_16x16x32_bf16 v[138:141], v[174:177], v[190:193], v[138:141]
	v_mfma_f32_16x16x32_bf16 v[134:137], v[182:185], v[190:193], v[134:137]
	v_mfma_f32_16x16x32_bf16 v[122:125], v[174:177], v[198:201], v[122:125]
	v_mfma_f32_16x16x32_bf16 v[118:121], v[182:185], v[198:201], v[118:121]
	v_mfma_f32_16x16x32_bf16 v[106:109], v[174:177], v[230:233], v[106:109]
	v_mfma_f32_16x16x32_bf16 v[102:105], v[182:185], v[230:233], v[102:105]
	v_mfma_f32_16x16x32_bf16 v[74:77], v[174:177], v[238:241], v[74:77]
	v_mfma_f32_16x16x32_bf16 v[70:73], v[182:185], v[238:241], v[70:73]
	s_barrier
	s_add_i32 s24, s78, s44
	s_mov_b32 m0, s24
	ds_read_b128 v[186:189], v173 offset:16384
	ds_read_b128 v[190:193], v173 offset:17408
	ds_read_b128 v[194:197], v173 offset:18432
	ds_read_b128 v[198:201], v173 offset:19456
	ds_read_b128 v[202:205], v173 offset:20480
	ds_read_b128 v[230:233], v173 offset:21504
	ds_read_b128 v[234:237], v173 offset:22528
	ds_read_b128 v[238:241], v173 offset:23552
	global_load_lds_dwordx4 v2, s[28:29]
	s_add_i32 m0, s24, 0x2000
	s_add_u32 s24, s28, 0x80000
	s_addc_u32 s25, s29, 0
	s_add_i32 s78, s79, s44
	global_load_lds_dwordx4 v0, s[28:29]
	s_mov_b32 m0, s78
	s_nop 0
	global_load_lds_dwordx4 v2, s[24:25]
	s_add_i32 m0, s78, 0x2000
	s_nop 0
	global_load_lds_dwordx4 v0, s[24:25]
	s_mov_b32 m0, s45
	s_nop 0
	global_load_lds_dwordx4 v2, s[30:31]
	s_mov_b32 m0, s46
	s_nop 0
	global_load_lds_dwordx4 v0, s[30:31]
	s_waitcnt vmcnt(8)
	s_waitcnt lgkmcnt(0)
	s_barrier
	s_waitcnt lgkmcnt(0)
	v_mfma_f32_16x16x32_bf16 v[66:69], v[78:81], v[186:189], v[66:69]
	v_mfma_f32_16x16x32_bf16 v[62:65], v[94:97], v[186:189], v[62:65]
	v_mfma_f32_16x16x32_bf16 v[50:53], v[78:81], v[194:197], v[50:53]
	v_mfma_f32_16x16x32_bf16 v[46:49], v[94:97], v[194:197], v[46:49]
	v_mfma_f32_16x16x32_bf16 v[34:37], v[78:81], v[202:205], v[34:37]
	v_mfma_f32_16x16x32_bf16 v[30:33], v[94:97], v[202:205], v[30:33]
	v_mfma_f32_16x16x32_bf16 v[18:21], v[78:81], v[234:237], v[18:21]
	v_mfma_f32_16x16x32_bf16 v[14:17], v[94:97], v[234:237], v[14:17]
	v_mfma_f32_16x16x32_bf16 v[66:69], v[90:93], v[190:193], v[66:69]
	v_mfma_f32_16x16x32_bf16 v[62:65], v[98:101], v[190:193], v[62:65]
	v_mfma_f32_16x16x32_bf16 v[50:53], v[90:93], v[198:201], v[50:53]
	v_mfma_f32_16x16x32_bf16 v[46:49], v[98:101], v[198:201], v[46:49]
	v_mfma_f32_16x16x32_bf16 v[34:37], v[90:93], v[230:233], v[34:37]
	v_mfma_f32_16x16x32_bf16 v[30:33], v[98:101], v[230:233], v[30:33]
	v_mfma_f32_16x16x32_bf16 v[18:21], v[90:93], v[238:241], v[18:21]
	v_mfma_f32_16x16x32_bf16 v[14:17], v[98:101], v[238:241], v[14:17]
	v_mfma_f32_16x16x32_bf16 v[58:61], v[166:169], v[186:189], v[58:61]
	v_mfma_f32_16x16x32_bf16 v[54:57], v[178:181], v[186:189], v[54:57]
	v_mfma_f32_16x16x32_bf16 v[42:45], v[166:169], v[194:197], v[42:45]
	v_mfma_f32_16x16x32_bf16 v[38:41], v[178:181], v[194:197], v[38:41]
	v_mfma_f32_16x16x32_bf16 v[26:29], v[166:169], v[202:205], v[26:29]
	v_mfma_f32_16x16x32_bf16 v[22:25], v[178:181], v[202:205], v[22:25]
	v_mfma_f32_16x16x32_bf16 v[10:13], v[166:169], v[234:237], v[10:13]
	v_mfma_f32_16x16x32_bf16 v[6:9], v[178:181], v[234:237], v[6:9]
	v_mfma_f32_16x16x32_bf16 v[58:61], v[174:177], v[190:193], v[58:61]
	v_mfma_f32_16x16x32_bf16 v[54:57], v[182:185], v[190:193], v[54:57]
	v_mfma_f32_16x16x32_bf16 v[42:45], v[174:177], v[198:201], v[42:45]
	v_mfma_f32_16x16x32_bf16 v[38:41], v[182:185], v[198:201], v[38:41]
	v_mfma_f32_16x16x32_bf16 v[26:29], v[174:177], v[230:233], v[26:29]
	v_mfma_f32_16x16x32_bf16 v[22:25], v[182:185], v[230:233], v[22:25]
	v_mfma_f32_16x16x32_bf16 v[10:13], v[174:177], v[238:241], v[10:13]
	v_mfma_f32_16x16x32_bf16 v[6:9], v[182:185], v[238:241], v[6:9]
	s_barrier
; #define PG8_STAGE(bufoff, gbase, voff) do { _Pragma("unroll") for (int _i = 0; _i < 2; ++_i) \
;         __builtin_amdgcn_global_load_lds((const unsigned*)((const char*)(gbase) + (voff)[_i]), (PG8_LAS unsigned*)(lds + (bufoff) + ldsw + _i * 8192), 16, 0, 0); } while (0)
; #define PG8_LDA(dst, b, h) do { _Pragma("unroll") for (int m = 0; m < 4; ++m) _Pragma("unroll") for (int k = 0; k < 2; ++k) dst[m][k] = *(const PG8_LAS bf16x8*)(lds + PG8_SA(b, h) + aoff + m * 2048 + k * 1024); } while (0)
; #define PG8_LDB(dst, b, h) do { _Pragma("unroll") for (int n = 0; n < 2; ++n) _Pragma("unroll") for (int k = 0; k < 2; ++k) dst[n][k] = *(const PG8_LAS bf16x8*)(lds + PG8_SB(b, h) + boff + n * 2048 + k * 1024); } while (0)
; #define PG8_MMA(ai, bj, At, Bt) do { __builtin_amdgcn_s_setprio(1); _Pragma("unroll") for (int m = 0; m < 4; ++m) _Pragma("unroll") for (int n = 0; n < 2; ++n) _Pragma("unroll") for (int k = 0; k < 2; ++k) \
;         acc[ai][bj][m][n] = __builtin_amdgcn_mfma_f32_16x16x32_bf16(Bt[n][k], At[m][k], acc[ai][bj][m][n], 0, 0, 0); __builtin_amdgcn_s_setprio(0); } while (0)
; #define PG8_WAIT_V(n) asm volatile("s_waitcnt vmcnt(" #n ")" ::: "memory")
; #define PG8_WAIT_L(n) asm volatile("s_waitcnt lgkmcnt(" #n ")" ::: "memory")
; #define PG8_BAR __builtin_amdgcn_s_barrier()
; #define PG8_SCHED __builtin_amdgcn_sched_barrier(0)
; template <class Epi, class Sched, bool ALIGN_EPI = false, bool SP2 = false>
; __device__ __forceinline__ void gemm_phase(PG8_LAS unsigned char* lds, const Gemm g, const Sched& S, const Epi& E) {
;     ...
;             PG8_LDB(B0, 1, 0); PG8_LDB(B1, 1, 1); PG8_SCHED; PG8_LDA(At, 1, 0); PG8_STAGE(PG8_SA(0, 1), a2 + hstep, voffA);
;             PG8_WAIT_V(8); PG8_WAIT_L(0); PG8_BAR; PG8_MMA(0, 0, At, B0); PG8_MMA(0, 1, At, B1); PG8_BAR; PG8_SCHED;
;             PG8_LDA(At, 1, 1); PG8_STAGE(PG8_SB(1, 0), b3, voffB); PG8_STAGE(PG8_SB(1, 1), b3 + hstep, voffB); PG8_STAGE(PG8_SA(1, 0), a3, voffA);
;             PG8_WAIT_V(8); PG8_WAIT_L(0); PG8_BAR; PG8_MMA(1, 0, At, B0); PG8_MMA(1, 1, At, B1); PG8_BAR; PG8_SCHED;
	s_add_i32 s78, 0, 0x18000
	s_add_i32 s79, 0, 0x1c000
	v_add_u32_e32 v98, s78, v152
	v_add_u32_e32 v160, s79, v152
	ds_read_b128 v[78:81], v98
	ds_read_b128 v[90:93], v98 offset:1024
	ds_read_b128 v[94:97], v98 offset:2048
	ds_read_b128 v[98:101], v98 offset:3072
	ds_read_b128 v[166:169], v160
	ds_read_b128 v[174:177], v160 offset:1024
	ds_read_b128 v[178:181], v160 offset:2048
	ds_read_b128 v[182:185], v160 offset:3072
	s_add_u32 s24, s30, 0x80000
	s_addc_u32 s25, s31, 0
	s_mov_b32 m0, s47
	ds_read_b128 v[186:189], v173 offset:32768
	ds_read_b128 v[190:193], v173 offset:33792
	ds_read_b128 v[194:197], v173 offset:34816
	ds_read_b128 v[198:201], v173 offset:35840
	ds_read_b128 v[202:205], v173 offset:36864
	ds_read_b128 v[230:233], v173 offset:37888
	ds_read_b128 v[234:237], v173 offset:38912
	ds_read_b128 v[238:241], v173 offset:39936
	global_load_lds_dwordx4 v2, s[24:25]
	s_mov_b32 m0, s48
	s_nop 0
	global_load_lds_dwordx4 v0, s[24:25]
	s_waitcnt vmcnt(8)
	s_waitcnt lgkmcnt(0)
	s_barrier
	s_waitcnt lgkmcnt(0)
	v_mfma_f32_16x16x32_bf16 v[146:149], v[78:81], v[186:189], v[146:149]
	v_mfma_f32_16x16x32_bf16 v[142:145], v[94:97], v[186:189], v[142:145]
	v_mfma_f32_16x16x32_bf16 v[130:133], v[78:81], v[194:197], v[130:133]
	v_mfma_f32_16x16x32_bf16 v[126:129], v[94:97], v[194:197], v[126:129]
	v_mfma_f32_16x16x32_bf16 v[114:117], v[78:81], v[202:205], v[114:117]
	v_mfma_f32_16x16x32_bf16 v[110:113], v[94:97], v[202:205], v[110:113]
	v_mfma_f32_16x16x32_bf16 v[86:89], v[78:81], v[234:237], v[86:89]
	v_mfma_f32_16x16x32_bf16 v[82:85], v[94:97], v[234:237], v[82:85]
	v_mfma_f32_16x16x32_bf16 v[146:149], v[90:93], v[190:193], v[146:149]
	v_mfma_f32_16x16x32_bf16 v[142:145], v[98:101], v[190:193], v[142:145]
	v_mfma_f32_16x16x32_bf16 v[130:133], v[90:93], v[198:201], v[130:133]
	v_mfma_f32_16x16x32_bf16 v[126:129], v[98:101], v[198:201], v[126:129]
	v_mfma_f32_16x16x32_bf16 v[114:117], v[90:93], v[230:233], v[114:117]
	v_mfma_f32_16x16x32_bf16 v[110:113], v[98:101], v[230:233], v[110:113]
	v_mfma_f32_16x16x32_bf16 v[86:89], v[90:93], v[238:241], v[86:89]
	v_mfma_f32_16x16x32_bf16 v[82:85], v[98:101], v[238:241], v[82:85]
	v_mfma_f32_16x16x32_bf16 v[138:141], v[166:169], v[186:189], v[138:141]
	v_mfma_f32_16x16x32_bf16 v[134:137], v[178:181], v[186:189], v[134:137]
	v_mfma_f32_16x16x32_bf16 v[122:125], v[166:169], v[194:197], v[122:125]
	v_mfma_f32_16x16x32_bf16 v[118:121], v[178:181], v[194:197], v[118:121]
	v_mfma_f32_16x16x32_bf16 v[106:109], v[166:169], v[202:205], v[106:109]
	v_mfma_f32_16x16x32_bf16 v[102:105], v[178:181], v[202:205], v[102:105]
	v_mfma_f32_16x16x32_bf16 v[74:77], v[166:169], v[234:237], v[74:77]
	v_mfma_f32_16x16x32_bf16 v[70:73], v[178:181], v[234:237], v[70:73]
	v_mfma_f32_16x16x32_bf16 v[138:141], v[174:177], v[190:193], v[138:141]
	v_mfma_f32_16x16x32_bf16 v[134:137], v[182:185], v[190:193], v[134:137]
	v_mfma_f32_16x16x32_bf16 v[122:125], v[174:177], v[198:201], v[122:125]
	v_mfma_f32_16x16x32_bf16 v[118:121], v[182:185], v[198:201], v[118:121]
	v_mfma_f32_16x16x32_bf16 v[106:109], v[174:177], v[230:233], v[106:109]
	v_mfma_f32_16x16x32_bf16 v[102:105], v[182:185], v[230:233], v[102:105]
	v_mfma_f32_16x16x32_bf16 v[74:77], v[174:177], v[238:241], v[74:77]
	v_mfma_f32_16x16x32_bf16 v[70:73], v[182:185], v[238:241], v[70:73]
	s_barrier
	s_add_u32 vcc_lo, s28, s2
	s_addc_u32 vcc_hi, s29, s3
	s_add_i32 s24, s78, s44
	s_mov_b32 m0, s24
	ds_read_b128 v[186:189], v173 offset:49152
	ds_read_b128 v[190:193], v173 offset:50176
	ds_read_b128 v[194:197], v173 offset:51200
	ds_read_b128 v[198:201], v173 offset:52224
	ds_read_b128 v[202:205], v173 offset:53248
	ds_read_b128 v[230:233], v173 offset:54272
	ds_read_b128 v[234:237], v173 offset:55296
	ds_read_b128 v[238:241], v173 offset:56320
	global_load_lds_dwordx4 v2, vcc
	s_add_i32 m0, s24, 0x2000
	s_add_u32 s24, s28, 0x80080
	s_addc_u32 s25, s29, 0
	s_add_i32 s28, s79, s44
	global_load_lds_dwordx4 v0, vcc
	s_mov_b32 m0, s28
	s_nop 0
	global_load_lds_dwordx4 v2, s[24:25]
	s_add_i32 m0, s28, 0x2000
	s_nop 0
	global_load_lds_dwordx4 v0, s[24:25]
	s_add_u32 vcc_lo, s30, s2
	s_addc_u32 vcc_hi, s31, s3
	s_mov_b32 m0, s49
	s_nop 0
	global_load_lds_dwordx4 v2, vcc
	s_mov_b32 m0, s50
	s_nop 0
	global_load_lds_dwordx4 v0, vcc
	s_waitcnt vmcnt(8)
	s_waitcnt lgkmcnt(0)
	s_barrier
	s_waitcnt lgkmcnt(0)
	v_mfma_f32_16x16x32_bf16 v[66:69], v[78:81], v[186:189], v[66:69]
	v_mfma_f32_16x16x32_bf16 v[62:65], v[94:97], v[186:189], v[62:65]
	v_mfma_f32_16x16x32_bf16 v[50:53], v[78:81], v[194:197], v[50:53]
	v_mfma_f32_16x16x32_bf16 v[46:49], v[94:97], v[194:197], v[46:49]
	v_mfma_f32_16x16x32_bf16 v[34:37], v[78:81], v[202:205], v[34:37]
	v_mfma_f32_16x16x32_bf16 v[30:33], v[94:97], v[202:205], v[30:33]
	v_mfma_f32_16x16x32_bf16 v[18:21], v[78:81], v[234:237], v[18:21]
	v_mfma_f32_16x16x32_bf16 v[14:17], v[94:97], v[234:237], v[14:17]
	v_mfma_f32_16x16x32_bf16 v[66:69], v[90:93], v[190:193], v[66:69]
	v_mfma_f32_16x16x32_bf16 v[62:65], v[98:101], v[190:193], v[62:65]
	v_mfma_f32_16x16x32_bf16 v[50:53], v[90:93], v[198:201], v[50:53]
	v_mfma_f32_16x16x32_bf16 v[46:49], v[98:101], v[198:201], v[46:49]
	v_mfma_f32_16x16x32_bf16 v[34:37], v[90:93], v[230:233], v[34:37]
	v_mfma_f32_16x16x32_bf16 v[30:33], v[98:101], v[230:233], v[30:33]
	v_mfma_f32_16x16x32_bf16 v[18:21], v[90:93], v[238:241], v[18:21]
	v_mfma_f32_16x16x32_bf16 v[14:17], v[98:101], v[238:241], v[14:17]
	v_mfma_f32_16x16x32_bf16 v[58:61], v[166:169], v[186:189], v[58:61]
	v_mfma_f32_16x16x32_bf16 v[54:57], v[178:181], v[186:189], v[54:57]
	v_mfma_f32_16x16x32_bf16 v[42:45], v[166:169], v[194:197], v[42:45]
	v_mfma_f32_16x16x32_bf16 v[38:41], v[178:181], v[194:197], v[38:41]
	v_mfma_f32_16x16x32_bf16 v[26:29], v[166:169], v[202:205], v[26:29]
	v_mfma_f32_16x16x32_bf16 v[22:25], v[178:181], v[202:205], v[22:25]
	v_mfma_f32_16x16x32_bf16 v[10:13], v[166:169], v[234:237], v[10:13]
	v_mfma_f32_16x16x32_bf16 v[6:9], v[178:181], v[234:237], v[6:9]
	v_mfma_f32_16x16x32_bf16 v[58:61], v[174:177], v[190:193], v[58:61]
	v_mfma_f32_16x16x32_bf16 v[54:57], v[182:185], v[190:193], v[54:57]
	v_mfma_f32_16x16x32_bf16 v[42:45], v[174:177], v[198:201], v[42:45]
	v_mfma_f32_16x16x32_bf16 v[38:41], v[182:185], v[198:201], v[38:41]
	v_mfma_f32_16x16x32_bf16 v[26:29], v[174:177], v[230:233], v[26:29]
	v_mfma_f32_16x16x32_bf16 v[22:25], v[182:185], v[230:233], v[22:25]
	v_mfma_f32_16x16x32_bf16 v[10:13], v[174:177], v[238:241], v[10:13]
	v_mfma_f32_16x16x32_bf16 v[6:9], v[182:185], v[238:241], v[6:9]
	s_barrier
;     __device__ __forceinline__ void operator()(const f32x4 (&acc)[2][2][4][2], const Unit& u, int wr, int wc, int fr, int fq) const {
;         const int row0 = u.pm * BM + wr * 64 + fr; const int col0 = u.pn * BM + wc * 32 + 4 * fq;
;         f32x4 gv[2][2];
; #pragma unroll
;         for (int bj = 0; bj < 2; ++bj)
; #pragma unroll
;             for (int n = 0; n < 2; ++n) gv[bj][n] = xg ? *(const f32x4*)(gn + col0 + bj * HALF + n * 16) : (f32x4){0.f, 0.f, 0.f, 0.f};
; #pragma unroll
;         for (int ai = 0; ai < 2; ++ai)
; #pragma unroll
;             for (int m = 0; m < 4; ++m) { const size_t off = (size_t)(row0 + ai * HALF + m * 16) * ldc + col0; float ss = 0.f;
; #pragma unroll
;                 for (int bj = 0; bj < 2; ++bj)
; #pragma unroll
;                     for (int n = 0; n < 2; ++n) { const f32x4 bs = *(const f32x4*)(base + off + bj * HALF + n * 16); const f32x4 o = bs + acc[ai][bj][m][n] * scale;
;                         *(f32x4*)(out + off + bj * HALF + n * 16) = o;
;                         if (xg) { ss += (o[0] * o[0] + o[1] * o[1]) + (o[2] * o[2] + o[3] * o[3]); const f32x4 og = o * gv[bj][n];
;                             typedef unsigned u32x2v __attribute__((ext_vector_type(2))); u32x2v w; w.x = cvt_pk_bf16(og[0], og[1]); w.y = cvt_pk_bf16(og[2], og[3]); *(u32x2v*)(xg + off + bj * HALF + n * 16) = w; } }
;                 if (xg) { ss += __shfl_xor(ss, 16); ss += __shfl_xor(ss, 32); if (fq == 0) atomicAdd(rowss + row0 + ai * HALF + m * 16, (rowss_t)(ss * 16777216.0f)); } }
; template <class Epi, class Sched, bool ALIGN_EPI = false, bool SP2 = false>
; __device__ __forceinline__ void gemm_phase(PG8_LAS unsigned char* lds, const Gemm g, const Sched& S, const Epi& E) {
;     ...
;         for (int t = 0; t < nt; t += 2) {
	s_add_i32 s71, s71, 2
	s_add_u32 s69, s69, 0x100
	s_addc_u32 s70, s70, 0
	s_cmp_gt_u32 s71, 29
	s_mov_b64 s[24:25], s[26:27]
	s_cbranch_scc0 .LBB0_1630
	v_lshl_add_u32 v170, s52, 8, v5
	v_lshl_or_b32 v168, s53, 8, v172
	v_ashrrev_i32_e32 v171, 31, v170
	v_ashrrev_i32_e32 v169, 31, v168
	v_readlane_b32 s72, v254, 12
	v_lshlrev_b64 v[158:159], 11, v[170:171]
	v_readlane_b32 s82, v254, 22
	v_readlane_b32 s83, v254, 23
	v_lshl_add_u64 v[166:167], v[158:159], 0, v[168:169]
	v_lshl_add_u64 v[158:159], v[166:167], 2, s[10:11]
	v_lshl_add_u64 v[78:79], v[168:169], 2, s[82:83]
	global_load_dwordx4 v[98:101], v[78:79], off
	global_load_dwordx4 v[94:97], v[78:79], off offset:64
	global_load_dwordx4 v[90:93], v[78:79], off offset:512
	s_nop 0
	global_load_dwordx4 v[78:81], v[78:79], off offset:576
	v_readlane_b32 s73, v254, 13
	global_load_dwordx4 v[174:177], v[158:159], off
	global_load_dwordx4 v[182:185], v[158:159], off offset:64
	global_load_dwordx4 v[186:189], v[158:159], off offset:512
	global_load_dwordx4 v[190:193], v[158:159], off offset:576
	v_readlane_b32 s74, v254, 14
	v_readlane_b32 s75, v254, 15
	v_readlane_b32 s76, v254, 16
	v_readlane_b32 s77, v254, 17
	v_readlane_b32 s78, v254, 18
	v_readlane_b32 s79, v254, 19
	v_readlane_b32 s80, v254, 20
	v_readlane_b32 s81, v254, 21
	v_readlane_b32 s84, v254, 24
	v_readlane_b32 s85, v254, 25
	v_readlane_b32 s86, v254, 26
	v_readlane_b32 s87, v254, 27
	s_waitcnt vmcnt(3) lgkmcnt(0)
	v_pk_add_f32 v[148:149], v[148:149], v[176:177]
	v_pk_add_f32 v[146:147], v[146:147], v[174:175]
	v_mul_f32_e32 v161, v149, v149
	v_mul_f32_e32 v160, v147, v147
	global_store_dwordx4 v[158:159], v[146:149], off
	v_fmac_f32_e32 v160, v146, v146
	v_fmac_f32_e32 v161, v148, v148
	v_pk_mul_f32 v[148:149], v[100:101], v[148:149]
	v_pk_mul_f32 v[146:147], v[98:99], v[146:147]
	v_lshl_add_u64 v[174:175], v[166:167], 1, s[12:13]
	v_cvt_pk_bf16_f32 v146, v146, v147
	v_cvt_pk_bf16_f32 v147, v148, v149
	global_store_dwordx2 v[174:175], v[146:147], off
	v_add_f32_e32 v160, v160, v161
	s_waitcnt vmcnt(4) lgkmcnt(0)
	v_pk_add_f32 v[144:145], v[144:145], v[184:185]
	v_pk_add_f32 v[142:143], v[142:143], v[182:183]
	v_mul_f32_e32 v147, v145, v145
	v_mul_f32_e32 v146, v143, v143
	global_store_dwordx4 v[158:159], v[142:145], off offset:64
	v_fmac_f32_e32 v146, v142, v142
	v_fmac_f32_e32 v147, v144, v144
	v_pk_mul_f32 v[144:145], v[96:97], v[144:145]
	v_pk_mul_f32 v[142:143], v[94:95], v[142:143]
	v_add_f32_e32 v146, v146, v147
	v_cvt_pk_bf16_f32 v142, v142, v143
	v_cvt_pk_bf16_f32 v143, v144, v145
	global_store_dwordx2 v[174:175], v[142:143], off offset:32
	v_add_f32_e32 v146, v160, v146
	s_waitcnt vmcnt(5) lgkmcnt(0)
	v_pk_add_f32 v[140:141], v[140:141], v[188:189]
	v_pk_add_f32 v[138:139], v[138:139], v[186:187]
	v_mul_f32_e32 v143, v141, v141
	v_mul_f32_e32 v142, v139, v139
	global_store_dwordx4 v[158:159], v[138:141], off offset:512
	v_fmac_f32_e32 v142, v138, v138
	v_fmac_f32_e32 v143, v140, v140
	v_pk_mul_f32 v[140:141], v[92:93], v[140:141]
	v_pk_mul_f32 v[138:139], v[90:91], v[138:139]
	v_add_f32_e32 v142, v142, v143
	v_cvt_pk_bf16_f32 v138, v138, v139
	v_cvt_pk_bf16_f32 v139, v140, v141
	global_store_dwordx2 v[174:175], v[138:139], off offset:256
	v_add_f32_e32 v142, v146, v142
	s_waitcnt vmcnt(6) lgkmcnt(0)
	v_pk_add_f32 v[136:137], v[136:137], v[192:193]
	v_pk_add_f32 v[134:135], v[134:135], v[190:191]
	global_store_dwordx4 v[158:159], v[134:137], off offset:576
	v_pk_mul_f32 v[140:141], v[78:79], v[134:135]
	v_pk_mul_f32 v[138:139], v[80:81], v[136:137]
	v_mul_f32_e32 v135, v135, v135
	v_fmac_f32_e32 v135, v134, v134
	v_mul_f32_e32 v134, v137, v137
	v_fmac_f32_e32 v134, v136, v136
	v_and_b32_e32 v136, 64, v218
	v_add_f32_e32 v134, v135, v134
	v_xor_b32_e32 v135, 16, v218
	v_add_u32_e32 v137, 64, v136
	v_cmp_lt_i32_e32 vcc, v135, v137
	v_add_f32_e32 v134, v142, v134
	v_cvt_pk_bf16_f32 v140, v140, v141
	v_cndmask_b32_e32 v135, v218, v135, vcc
	v_lshlrev_b32_e32 v136, 2, v135
	ds_bpermute_b32 v135, v136, v134
	v_cvt_pk_bf16_f32 v141, v138, v139
	global_store_dwordx2 v[174:175], v[140:141], off offset:288
	s_waitcnt lgkmcnt(0)
	v_add_f32_e32 v138, v134, v135
	v_xor_b32_e32 v134, 32, v218
	v_cmp_lt_i32_e32 vcc, v134, v137
	s_nop 1
	v_cndmask_b32_e32 v134, v218, v134, vcc
	v_lshlrev_b32_e32 v137, 2, v134
	ds_bpermute_b32 v139, v137, v138
	v_lshl_add_u64 v[134:135], v[170:171], 3, s[14:15]
	s_and_saveexec_b64 s[24:25], s[6:7]
	s_cbranch_execz .LBB0_1633
	s_waitcnt lgkmcnt(0)
	v_add_f32_e32 v138, v138, v139
	v_mul_f32_e32 v138, 0x4b800000, v138
	v_trunc_f32_e32 v138, v138
	v_mul_f32_e32 v139, 0x2f800000, v138
	v_floor_f32_e32 v139, v139
	v_fmac_f32_e32 v138, 0xcf800000, v139
	v_cvt_u32_f32_e32 v138, v138
	v_cvt_u32_f32_e32 v139, v139
	global_atomic_add_x2 v[134:135], v[138:139], off
